# v21 + LDS-DMA groups: m0 written before the address add, which supplies the wait state: 96 s_nop 0 removed from the K-loop load segments and prologues
# speedup vs baseline: 1.1086x; 1.1086x over previous
; #define PG8_STAGE(bufoff, gbase, voff) do { _Pragma("unroll") for (int _i = 0; _i < 2; ++_i) \
;         __builtin_amdgcn_global_load_lds((const unsigned*)((const char*)(gbase) + (voff)[_i]), (PG8_LAS unsigned*)(lds + (bufoff) + ldsw + _i * 8192), 16, 0, 0); } while (0)
; #define PG8_WAIT_V(n) asm volatile("s_waitcnt vmcnt(" #n ")" ::: "memory")
; #define PG8_WAIT_L(n) asm volatile("s_waitcnt lgkmcnt(" #n ")" ::: "memory")
; #define PG8_BAR __builtin_amdgcn_s_barrier()
; #define PG8_SCHED __builtin_amdgcn_sched_barrier(0)
; template <class Epi, class Sched, bool ALIGN_EPI = true, bool SP2 = true>
; __device__ __forceinline__ void gemm_phase(PG8_LAS unsigned char* lds, const int K  , const Sched& S, const Epi& E) {
;     ...
;             const char* a1 = cA + (size_t)(t + 1) * kstep;
;             const char* a2 = last ? nA : cA + (size_t)(t + 2) * kstep; const char* b2 = last ? nB : cB + (size_t)(t + 2) * kstep;
;             const char* a3 = a2 + kstep; const char* b3 = b2 + kstep;
;             if constexpr (SP2) {
;             PG8_LDB(B0, 0, 0); PG8_LDB(B1, 0, 1); PG8_SCHED; PG8_LDA(At, 0, 0); PG8_STAGE(PG8_SA(1, 1), a1 + hstep, voffA);
;             PG8_WAIT_V(8); PG8_WAIT_L(0); PG8_BAR; PG8_MMA(0, 0, At, B0); PG8_MMA(0, 1, At, B1); PG8_BAR; PG8_SCHED;
;             PG8_LDA(At, 0, 1); PG8_STAGE(PG8_SB(0, 0), b2, voffB); PG8_STAGE(PG8_SB(0, 1), b2 + hstep, voffB); PG8_STAGE(PG8_SA(0, 0), a2, voffA);
;             PG8_WAIT_V(8); PG8_WAIT_L(0); PG8_BAR; PG8_MMA(1, 0, At, B0); PG8_MMA(1, 1, At, B1); PG8_BAR; PG8_SCHED;
.LBB0_219:
	ds_read_b128 v[148:151], v154
	ds_read_b128 v[160:163], v154 offset:1024
	ds_read_b128 v[164:167], v154 offset:2048
	ds_read_b128 v[168:171], v154 offset:3072
	ds_read_b128 v[172:175], v155
	ds_read_b128 v[176:179], v155 offset:1024
	ds_read_b128 v[180:183], v155 offset:2048
	ds_read_b128 v[184:187], v155 offset:3072
	s_add_u32 s22, s20, 0xfff80080
	s_addc_u32 s23, s21, -1
	s_cmp_eq_u32 s48, 28
	s_cselect_b32 s25, s13, s23
	s_cselect_b32 s24, s44, s22
	s_cselect_b32 s23, s11, s47
	s_cselect_b32 s22, s45, s46
	v_lshl_add_u64 v[220:221], s[20:21], 0, v[140:141]
	s_add_i32 m0, s19, 0xc000
	ds_read_b128 v[188:191], v156
	ds_read_b128 v[192:195], v156 offset:1024
	ds_read_b128 v[196:199], v156 offset:2048
	ds_read_b128 v[200:203], v156 offset:3072
	ds_read_b128 v[204:207], v156 offset:4096
	ds_read_b128 v[208:211], v156 offset:5120
	ds_read_b128 v[212:215], v156 offset:6144
	ds_read_b128 v[216:219], v156 offset:7168
	global_load_lds_dwordx4 v[220:221], off
	s_add_i32 m0, s19, 0xe000
	v_lshl_add_u64 v[220:221], s[20:21], 0, v[142:143]
	global_load_lds_dwordx4 v[220:221], off
	s_waitcnt vmcnt(8)
	s_waitcnt lgkmcnt(0)
	s_setprio 1
	s_barrier
	v_mfma_f32_16x16x32_bf16 v[126:129], v[148:151], v[188:191], v[126:129]
	v_mfma_f32_16x16x32_bf16 v[118:121], v[164:167], v[188:191], v[118:121]
	v_mfma_f32_16x16x32_bf16 v[110:113], v[148:151], v[196:199], v[110:113]
	v_mfma_f32_16x16x32_bf16 v[102:105], v[164:167], v[196:199], v[102:105]
	v_mfma_f32_16x16x32_bf16 v[94:97], v[148:151], v[204:207], v[94:97]
	v_mfma_f32_16x16x32_bf16 v[86:89], v[164:167], v[204:207], v[86:89]
	v_mfma_f32_16x16x32_bf16 v[78:81], v[148:151], v[212:215], v[78:81]
	v_mfma_f32_16x16x32_bf16 v[70:73], v[164:167], v[212:215], v[70:73]
	v_mfma_f32_16x16x32_bf16 v[126:129], v[160:163], v[192:195], v[126:129]
	v_mfma_f32_16x16x32_bf16 v[118:121], v[168:171], v[192:195], v[118:121]
	v_mfma_f32_16x16x32_bf16 v[110:113], v[160:163], v[200:203], v[110:113]
	v_mfma_f32_16x16x32_bf16 v[102:105], v[168:171], v[200:203], v[102:105]
	v_mfma_f32_16x16x32_bf16 v[94:97], v[160:163], v[208:211], v[94:97]
	v_mfma_f32_16x16x32_bf16 v[86:89], v[168:171], v[208:211], v[86:89]
	v_mfma_f32_16x16x32_bf16 v[78:81], v[160:163], v[216:219], v[78:81]
	v_mfma_f32_16x16x32_bf16 v[70:73], v[168:171], v[216:219], v[70:73]
	s_setprio 0
	s_setprio 1
	v_mfma_f32_16x16x32_bf16 v[122:125], v[172:175], v[188:191], v[122:125]
	v_mfma_f32_16x16x32_bf16 v[114:117], v[180:183], v[188:191], v[114:117]
	v_mfma_f32_16x16x32_bf16 v[106:109], v[172:175], v[196:199], v[106:109]
	v_mfma_f32_16x16x32_bf16 v[98:101], v[180:183], v[196:199], v[98:101]
	v_mfma_f32_16x16x32_bf16 v[90:93], v[172:175], v[204:207], v[90:93]
	v_mfma_f32_16x16x32_bf16 v[82:85], v[180:183], v[204:207], v[82:85]
	v_mfma_f32_16x16x32_bf16 v[74:77], v[172:175], v[212:215], v[74:77]
	v_mfma_f32_16x16x32_bf16 v[66:69], v[180:183], v[212:215], v[66:69]
	v_mfma_f32_16x16x32_bf16 v[122:125], v[176:179], v[192:195], v[122:125]
	v_mfma_f32_16x16x32_bf16 v[114:117], v[184:187], v[192:195], v[114:117]
	v_mfma_f32_16x16x32_bf16 v[106:109], v[176:179], v[200:203], v[106:109]
	v_mfma_f32_16x16x32_bf16 v[98:101], v[184:187], v[200:203], v[98:101]
	v_mfma_f32_16x16x32_bf16 v[90:93], v[176:179], v[208:211], v[90:93]
	v_mfma_f32_16x16x32_bf16 v[82:85], v[184:187], v[208:211], v[82:85]
	v_mfma_f32_16x16x32_bf16 v[74:77], v[176:179], v[216:219], v[74:77]
	v_mfma_f32_16x16x32_bf16 v[66:69], v[184:187], v[216:219], v[66:69]
	s_barrier
	s_setprio 0
	s_add_i32 s49, s39, s29
	v_lshl_add_u64 v[220:221], s[22:23], 0, v[136:137]
	s_mov_b32 m0, s49
	ds_read_b128 v[188:191], v156 offset:16384
	ds_read_b128 v[192:195], v156 offset:17408
	ds_read_b128 v[196:199], v156 offset:18432
	ds_read_b128 v[200:203], v156 offset:19456
	ds_read_b128 v[204:207], v156 offset:20480
	ds_read_b128 v[208:211], v156 offset:21504
	ds_read_b128 v[212:215], v156 offset:22528
	ds_read_b128 v[216:219], v156 offset:23552
	global_load_lds_dwordx4 v[220:221], off
	s_add_i32 m0, s49, 0x2000
	s_add_u32 s50, s22, 0x80000
	v_lshl_add_u64 v[222:223], s[22:23], 0, v[132:133]
	s_addc_u32 s51, s23, 0
	s_add_i32 s49, s40, s29
	global_load_lds_dwordx4 v[222:223], off
	v_lshl_add_u64 v[224:225], s[50:51], 0, v[136:137]
	s_mov_b32 m0, s49
	v_lshl_add_u64 v[226:227], s[24:25], 0, v[134:135]
	global_load_lds_dwordx4 v[224:225], off
	s_add_i32 m0, s49, 0x2000
	v_lshl_add_u64 v[224:225], s[50:51], 0, v[132:133]
	global_load_lds_dwordx4 v[224:225], off
	s_mov_b32 m0, s19
	v_lshl_add_u64 v[224:225], s[24:25], 0, v[138:139]
	global_load_lds_dwordx4 v[224:225], off
	s_mov_b32 m0, s31
	s_nop 0
	global_load_lds_dwordx4 v[226:227], off
	s_waitcnt vmcnt(8)
	s_waitcnt lgkmcnt(0)
	s_setprio 1
	s_barrier
; #define PG8_STAGE(bufoff, gbase, voff) do { _Pragma("unroll") for (int _i = 0; _i < 2; ++_i) \
;         __builtin_amdgcn_global_load_lds((const unsigned*)((const char*)(gbase) + (voff)[_i]), (PG8_LAS unsigned*)(lds + (bufoff) + ldsw + _i * 8192), 16, 0, 0); } while (0)
; #define PG8_WAIT_V(n) asm volatile("s_waitcnt vmcnt(" #n ")" ::: "memory")
; #define PG8_WAIT_L(n) asm volatile("s_waitcnt lgkmcnt(" #n ")" ::: "memory")
; #define PG8_BAR __builtin_amdgcn_s_barrier()
; #define PG8_SCHED __builtin_amdgcn_sched_barrier(0)
; template <class Epi, class Sched, bool ALIGN_EPI = true, bool SP2 = true>
; __device__ __forceinline__ void gemm_phase(PG8_LAS unsigned char* lds, const int K  , const Sched& S, const Epi& E) {
;     ...
;             PG8_WAIT_V(8); PG8_WAIT_L(0); PG8_BAR; PG8_MMA(1, 0, At, B0); PG8_MMA(1, 1, At, B1); PG8_BAR; PG8_SCHED;
;             PG8_LDB(B0, 1, 0); PG8_LDB(B1, 1, 1); PG8_SCHED; PG8_LDA(At, 1, 0); PG8_STAGE(PG8_SA(0, 1), a2 + hstep, voffA);
;             PG8_WAIT_V(8); PG8_WAIT_L(0); PG8_BAR; PG8_MMA(0, 0, At, B0); PG8_MMA(0, 1, At, B1); PG8_BAR; PG8_SCHED;
	v_mfma_f32_16x16x32_bf16 v[62:65], v[148:151], v[188:191], v[62:65]
	v_mfma_f32_16x16x32_bf16 v[54:57], v[164:167], v[188:191], v[54:57]
	v_mfma_f32_16x16x32_bf16 v[46:49], v[148:151], v[196:199], v[46:49]
	v_mfma_f32_16x16x32_bf16 v[38:41], v[164:167], v[196:199], v[38:41]
	v_mfma_f32_16x16x32_bf16 v[30:33], v[148:151], v[204:207], v[30:33]
	v_mfma_f32_16x16x32_bf16 v[22:25], v[164:167], v[204:207], v[22:25]
	v_mfma_f32_16x16x32_bf16 v[14:17], v[148:151], v[212:215], v[14:17]
	v_mfma_f32_16x16x32_bf16 v[6:9], v[164:167], v[212:215], v[6:9]
	v_mfma_f32_16x16x32_bf16 v[62:65], v[160:163], v[192:195], v[62:65]
	v_mfma_f32_16x16x32_bf16 v[54:57], v[168:171], v[192:195], v[54:57]
	v_mfma_f32_16x16x32_bf16 v[46:49], v[160:163], v[200:203], v[46:49]
	v_mfma_f32_16x16x32_bf16 v[38:41], v[168:171], v[200:203], v[38:41]
	v_mfma_f32_16x16x32_bf16 v[30:33], v[160:163], v[208:211], v[30:33]
	v_mfma_f32_16x16x32_bf16 v[22:25], v[168:171], v[208:211], v[22:25]
	v_mfma_f32_16x16x32_bf16 v[14:17], v[160:163], v[216:219], v[14:17]
	v_mfma_f32_16x16x32_bf16 v[6:9], v[168:171], v[216:219], v[6:9]
	s_setprio 0
	s_setprio 1
	v_mfma_f32_16x16x32_bf16 v[58:61], v[172:175], v[188:191], v[58:61]
	v_mfma_f32_16x16x32_bf16 v[50:53], v[180:183], v[188:191], v[50:53]
	v_mfma_f32_16x16x32_bf16 v[42:45], v[172:175], v[196:199], v[42:45]
	v_mfma_f32_16x16x32_bf16 v[34:37], v[180:183], v[196:199], v[34:37]
	v_mfma_f32_16x16x32_bf16 v[26:29], v[172:175], v[204:207], v[26:29]
	v_mfma_f32_16x16x32_bf16 v[18:21], v[180:183], v[204:207], v[18:21]
	v_mfma_f32_16x16x32_bf16 v[10:13], v[172:175], v[212:215], v[10:13]
	v_mfma_f32_16x16x32_bf16 v[2:5], v[180:183], v[212:215], v[2:5]
	v_mfma_f32_16x16x32_bf16 v[58:61], v[176:179], v[192:195], v[58:61]
	v_mfma_f32_16x16x32_bf16 v[50:53], v[184:187], v[192:195], v[50:53]
	v_mfma_f32_16x16x32_bf16 v[42:45], v[176:179], v[200:203], v[42:45]
	v_mfma_f32_16x16x32_bf16 v[34:37], v[184:187], v[200:203], v[34:37]
	v_mfma_f32_16x16x32_bf16 v[26:29], v[176:179], v[208:211], v[26:29]
	v_mfma_f32_16x16x32_bf16 v[18:21], v[184:187], v[208:211], v[18:21]
	v_mfma_f32_16x16x32_bf16 v[10:13], v[176:179], v[216:219], v[10:13]
	v_mfma_f32_16x16x32_bf16 v[2:5], v[184:187], v[216:219], v[2:5]
	s_barrier
	s_setprio 0
	s_add_i32 s49, 0, 0x18000
	v_add_u32_e32 v159, s49, v152
	s_add_i32 s50, 0, 0x1c000
	ds_read_b128 v[148:151], v159
	ds_read_b128 v[160:163], v159 offset:1024
	ds_read_b128 v[164:167], v159 offset:2048
	ds_read_b128 v[168:171], v159 offset:3072
	v_add_u32_e32 v159, s50, v152
	ds_read_b128 v[172:175], v159
	ds_read_b128 v[176:179], v159 offset:1024
	ds_read_b128 v[180:183], v159 offset:2048
	ds_read_b128 v[184:187], v159 offset:3072
	s_add_u32 s24, s24, 0x80000
	s_addc_u32 s25, s25, 0
	s_mov_b32 m0, s33
	v_lshl_add_u64 v[230:231], s[24:25], 0, v[138:139]
	ds_read_b128 v[188:191], v156 offset:32768
	ds_read_b128 v[192:195], v156 offset:33792
	ds_read_b128 v[196:199], v156 offset:34816
	ds_read_b128 v[200:203], v156 offset:35840
	ds_read_b128 v[204:207], v156 offset:36864
	ds_read_b128 v[208:211], v156 offset:37888
	ds_read_b128 v[212:215], v156 offset:38912
	ds_read_b128 v[216:219], v156 offset:39936
	global_load_lds_dwordx4 v[230:231], off
	s_mov_b32 m0, s34
	v_lshl_add_u64 v[230:231], s[24:25], 0, v[134:135]
	global_load_lds_dwordx4 v[230:231], off
	s_waitcnt vmcnt(8)
	s_waitcnt lgkmcnt(0)
	s_setprio 1
	s_barrier
	v_mfma_f32_16x16x32_bf16 v[126:129], v[148:151], v[188:191], v[126:129]
	v_mfma_f32_16x16x32_bf16 v[118:121], v[164:167], v[188:191], v[118:121]
	v_mfma_f32_16x16x32_bf16 v[110:113], v[148:151], v[196:199], v[110:113]
	v_mfma_f32_16x16x32_bf16 v[102:105], v[164:167], v[196:199], v[102:105]
	v_mfma_f32_16x16x32_bf16 v[94:97], v[148:151], v[204:207], v[94:97]
	v_mfma_f32_16x16x32_bf16 v[86:89], v[164:167], v[204:207], v[86:89]
	v_mfma_f32_16x16x32_bf16 v[78:81], v[148:151], v[212:215], v[78:81]
	v_mfma_f32_16x16x32_bf16 v[70:73], v[164:167], v[212:215], v[70:73]
	v_mfma_f32_16x16x32_bf16 v[126:129], v[160:163], v[192:195], v[126:129]
	v_mfma_f32_16x16x32_bf16 v[118:121], v[168:171], v[192:195], v[118:121]
	v_mfma_f32_16x16x32_bf16 v[110:113], v[160:163], v[200:203], v[110:113]
	v_mfma_f32_16x16x32_bf16 v[102:105], v[168:171], v[200:203], v[102:105]
	v_mfma_f32_16x16x32_bf16 v[94:97], v[160:163], v[208:211], v[94:97]
	v_mfma_f32_16x16x32_bf16 v[86:89], v[168:171], v[208:211], v[86:89]
	v_mfma_f32_16x16x32_bf16 v[78:81], v[160:163], v[216:219], v[78:81]
	v_mfma_f32_16x16x32_bf16 v[70:73], v[168:171], v[216:219], v[70:73]
	s_setprio 0
	s_setprio 1
	v_mfma_f32_16x16x32_bf16 v[122:125], v[172:175], v[188:191], v[122:125]
	v_mfma_f32_16x16x32_bf16 v[114:117], v[180:183], v[188:191], v[114:117]
	v_mfma_f32_16x16x32_bf16 v[106:109], v[172:175], v[196:199], v[106:109]
	v_mfma_f32_16x16x32_bf16 v[98:101], v[180:183], v[196:199], v[98:101]
	v_mfma_f32_16x16x32_bf16 v[90:93], v[172:175], v[204:207], v[90:93]
	v_mfma_f32_16x16x32_bf16 v[82:85], v[180:183], v[204:207], v[82:85]
	v_mfma_f32_16x16x32_bf16 v[74:77], v[172:175], v[212:215], v[74:77]
	v_mfma_f32_16x16x32_bf16 v[66:69], v[180:183], v[212:215], v[66:69]
	v_mfma_f32_16x16x32_bf16 v[122:125], v[176:179], v[192:195], v[122:125]
	v_mfma_f32_16x16x32_bf16 v[114:117], v[184:187], v[192:195], v[114:117]
	v_mfma_f32_16x16x32_bf16 v[106:109], v[176:179], v[200:203], v[106:109]
	v_mfma_f32_16x16x32_bf16 v[98:101], v[184:187], v[200:203], v[98:101]
	v_mfma_f32_16x16x32_bf16 v[90:93], v[176:179], v[208:211], v[90:93]
	v_mfma_f32_16x16x32_bf16 v[82:85], v[184:187], v[208:211], v[82:85]
	v_mfma_f32_16x16x32_bf16 v[74:77], v[176:179], v[216:219], v[74:77]
	v_mfma_f32_16x16x32_bf16 v[66:69], v[184:187], v[216:219], v[66:69]
	s_barrier
; #define PG8_STAGE(bufoff, gbase, voff) do { _Pragma("unroll") for (int _i = 0; _i < 2; ++_i) \
;         __builtin_amdgcn_global_load_lds((const unsigned*)((const char*)(gbase) + (voff)[_i]), (PG8_LAS unsigned*)(lds + (bufoff) + ldsw + _i * 8192), 16, 0, 0); } while (0)
; #define PG8_WAIT_V(n) asm volatile("s_waitcnt vmcnt(" #n ")" ::: "memory")
; #define PG8_WAIT_L(n) asm volatile("s_waitcnt lgkmcnt(" #n ")" ::: "memory")
; #define PG8_BAR __builtin_amdgcn_s_barrier()
; #define PG8_SCHED __builtin_amdgcn_sched_barrier(0)
; template <class Epi, class Sched, bool ALIGN_EPI = true, bool SP2 = true>
; __device__ __forceinline__ void gemm_phase(PG8_LAS unsigned char* lds, const int K  , const Sched& S, const Epi& E) {
;     ...
;             PG8_LDA(At, 1, 1); PG8_STAGE(PG8_SB(1, 0), b3, voffB); PG8_STAGE(PG8_SB(1, 1), b3 + hstep, voffB); PG8_STAGE(PG8_SA(1, 0), a3, voffA);
;             PG8_WAIT_V(8); PG8_WAIT_L(0); PG8_BAR; PG8_MMA(1, 0, At, B0); PG8_MMA(1, 1, At, B1); PG8_BAR; PG8_SCHED;
	s_setprio 0
	s_add_i32 s24, s49, s29
	v_lshl_add_u64 v[220:221], v[220:221], 0, s[6:7]
	s_mov_b32 m0, s24
	ds_read_b128 v[188:191], v156 offset:49152
	ds_read_b128 v[192:195], v156 offset:50176
	ds_read_b128 v[196:199], v156 offset:51200
	ds_read_b128 v[200:203], v156 offset:52224
	ds_read_b128 v[204:207], v156 offset:53248
	ds_read_b128 v[208:211], v156 offset:54272
	ds_read_b128 v[212:215], v156 offset:55296
	ds_read_b128 v[216:219], v156 offset:56320
	global_load_lds_dwordx4 v[220:221], off
	s_add_i32 m0, s24, 0x2000
	s_add_u32 s22, s22, 0x80080
	v_lshl_add_u64 v[220:221], v[222:223], 0, s[6:7]
	s_addc_u32 s23, s23, 0
	s_add_i32 s24, s50, s29
	global_load_lds_dwordx4 v[220:221], off
	s_mov_b32 m0, s24
	v_lshl_add_u64 v[220:221], s[22:23], 0, v[136:137]
	global_load_lds_dwordx4 v[220:221], off
	s_add_i32 m0, s24, 0x2000
	v_lshl_add_u64 v[220:221], s[22:23], 0, v[132:133]
	global_load_lds_dwordx4 v[220:221], off
	s_mov_b32 m0, s36
	v_lshl_add_u64 v[220:221], v[224:225], 0, s[6:7]
	global_load_lds_dwordx4 v[220:221], off
	s_mov_b32 m0, s37
	v_lshl_add_u64 v[220:221], v[226:227], 0, s[6:7]
	global_load_lds_dwordx4 v[220:221], off
	s_waitcnt vmcnt(8)
	s_waitcnt lgkmcnt(0)
	s_setprio 1
	s_barrier
	v_mfma_f32_16x16x32_bf16 v[62:65], v[148:151], v[188:191], v[62:65]
	v_mfma_f32_16x16x32_bf16 v[54:57], v[164:167], v[188:191], v[54:57]
	v_mfma_f32_16x16x32_bf16 v[46:49], v[148:151], v[196:199], v[46:49]
	v_mfma_f32_16x16x32_bf16 v[38:41], v[164:167], v[196:199], v[38:41]
	v_mfma_f32_16x16x32_bf16 v[30:33], v[148:151], v[204:207], v[30:33]
	v_mfma_f32_16x16x32_bf16 v[22:25], v[164:167], v[204:207], v[22:25]
	v_mfma_f32_16x16x32_bf16 v[14:17], v[148:151], v[212:215], v[14:17]
	v_mfma_f32_16x16x32_bf16 v[6:9], v[164:167], v[212:215], v[6:9]
	v_mfma_f32_16x16x32_bf16 v[62:65], v[160:163], v[192:195], v[62:65]
	v_mfma_f32_16x16x32_bf16 v[54:57], v[168:171], v[192:195], v[54:57]
	v_mfma_f32_16x16x32_bf16 v[46:49], v[160:163], v[200:203], v[46:49]
	v_mfma_f32_16x16x32_bf16 v[38:41], v[168:171], v[200:203], v[38:41]
	v_mfma_f32_16x16x32_bf16 v[30:33], v[160:163], v[208:211], v[30:33]
	v_mfma_f32_16x16x32_bf16 v[22:25], v[168:171], v[208:211], v[22:25]
	v_mfma_f32_16x16x32_bf16 v[14:17], v[160:163], v[216:219], v[14:17]
	v_mfma_f32_16x16x32_bf16 v[6:9], v[168:171], v[216:219], v[6:9]
	s_setprio 0
	s_setprio 1
	v_mfma_f32_16x16x32_bf16 v[58:61], v[172:175], v[188:191], v[58:61]
	v_mfma_f32_16x16x32_bf16 v[50:53], v[180:183], v[188:191], v[50:53]
	v_mfma_f32_16x16x32_bf16 v[42:45], v[172:175], v[196:199], v[42:45]
	v_mfma_f32_16x16x32_bf16 v[34:37], v[180:183], v[196:199], v[34:37]
	v_mfma_f32_16x16x32_bf16 v[26:29], v[172:175], v[204:207], v[26:29]
	v_mfma_f32_16x16x32_bf16 v[18:21], v[180:183], v[204:207], v[18:21]
	v_mfma_f32_16x16x32_bf16 v[10:13], v[172:175], v[212:215], v[10:13]
	v_mfma_f32_16x16x32_bf16 v[2:5], v[180:183], v[212:215], v[2:5]
	v_mfma_f32_16x16x32_bf16 v[58:61], v[176:179], v[192:195], v[58:61]
	v_mfma_f32_16x16x32_bf16 v[50:53], v[184:187], v[192:195], v[50:53]
	v_mfma_f32_16x16x32_bf16 v[42:45], v[176:179], v[200:203], v[42:45]
	v_mfma_f32_16x16x32_bf16 v[34:37], v[184:187], v[200:203], v[34:37]
	v_mfma_f32_16x16x32_bf16 v[26:29], v[176:179], v[208:211], v[26:29]
	v_mfma_f32_16x16x32_bf16 v[18:21], v[184:187], v[208:211], v[18:21]
	v_mfma_f32_16x16x32_bf16 v[10:13], v[176:179], v[216:219], v[10:13]
	v_mfma_f32_16x16x32_bf16 v[2:5], v[184:187], v[216:219], v[2:5]
	s_barrier
	s_setprio 0
	s_add_i32 s48, s48, 2
	s_add_u32 s20, s20, 0x100
	s_addc_u32 s21, s21, 0
	s_add_u32 s46, s46, 0x100
	s_addc_u32 s47, s47, 0
	s_cmp_gt_u32 s48, 29
	s_cbranch_scc0 .LBB0_219
	s_and_b64 vcc, exec, s[8:9]
	s_cbranch_vccz .LBB0_222
	s_barrier

; #define PG8_STAGE(bufoff, gbase, voff) do { _Pragma("unroll") for (int _i = 0; _i < 2; ++_i) \
;         __builtin_amdgcn_global_load_lds((const unsigned*)((const char*)(gbase) + (voff)[_i]), (PG8_LAS unsigned*)(lds + (bufoff) + ldsw + _i * 8192), 16, 0, 0); } while (0)
; #define PG8_WAIT_V(n) asm volatile("s_waitcnt vmcnt(" #n ")" ::: "memory")
; #define PG8_WAIT_L(n) asm volatile("s_waitcnt lgkmcnt(" #n ")" ::: "memory")
; #define PG8_BAR __builtin_amdgcn_s_barrier()
; #define PG8_SCHED __builtin_amdgcn_sched_barrier(0)
; template <class Epi, class Sched, bool ALIGN_EPI = true, bool SP2 = true>
; __device__ __forceinline__ void gemm_phase(PG8_LAS unsigned char* lds, const int K  , const Sched& S, const Epi& E) {
;     ...
;             const char* a1 = cA + (size_t)(t + 1) * kstep;
;             const char* a2 = last ? nA : cA + (size_t)(t + 2) * kstep; const char* b2 = last ? nB : cB + (size_t)(t + 2) * kstep;
;             const char* a3 = a2 + kstep; const char* b3 = b2 + kstep;
;             if constexpr (SP2) {
;             PG8_LDB(B0, 0, 0); PG8_LDB(B1, 0, 1); PG8_SCHED; PG8_LDA(At, 0, 0); PG8_STAGE(PG8_SA(1, 1), a1 + hstep, voffA);
;             PG8_WAIT_V(8); PG8_WAIT_L(0); PG8_BAR; PG8_MMA(0, 0, At, B0); PG8_MMA(0, 1, At, B1); PG8_BAR; PG8_SCHED;
;             PG8_LDA(At, 0, 1); PG8_STAGE(PG8_SB(0, 0), b2, voffB); PG8_STAGE(PG8_SB(0, 1), b2 + hstep, voffB); PG8_STAGE(PG8_SA(0, 0), a2, voffA);
;             PG8_WAIT_V(8); PG8_WAIT_L(0); PG8_BAR; PG8_MMA(1, 0, At, B0); PG8_MMA(1, 1, At, B1); PG8_BAR; PG8_SCHED;
.LBB0_393:
	ds_read_b128 v[18:21], v190
	ds_read_b128 v[22:25], v190 offset:1024
	ds_read_b128 v[26:29], v190 offset:2048
	ds_read_b128 v[30:33], v190 offset:3072
	ds_read_b128 v[2:5], v191
	ds_read_b128 v[6:9], v191 offset:1024
	ds_read_b128 v[10:13], v191 offset:2048
	ds_read_b128 v[14:17], v191 offset:3072
	s_add_i32 s50, s22, 2
	s_add_u32 s20, s18, 0xfff50080
	s_addc_u32 s21, s19, -1
	s_cmp_eq_u32 s47, s22
	s_cselect_b32 s22, s14, s20
	s_cselect_b32 s23, s15, s21
	s_cselect_b32 s21, s17, s49
	s_cselect_b32 s20, s16, s48
	v_lshl_add_u64 v[218:219], s[18:19], 0, v[170:171]
	s_add_i32 m0, s26, 0xc000
	ds_read_b128 v[178:181], v192
	ds_read_b128 v[182:185], v192 offset:1024
	ds_read_b128 v[194:197], v192 offset:2048
	ds_read_b128 v[198:201], v192 offset:3072
	ds_read_b128 v[202:205], v192 offset:4096
	ds_read_b128 v[206:209], v192 offset:5120
	ds_read_b128 v[210:213], v192 offset:6144
	ds_read_b128 v[214:217], v192 offset:7168
	global_load_lds_dwordx4 v[218:219], off
	s_add_i32 m0, s26, 0xe000
	v_lshl_add_u64 v[218:219], s[18:19], 0, v[172:173]
	global_load_lds_dwordx4 v[218:219], off
	s_waitcnt vmcnt(8)
	s_waitcnt lgkmcnt(0)
	s_setprio 1
	s_barrier
	v_mfma_scale_f32_16x16x128_f8f6f4 v[158:161], v[18:25], v[178:185], v[158:161], v186, v186 op_sel_hi:[0,0,0]
	v_mfma_scale_f32_16x16x128_f8f6f4 v[154:157], v[26:33], v[178:185], v[154:157], v186, v186 op_sel_hi:[0,0,0]
	v_mfma_scale_f32_16x16x128_f8f6f4 v[150:153], v[18:25], v[194:201], v[150:153], v186, v186 op_sel_hi:[0,0,0]
	v_mfma_scale_f32_16x16x128_f8f6f4 v[142:145], v[26:33], v[194:201], v[142:145], v186, v186 op_sel_hi:[0,0,0]
	v_mfma_scale_f32_16x16x128_f8f6f4 v[134:137], v[18:25], v[202:209], v[134:137], v186, v186 op_sel_hi:[0,0,0]
	v_mfma_scale_f32_16x16x128_f8f6f4 v[126:129], v[26:33], v[202:209], v[126:129], v186, v186 op_sel_hi:[0,0,0]
	v_mfma_scale_f32_16x16x128_f8f6f4 v[118:121], v[18:25], v[210:217], v[118:121], v186, v186 op_sel_hi:[0,0,0]
	v_mfma_scale_f32_16x16x128_f8f6f4 v[110:113], v[26:33], v[210:217], v[110:113], v186, v186 op_sel_hi:[0,0,0]
	s_setprio 0
	s_setprio 1
	v_mfma_scale_f32_16x16x128_f8f6f4 v[146:149], v[2:9], v[178:185], v[146:149], v186, v186 op_sel_hi:[0,0,0]
	v_mfma_scale_f32_16x16x128_f8f6f4 v[138:141], v[10:17], v[178:185], v[138:141], v186, v186 op_sel_hi:[0,0,0]
	v_mfma_scale_f32_16x16x128_f8f6f4 v[130:133], v[2:9], v[194:201], v[130:133], v186, v186 op_sel_hi:[0,0,0]
	v_mfma_scale_f32_16x16x128_f8f6f4 v[122:125], v[10:17], v[194:201], v[122:125], v186, v186 op_sel_hi:[0,0,0]
	v_mfma_scale_f32_16x16x128_f8f6f4 v[114:117], v[2:9], v[202:209], v[114:117], v186, v186 op_sel_hi:[0,0,0]
	v_mfma_scale_f32_16x16x128_f8f6f4 v[106:109], v[10:17], v[202:209], v[106:109], v186, v186 op_sel_hi:[0,0,0]
	v_mfma_scale_f32_16x16x128_f8f6f4 v[102:105], v[2:9], v[210:217], v[102:105], v186, v186 op_sel_hi:[0,0,0]
	v_mfma_scale_f32_16x16x128_f8f6f4 v[98:101], v[10:17], v[210:217], v[98:101], v186, v186 op_sel_hi:[0,0,0]
	s_barrier
	s_setprio 0
	s_add_i32 s51, s37, s25
	v_lshl_add_u64 v[178:179], s[20:21], 0, v[164:165]
	s_mov_b32 m0, s51
	ds_read_b128 v[194:197], v192 offset:16384
	ds_read_b128 v[198:201], v192 offset:17408
	ds_read_b128 v[202:205], v192 offset:18432
	ds_read_b128 v[206:209], v192 offset:19456
	ds_read_b128 v[210:213], v192 offset:20480
	ds_read_b128 v[214:217], v192 offset:21504
	ds_read_b128 v[218:221], v192 offset:22528
	ds_read_b128 v[222:225], v192 offset:23552
	global_load_lds_dwordx4 v[178:179], off
	s_add_i32 m0, s51, 0x2000
	s_add_u32 s68, s20, 0xb0000
	v_lshl_add_u64 v[180:181], s[20:21], 0, v[168:169]
	s_addc_u32 s69, s21, 0
	s_add_i32 s51, s38, s25
	global_load_lds_dwordx4 v[180:181], off
	v_lshl_add_u64 v[182:183], s[68:69], 0, v[164:165]
	s_mov_b32 m0, s51
	v_lshl_add_u64 v[184:185], s[22:23], 0, v[166:167]
	global_load_lds_dwordx4 v[182:183], off
	s_add_i32 m0, s51, 0x2000
	v_lshl_add_u64 v[182:183], s[68:69], 0, v[168:169]
	global_load_lds_dwordx4 v[182:183], off
	s_mov_b32 m0, s26
	v_lshl_add_u64 v[182:183], s[22:23], 0, v[162:163]
	global_load_lds_dwordx4 v[182:183], off
	s_mov_b32 m0, s27
	s_nop 0
	global_load_lds_dwordx4 v[184:185], off
	s_waitcnt vmcnt(8)
	s_waitcnt lgkmcnt(0)
	s_setprio 1
	s_barrier
	v_mfma_scale_f32_16x16x128_f8f6f4 v[94:97], v[18:25], v[194:201], v[94:97], v186, v186 op_sel_hi:[0,0,0]
	v_mfma_scale_f32_16x16x128_f8f6f4 v[90:93], v[26:33], v[194:201], v[90:93], v186, v186 op_sel_hi:[0,0,0]
	v_mfma_scale_f32_16x16x128_f8f6f4 v[86:89], v[18:25], v[202:209], v[86:89], v186, v186 op_sel_hi:[0,0,0]
	v_mfma_scale_f32_16x16x128_f8f6f4 v[78:81], v[26:33], v[202:209], v[78:81], v186, v186 op_sel_hi:[0,0,0]
	v_mfma_scale_f32_16x16x128_f8f6f4 v[70:73], v[18:25], v[210:217], v[70:73], v186, v186 op_sel_hi:[0,0,0]
	v_mfma_scale_f32_16x16x128_f8f6f4 v[62:65], v[26:33], v[210:217], v[62:65], v186, v186 op_sel_hi:[0,0,0]
	v_mfma_scale_f32_16x16x128_f8f6f4 v[54:57], v[18:25], v[218:225], v[54:57], v186, v186 op_sel_hi:[0,0,0]
	v_mfma_scale_f32_16x16x128_f8f6f4 v[46:49], v[26:33], v[218:225], v[46:49], v186, v186 op_sel_hi:[0,0,0]
	s_setprio 0
	s_setprio 1
	v_mfma_scale_f32_16x16x128_f8f6f4 v[82:85], v[2:9], v[194:201], v[82:85], v186, v186 op_sel_hi:[0,0,0]
	v_mfma_scale_f32_16x16x128_f8f6f4 v[74:77], v[10:17], v[194:201], v[74:77], v186, v186 op_sel_hi:[0,0,0]
	v_mfma_scale_f32_16x16x128_f8f6f4 v[66:69], v[2:9], v[202:209], v[66:69], v186, v186 op_sel_hi:[0,0,0]
	v_mfma_scale_f32_16x16x128_f8f6f4 v[58:61], v[10:17], v[202:209], v[58:61], v186, v186 op_sel_hi:[0,0,0]
	v_mfma_scale_f32_16x16x128_f8f6f4 v[50:53], v[2:9], v[210:217], v[50:53], v186, v186 op_sel_hi:[0,0,0]
	v_mfma_scale_f32_16x16x128_f8f6f4 v[42:45], v[10:17], v[210:217], v[42:45], v186, v186 op_sel_hi:[0,0,0]
	v_mfma_scale_f32_16x16x128_f8f6f4 v[38:41], v[2:9], v[218:225], v[38:41], v186, v186 op_sel_hi:[0,0,0]
	v_mfma_scale_f32_16x16x128_f8f6f4 v[34:37], v[10:17], v[218:225], v[34:37], v186, v186 op_sel_hi:[0,0,0]
	s_barrier
; #define PG8_STAGE(bufoff, gbase, voff) do { _Pragma("unroll") for (int _i = 0; _i < 2; ++_i) \
;         __builtin_amdgcn_global_load_lds((const unsigned*)((const char*)(gbase) + (voff)[_i]), (PG8_LAS unsigned*)(lds + (bufoff) + ldsw + _i * 8192), 16, 0, 0); } while (0)
; #define PG8_WAIT_V(n) asm volatile("s_waitcnt vmcnt(" #n ")" ::: "memory")
; #define PG8_WAIT_L(n) asm volatile("s_waitcnt lgkmcnt(" #n ")" ::: "memory")
; #define PG8_BAR __builtin_amdgcn_s_barrier()
; #define PG8_SCHED __builtin_amdgcn_sched_barrier(0)
; template <class Epi, class Sched, bool ALIGN_EPI = true, bool SP2 = true>
; __device__ __forceinline__ void gemm_phase(PG8_LAS unsigned char* lds, const int K  , const Sched& S, const Epi& E) {
;     ...
;             PG8_LDB(B0, 1, 0); PG8_LDB(B1, 1, 1); PG8_SCHED; PG8_LDA(At, 1, 0); PG8_STAGE(PG8_SA(0, 1), a2 + hstep, voffA);
;             PG8_WAIT_V(8); PG8_WAIT_L(0); PG8_BAR; PG8_MMA(0, 0, At, B0); PG8_MMA(0, 1, At, B1); PG8_BAR; PG8_SCHED;
;             PG8_LDA(At, 1, 1); PG8_STAGE(PG8_SB(1, 0), b3, voffB); PG8_STAGE(PG8_SB(1, 1), b3 + hstep, voffB); PG8_STAGE(PG8_SA(1, 0), a3, voffA);
;             PG8_WAIT_V(8); PG8_WAIT_L(0); PG8_BAR; PG8_MMA(1, 0, At, B0); PG8_MMA(1, 1, At, B1); PG8_BAR; PG8_SCHED;
;     ...
;         if constexpr (Epi::FP8) asm volatile("s_nop 15\n\ts_nop 15\n\ts_nop 15\n\ts_nop 15\n\ts_nop 15" ::: "memory");
;         if constexpr (ALIGN_EPI) { if (wr == 0) PG8_BAR; }
	s_setprio 0
	s_add_i32 s51, 0, 0x18000
	s_add_i32 s68, 0, 0x1c000
	v_add_u32_e32 v14, s51, v188
	v_add_u32_e32 v30, s68, v188
	ds_read_b128 v[2:5], v14
	ds_read_b128 v[6:9], v14 offset:1024
	ds_read_b128 v[10:13], v14 offset:2048
	ds_read_b128 v[14:17], v14 offset:3072
	ds_read_b128 v[18:21], v30
	ds_read_b128 v[22:25], v30 offset:1024
	ds_read_b128 v[26:29], v30 offset:2048
	ds_read_b128 v[30:33], v30 offset:3072
	s_add_u32 s22, s22, 0xb0000
	s_addc_u32 s23, s23, 0
	s_mov_b32 m0, s28
	v_lshl_add_u64 v[226:227], s[22:23], 0, v[162:163]
	ds_read_b128 v[194:197], v192 offset:32768
	ds_read_b128 v[198:201], v192 offset:33792
	ds_read_b128 v[202:205], v192 offset:34816
	ds_read_b128 v[206:209], v192 offset:35840
	ds_read_b128 v[210:213], v192 offset:36864
	ds_read_b128 v[214:217], v192 offset:37888
	ds_read_b128 v[218:221], v192 offset:38912
	ds_read_b128 v[222:225], v192 offset:39936
	global_load_lds_dwordx4 v[226:227], off
	s_mov_b32 m0, s29
	v_lshl_add_u64 v[226:227], s[22:23], 0, v[166:167]
	global_load_lds_dwordx4 v[226:227], off
	s_waitcnt vmcnt(8)
	s_waitcnt lgkmcnt(0)
	s_setprio 1
	s_barrier
	v_mfma_scale_f32_16x16x128_f8f6f4 v[158:161], v[2:9], v[194:201], v[158:161], v186, v186 op_sel_hi:[0,0,0]
	v_mfma_scale_f32_16x16x128_f8f6f4 v[154:157], v[10:17], v[194:201], v[154:157], v186, v186 op_sel_hi:[0,0,0]
	v_mfma_scale_f32_16x16x128_f8f6f4 v[150:153], v[2:9], v[202:209], v[150:153], v186, v186 op_sel_hi:[0,0,0]
	v_mfma_scale_f32_16x16x128_f8f6f4 v[142:145], v[10:17], v[202:209], v[142:145], v186, v186 op_sel_hi:[0,0,0]
	v_mfma_scale_f32_16x16x128_f8f6f4 v[134:137], v[2:9], v[210:217], v[134:137], v186, v186 op_sel_hi:[0,0,0]
	v_mfma_scale_f32_16x16x128_f8f6f4 v[126:129], v[10:17], v[210:217], v[126:129], v186, v186 op_sel_hi:[0,0,0]
	v_mfma_scale_f32_16x16x128_f8f6f4 v[118:121], v[2:9], v[218:225], v[118:121], v186, v186 op_sel_hi:[0,0,0]
	v_mfma_scale_f32_16x16x128_f8f6f4 v[110:113], v[10:17], v[218:225], v[110:113], v186, v186 op_sel_hi:[0,0,0]
	s_setprio 0
	s_setprio 1
	v_mfma_scale_f32_16x16x128_f8f6f4 v[146:149], v[18:25], v[194:201], v[146:149], v186, v186 op_sel_hi:[0,0,0]
	v_mfma_scale_f32_16x16x128_f8f6f4 v[138:141], v[26:33], v[194:201], v[138:141], v186, v186 op_sel_hi:[0,0,0]
	v_mfma_scale_f32_16x16x128_f8f6f4 v[130:133], v[18:25], v[202:209], v[130:133], v186, v186 op_sel_hi:[0,0,0]
	v_mfma_scale_f32_16x16x128_f8f6f4 v[122:125], v[26:33], v[202:209], v[122:125], v186, v186 op_sel_hi:[0,0,0]
	v_mfma_scale_f32_16x16x128_f8f6f4 v[114:117], v[18:25], v[210:217], v[114:117], v186, v186 op_sel_hi:[0,0,0]
	v_mfma_scale_f32_16x16x128_f8f6f4 v[106:109], v[26:33], v[210:217], v[106:109], v186, v186 op_sel_hi:[0,0,0]
	v_mfma_scale_f32_16x16x128_f8f6f4 v[102:105], v[18:25], v[218:225], v[102:105], v186, v186 op_sel_hi:[0,0,0]
	v_mfma_scale_f32_16x16x128_f8f6f4 v[98:101], v[26:33], v[218:225], v[98:101], v186, v186 op_sel_hi:[0,0,0]
	s_barrier
	s_setprio 0
	s_add_i32 s22, s51, s25
	v_lshl_add_u64 v[178:179], v[178:179], 0, s[8:9]
	s_mov_b32 m0, s22
	ds_read_b128 v[194:197], v192 offset:49152
	ds_read_b128 v[198:201], v192 offset:50176
	ds_read_b128 v[202:205], v192 offset:51200
	ds_read_b128 v[206:209], v192 offset:52224
	ds_read_b128 v[210:213], v192 offset:53248
	ds_read_b128 v[214:217], v192 offset:54272
	ds_read_b128 v[218:221], v192 offset:55296
	ds_read_b128 v[222:225], v192 offset:56320
	global_load_lds_dwordx4 v[178:179], off
	s_add_i32 m0, s22, 0x2000
	s_add_u32 s20, s20, 0xb0080
	v_lshl_add_u64 v[178:179], v[180:181], 0, s[8:9]
	s_addc_u32 s21, s21, 0
	s_add_i32 s22, s68, s25
	global_load_lds_dwordx4 v[178:179], off
	s_mov_b32 m0, s22
	v_lshl_add_u64 v[178:179], s[20:21], 0, v[164:165]
	global_load_lds_dwordx4 v[178:179], off
	s_add_i32 m0, s22, 0x2000
	v_lshl_add_u64 v[178:179], s[20:21], 0, v[168:169]
	global_load_lds_dwordx4 v[178:179], off
	s_mov_b32 m0, s33
	v_lshl_add_u64 v[178:179], v[182:183], 0, s[8:9]
	global_load_lds_dwordx4 v[178:179], off
	s_mov_b32 m0, s34
	v_lshl_add_u64 v[178:179], v[184:185], 0, s[8:9]
	global_load_lds_dwordx4 v[178:179], off
	s_waitcnt vmcnt(8)
	s_waitcnt lgkmcnt(0)
	s_setprio 1
	s_barrier
	v_mfma_scale_f32_16x16x128_f8f6f4 v[94:97], v[2:9], v[194:201], v[94:97], v186, v186 op_sel_hi:[0,0,0]
	v_mfma_scale_f32_16x16x128_f8f6f4 v[90:93], v[10:17], v[194:201], v[90:93], v186, v186 op_sel_hi:[0,0,0]
	v_mfma_scale_f32_16x16x128_f8f6f4 v[86:89], v[2:9], v[202:209], v[86:89], v186, v186 op_sel_hi:[0,0,0]
	v_mfma_scale_f32_16x16x128_f8f6f4 v[78:81], v[10:17], v[202:209], v[78:81], v186, v186 op_sel_hi:[0,0,0]
	v_mfma_scale_f32_16x16x128_f8f6f4 v[70:73], v[2:9], v[210:217], v[70:73], v186, v186 op_sel_hi:[0,0,0]
	v_mfma_scale_f32_16x16x128_f8f6f4 v[62:65], v[10:17], v[210:217], v[62:65], v186, v186 op_sel_hi:[0,0,0]
	v_mfma_scale_f32_16x16x128_f8f6f4 v[54:57], v[2:9], v[218:225], v[54:57], v186, v186 op_sel_hi:[0,0,0]
	v_mfma_scale_f32_16x16x128_f8f6f4 v[46:49], v[10:17], v[218:225], v[46:49], v186, v186 op_sel_hi:[0,0,0]
	s_setprio 0
	s_setprio 1
	v_mfma_scale_f32_16x16x128_f8f6f4 v[82:85], v[18:25], v[194:201], v[82:85], v186, v186 op_sel_hi:[0,0,0]
	v_mfma_scale_f32_16x16x128_f8f6f4 v[74:77], v[26:33], v[194:201], v[74:77], v186, v186 op_sel_hi:[0,0,0]
	v_mfma_scale_f32_16x16x128_f8f6f4 v[66:69], v[18:25], v[202:209], v[66:69], v186, v186 op_sel_hi:[0,0,0]
	v_mfma_scale_f32_16x16x128_f8f6f4 v[58:61], v[26:33], v[202:209], v[58:61], v186, v186 op_sel_hi:[0,0,0]
	v_mfma_scale_f32_16x16x128_f8f6f4 v[50:53], v[18:25], v[210:217], v[50:53], v186, v186 op_sel_hi:[0,0,0]
	v_mfma_scale_f32_16x16x128_f8f6f4 v[42:45], v[26:33], v[210:217], v[42:45], v186, v186 op_sel_hi:[0,0,0]
	v_mfma_scale_f32_16x16x128_f8f6f4 v[38:41], v[18:25], v[218:225], v[38:41], v186, v186 op_sel_hi:[0,0,0]
	v_mfma_scale_f32_16x16x128_f8f6f4 v[34:37], v[26:33], v[218:225], v[34:37], v186, v186 op_sel_hi:[0,0,0]
	s_barrier
	s_setprio 0
	s_add_u32 s18, s18, 0x100
	s_addc_u32 s19, s19, 0
	s_add_u32 s48, s48, 0x100
	s_addc_u32 s49, s49, 0
	s_cmp_ge_u32 s50, s4
	s_mov_b32 s22, s50
	s_cbranch_scc0 .LBB0_393
	s_nop 15
	s_nop 15
	s_nop 15
	s_nop 15
	s_nop 15
	s_and_b64 vcc, exec, s[10:11]
	s_cbranch_vccz .LBB0_396
	s_barrier

; #define PG8_STAGE(bufoff, gbase, voff) do { _Pragma("unroll") for (int _i = 0; _i < 2; ++_i) \
;         __builtin_amdgcn_global_load_lds((const unsigned*)((const char*)(gbase) + (voff)[_i]), (PG8_LAS unsigned*)(lds + (bufoff) + ldsw + _i * 8192), 16, 0, 0); } while (0)
; #define PG8_WAIT_V(n) asm volatile("s_waitcnt vmcnt(" #n ")" ::: "memory")
; #define PG8_WAIT_L(n) asm volatile("s_waitcnt lgkmcnt(" #n ")" ::: "memory")
; #define PG8_BAR __builtin_amdgcn_s_barrier()
; #define PG8_SCHED __builtin_amdgcn_sched_barrier(0)
; template <class Epi, class Sched, bool ALIGN_EPI = true, bool SP2 = true>
; __device__ __forceinline__ void gemm_phase(PG8_LAS unsigned char* lds, const int K  , const Sched& S, const Epi& E) {
;     ...
;             const char* a1 = cA + (size_t)(t + 1) * kstep;
;             const char* a2 = last ? nA : cA + (size_t)(t + 2) * kstep; const char* b2 = last ? nB : cB + (size_t)(t + 2) * kstep;
;             const char* a3 = a2 + kstep; const char* b3 = b2 + kstep;
;             if constexpr (SP2) {
;             PG8_LDB(B0, 0, 0); PG8_LDB(B1, 0, 1); PG8_SCHED; PG8_LDA(At, 0, 0); PG8_STAGE(PG8_SA(1, 1), a1 + hstep, voffA);
;             PG8_WAIT_V(8); PG8_WAIT_L(0); PG8_BAR; PG8_MMA(0, 0, At, B0); PG8_MMA(0, 1, At, B1); PG8_BAR; PG8_SCHED;
;             PG8_LDA(At, 0, 1); PG8_STAGE(PG8_SB(0, 0), b2, voffB); PG8_STAGE(PG8_SB(0, 1), b2 + hstep, voffB); PG8_STAGE(PG8_SA(0, 0), a2, voffA);
;             PG8_WAIT_V(8); PG8_WAIT_L(0); PG8_BAR; PG8_MMA(1, 0, At, B0); PG8_MMA(1, 1, At, B1); PG8_BAR; PG8_SCHED;
.LBB0_537:
	ds_read_b128 v[150:153], v156
	ds_read_b128 v[160:163], v156 offset:1024
	ds_read_b128 v[164:167], v156 offset:2048
	ds_read_b128 v[168:171], v156 offset:3072
	ds_read_b128 v[172:175], v157
	ds_read_b128 v[176:179], v157 offset:1024
	ds_read_b128 v[180:183], v157 offset:2048
	ds_read_b128 v[184:187], v157 offset:3072
	s_add_u32 s22, s20, 0xfff80080
	s_addc_u32 s23, s21, -1
	s_cmp_eq_u32 s47, 28
	s_cselect_b32 s25, s13, s23
	s_cselect_b32 s24, s19, s22
	s_cselect_b32 s23, s11, s46
	s_cselect_b32 s22, s44, s45
	v_lshl_add_u64 v[220:221], s[20:21], 0, v[142:143]
	s_add_i32 m0, s31, 0xc000
	ds_read_b128 v[188:191], v158
	ds_read_b128 v[192:195], v158 offset:1024
	ds_read_b128 v[196:199], v158 offset:2048
	ds_read_b128 v[200:203], v158 offset:3072
	ds_read_b128 v[204:207], v158 offset:4096
	ds_read_b128 v[208:211], v158 offset:5120
	ds_read_b128 v[212:215], v158 offset:6144
	ds_read_b128 v[216:219], v158 offset:7168
	global_load_lds_dwordx4 v[220:221], off
	s_add_i32 m0, s31, 0xe000
	v_lshl_add_u64 v[220:221], s[20:21], 0, v[144:145]
	global_load_lds_dwordx4 v[220:221], off
	s_waitcnt vmcnt(8)
	s_waitcnt lgkmcnt(0)
	s_setprio 1
	s_barrier
	v_mfma_f32_16x16x32_bf16 v[126:129], v[150:153], v[188:191], v[126:129]
	v_mfma_f32_16x16x32_bf16 v[122:125], v[164:167], v[188:191], v[122:125]
	v_mfma_f32_16x16x32_bf16 v[118:121], v[150:153], v[196:199], v[118:121]
	v_mfma_f32_16x16x32_bf16 v[110:113], v[164:167], v[196:199], v[110:113]
	v_mfma_f32_16x16x32_bf16 v[102:105], v[150:153], v[204:207], v[102:105]
	v_mfma_f32_16x16x32_bf16 v[94:97], v[164:167], v[204:207], v[94:97]
	v_mfma_f32_16x16x32_bf16 v[86:89], v[150:153], v[212:215], v[86:89]
	v_mfma_f32_16x16x32_bf16 v[78:81], v[164:167], v[212:215], v[78:81]
	v_mfma_f32_16x16x32_bf16 v[126:129], v[160:163], v[192:195], v[126:129]
	v_mfma_f32_16x16x32_bf16 v[122:125], v[168:171], v[192:195], v[122:125]
	v_mfma_f32_16x16x32_bf16 v[118:121], v[160:163], v[200:203], v[118:121]
	v_mfma_f32_16x16x32_bf16 v[110:113], v[168:171], v[200:203], v[110:113]
	v_mfma_f32_16x16x32_bf16 v[102:105], v[160:163], v[208:211], v[102:105]
	v_mfma_f32_16x16x32_bf16 v[94:97], v[168:171], v[208:211], v[94:97]
	v_mfma_f32_16x16x32_bf16 v[86:89], v[160:163], v[216:219], v[86:89]
	v_mfma_f32_16x16x32_bf16 v[78:81], v[168:171], v[216:219], v[78:81]
	s_setprio 0
	s_setprio 1
	v_mfma_f32_16x16x32_bf16 v[114:117], v[172:175], v[188:191], v[114:117]
	v_mfma_f32_16x16x32_bf16 v[106:109], v[180:183], v[188:191], v[106:109]
	v_mfma_f32_16x16x32_bf16 v[98:101], v[172:175], v[196:199], v[98:101]
	v_mfma_f32_16x16x32_bf16 v[90:93], v[180:183], v[196:199], v[90:93]
	v_mfma_f32_16x16x32_bf16 v[82:85], v[172:175], v[204:207], v[82:85]
	v_mfma_f32_16x16x32_bf16 v[74:77], v[180:183], v[204:207], v[74:77]
	v_mfma_f32_16x16x32_bf16 v[70:73], v[172:175], v[212:215], v[70:73]
	v_mfma_f32_16x16x32_bf16 v[66:69], v[180:183], v[212:215], v[66:69]
	v_mfma_f32_16x16x32_bf16 v[114:117], v[176:179], v[192:195], v[114:117]
	v_mfma_f32_16x16x32_bf16 v[106:109], v[184:187], v[192:195], v[106:109]
	v_mfma_f32_16x16x32_bf16 v[98:101], v[176:179], v[200:203], v[98:101]
	v_mfma_f32_16x16x32_bf16 v[90:93], v[184:187], v[200:203], v[90:93]
	v_mfma_f32_16x16x32_bf16 v[82:85], v[176:179], v[208:211], v[82:85]
	v_mfma_f32_16x16x32_bf16 v[74:77], v[184:187], v[208:211], v[74:77]
	v_mfma_f32_16x16x32_bf16 v[70:73], v[176:179], v[216:219], v[70:73]
	v_mfma_f32_16x16x32_bf16 v[66:69], v[184:187], v[216:219], v[66:69]
	s_barrier
	s_setprio 0
	s_add_i32 s48, s40, s29
	v_lshl_add_u64 v[220:221], s[22:23], 0, v[136:137]
	s_mov_b32 m0, s48
	ds_read_b128 v[188:191], v158 offset:16384
	ds_read_b128 v[192:195], v158 offset:17408
	ds_read_b128 v[196:199], v158 offset:18432
	ds_read_b128 v[200:203], v158 offset:19456
	ds_read_b128 v[204:207], v158 offset:20480
	ds_read_b128 v[208:211], v158 offset:21504
	ds_read_b128 v[212:215], v158 offset:22528
	ds_read_b128 v[216:219], v158 offset:23552
	global_load_lds_dwordx4 v[220:221], off
	s_add_i32 m0, s48, 0x2000
	s_add_u32 s48, s22, 0x80000
	v_lshl_add_u64 v[222:223], s[22:23], 0, v[132:133]
	s_addc_u32 s49, s23, 0
	s_add_i32 s50, s41, s29
	global_load_lds_dwordx4 v[222:223], off
	v_lshl_add_u64 v[224:225], s[48:49], 0, v[136:137]
	s_mov_b32 m0, s50
	v_lshl_add_u64 v[226:227], s[24:25], 0, v[134:135]
	global_load_lds_dwordx4 v[224:225], off
	s_add_i32 m0, s50, 0x2000
	v_lshl_add_u64 v[224:225], s[48:49], 0, v[132:133]
	global_load_lds_dwordx4 v[224:225], off
	s_mov_b32 m0, s31
	v_lshl_add_u64 v[224:225], s[24:25], 0, v[138:139]
	global_load_lds_dwordx4 v[224:225], off
	s_mov_b32 m0, s33
	s_nop 0
	global_load_lds_dwordx4 v[226:227], off
	s_waitcnt vmcnt(8)
	s_waitcnt lgkmcnt(0)
	s_setprio 1
	s_barrier
; #define PG8_STAGE(bufoff, gbase, voff) do { _Pragma("unroll") for (int _i = 0; _i < 2; ++_i) \
;         __builtin_amdgcn_global_load_lds((const unsigned*)((const char*)(gbase) + (voff)[_i]), (PG8_LAS unsigned*)(lds + (bufoff) + ldsw + _i * 8192), 16, 0, 0); } while (0)
; #define PG8_WAIT_V(n) asm volatile("s_waitcnt vmcnt(" #n ")" ::: "memory")
; #define PG8_WAIT_L(n) asm volatile("s_waitcnt lgkmcnt(" #n ")" ::: "memory")
; #define PG8_BAR __builtin_amdgcn_s_barrier()
; #define PG8_SCHED __builtin_amdgcn_sched_barrier(0)
; template <class Epi, class Sched, bool ALIGN_EPI = true, bool SP2 = true>
; __device__ __forceinline__ void gemm_phase(PG8_LAS unsigned char* lds, const int K  , const Sched& S, const Epi& E) {
;     ...
;             PG8_WAIT_V(8); PG8_WAIT_L(0); PG8_BAR; PG8_MMA(1, 0, At, B0); PG8_MMA(1, 1, At, B1); PG8_BAR; PG8_SCHED;
;             PG8_LDB(B0, 1, 0); PG8_LDB(B1, 1, 1); PG8_SCHED; PG8_LDA(At, 1, 0); PG8_STAGE(PG8_SA(0, 1), a2 + hstep, voffA);
;             PG8_WAIT_V(8); PG8_WAIT_L(0); PG8_BAR; PG8_MMA(0, 0, At, B0); PG8_MMA(0, 1, At, B1); PG8_BAR; PG8_SCHED;
	v_mfma_f32_16x16x32_bf16 v[62:65], v[150:153], v[188:191], v[62:65]
	v_mfma_f32_16x16x32_bf16 v[58:61], v[164:167], v[188:191], v[58:61]
	v_mfma_f32_16x16x32_bf16 v[54:57], v[150:153], v[196:199], v[54:57]
	v_mfma_f32_16x16x32_bf16 v[46:49], v[164:167], v[196:199], v[46:49]
	v_mfma_f32_16x16x32_bf16 v[38:41], v[150:153], v[204:207], v[38:41]
	v_mfma_f32_16x16x32_bf16 v[30:33], v[164:167], v[204:207], v[30:33]
	v_mfma_f32_16x16x32_bf16 v[22:25], v[150:153], v[212:215], v[22:25]
	v_mfma_f32_16x16x32_bf16 v[14:17], v[164:167], v[212:215], v[14:17]
	v_mfma_f32_16x16x32_bf16 v[62:65], v[160:163], v[192:195], v[62:65]
	v_mfma_f32_16x16x32_bf16 v[58:61], v[168:171], v[192:195], v[58:61]
	v_mfma_f32_16x16x32_bf16 v[54:57], v[160:163], v[200:203], v[54:57]
	v_mfma_f32_16x16x32_bf16 v[46:49], v[168:171], v[200:203], v[46:49]
	v_mfma_f32_16x16x32_bf16 v[38:41], v[160:163], v[208:211], v[38:41]
	v_mfma_f32_16x16x32_bf16 v[30:33], v[168:171], v[208:211], v[30:33]
	v_mfma_f32_16x16x32_bf16 v[22:25], v[160:163], v[216:219], v[22:25]
	v_mfma_f32_16x16x32_bf16 v[14:17], v[168:171], v[216:219], v[14:17]
	s_setprio 0
	s_setprio 1
	v_mfma_f32_16x16x32_bf16 v[50:53], v[172:175], v[188:191], v[50:53]
	v_mfma_f32_16x16x32_bf16 v[42:45], v[180:183], v[188:191], v[42:45]
	v_mfma_f32_16x16x32_bf16 v[34:37], v[172:175], v[196:199], v[34:37]
	v_mfma_f32_16x16x32_bf16 v[26:29], v[180:183], v[196:199], v[26:29]
	v_mfma_f32_16x16x32_bf16 v[18:21], v[172:175], v[204:207], v[18:21]
	v_mfma_f32_16x16x32_bf16 v[10:13], v[180:183], v[204:207], v[10:13]
	v_mfma_f32_16x16x32_bf16 v[6:9], v[172:175], v[212:215], v[6:9]
	v_mfma_f32_16x16x32_bf16 v[2:5], v[180:183], v[212:215], v[2:5]
	v_mfma_f32_16x16x32_bf16 v[50:53], v[176:179], v[192:195], v[50:53]
	v_mfma_f32_16x16x32_bf16 v[42:45], v[184:187], v[192:195], v[42:45]
	v_mfma_f32_16x16x32_bf16 v[34:37], v[176:179], v[200:203], v[34:37]
	v_mfma_f32_16x16x32_bf16 v[26:29], v[184:187], v[200:203], v[26:29]
	v_mfma_f32_16x16x32_bf16 v[18:21], v[176:179], v[208:211], v[18:21]
	v_mfma_f32_16x16x32_bf16 v[10:13], v[184:187], v[208:211], v[10:13]
	v_mfma_f32_16x16x32_bf16 v[6:9], v[176:179], v[216:219], v[6:9]
	v_mfma_f32_16x16x32_bf16 v[2:5], v[184:187], v[216:219], v[2:5]
	s_barrier
	s_setprio 0
	s_add_i32 s48, 0, 0x18000
	v_add_u32_e32 v140, s48, v154
	s_add_i32 s49, 0, 0x1c000
	ds_read_b128 v[150:153], v140
	ds_read_b128 v[160:163], v140 offset:1024
	ds_read_b128 v[164:167], v140 offset:2048
	ds_read_b128 v[168:171], v140 offset:3072
	v_add_u32_e32 v140, s49, v154
	ds_read_b128 v[172:175], v140
	ds_read_b128 v[176:179], v140 offset:1024
	ds_read_b128 v[180:183], v140 offset:2048
	ds_read_b128 v[184:187], v140 offset:3072
	s_add_u32 s24, s24, 0x80000
	s_addc_u32 s25, s25, 0
	s_mov_b32 m0, s34
	v_lshl_add_u64 v[230:231], s[24:25], 0, v[138:139]
	ds_read_b128 v[188:191], v158 offset:32768
	ds_read_b128 v[192:195], v158 offset:33792
	ds_read_b128 v[196:199], v158 offset:34816
	ds_read_b128 v[200:203], v158 offset:35840
	ds_read_b128 v[204:207], v158 offset:36864
	ds_read_b128 v[208:211], v158 offset:37888
	ds_read_b128 v[212:215], v158 offset:38912
	ds_read_b128 v[216:219], v158 offset:39936
	global_load_lds_dwordx4 v[230:231], off
	s_mov_b32 m0, s35
	v_lshl_add_u64 v[230:231], s[24:25], 0, v[134:135]
	global_load_lds_dwordx4 v[230:231], off
	s_waitcnt vmcnt(8)
	s_waitcnt lgkmcnt(0)
	s_setprio 1
	s_barrier
	v_mfma_f32_16x16x32_bf16 v[126:129], v[150:153], v[188:191], v[126:129]
	v_mfma_f32_16x16x32_bf16 v[122:125], v[164:167], v[188:191], v[122:125]
	v_mfma_f32_16x16x32_bf16 v[118:121], v[150:153], v[196:199], v[118:121]
	v_mfma_f32_16x16x32_bf16 v[110:113], v[164:167], v[196:199], v[110:113]
	v_mfma_f32_16x16x32_bf16 v[102:105], v[150:153], v[204:207], v[102:105]
	v_mfma_f32_16x16x32_bf16 v[94:97], v[164:167], v[204:207], v[94:97]
	v_mfma_f32_16x16x32_bf16 v[86:89], v[150:153], v[212:215], v[86:89]
	v_mfma_f32_16x16x32_bf16 v[78:81], v[164:167], v[212:215], v[78:81]
	v_mfma_f32_16x16x32_bf16 v[126:129], v[160:163], v[192:195], v[126:129]
	v_mfma_f32_16x16x32_bf16 v[122:125], v[168:171], v[192:195], v[122:125]
	v_mfma_f32_16x16x32_bf16 v[118:121], v[160:163], v[200:203], v[118:121]
	v_mfma_f32_16x16x32_bf16 v[110:113], v[168:171], v[200:203], v[110:113]
	v_mfma_f32_16x16x32_bf16 v[102:105], v[160:163], v[208:211], v[102:105]
	v_mfma_f32_16x16x32_bf16 v[94:97], v[168:171], v[208:211], v[94:97]
	v_mfma_f32_16x16x32_bf16 v[86:89], v[160:163], v[216:219], v[86:89]
	v_mfma_f32_16x16x32_bf16 v[78:81], v[168:171], v[216:219], v[78:81]
	s_setprio 0
	s_setprio 1
	v_mfma_f32_16x16x32_bf16 v[114:117], v[172:175], v[188:191], v[114:117]
	v_mfma_f32_16x16x32_bf16 v[106:109], v[180:183], v[188:191], v[106:109]
	v_mfma_f32_16x16x32_bf16 v[98:101], v[172:175], v[196:199], v[98:101]
	v_mfma_f32_16x16x32_bf16 v[90:93], v[180:183], v[196:199], v[90:93]
	v_mfma_f32_16x16x32_bf16 v[82:85], v[172:175], v[204:207], v[82:85]
	v_mfma_f32_16x16x32_bf16 v[74:77], v[180:183], v[204:207], v[74:77]
	v_mfma_f32_16x16x32_bf16 v[70:73], v[172:175], v[212:215], v[70:73]
	v_mfma_f32_16x16x32_bf16 v[66:69], v[180:183], v[212:215], v[66:69]
	v_mfma_f32_16x16x32_bf16 v[114:117], v[176:179], v[192:195], v[114:117]
	v_mfma_f32_16x16x32_bf16 v[106:109], v[184:187], v[192:195], v[106:109]
	v_mfma_f32_16x16x32_bf16 v[98:101], v[176:179], v[200:203], v[98:101]
	v_mfma_f32_16x16x32_bf16 v[90:93], v[184:187], v[200:203], v[90:93]
	v_mfma_f32_16x16x32_bf16 v[82:85], v[176:179], v[208:211], v[82:85]
	v_mfma_f32_16x16x32_bf16 v[74:77], v[184:187], v[208:211], v[74:77]
	v_mfma_f32_16x16x32_bf16 v[70:73], v[176:179], v[216:219], v[70:73]
	v_mfma_f32_16x16x32_bf16 v[66:69], v[184:187], v[216:219], v[66:69]
	s_barrier
; #define PG8_STAGE(bufoff, gbase, voff) do { _Pragma("unroll") for (int _i = 0; _i < 2; ++_i) \
;         __builtin_amdgcn_global_load_lds((const unsigned*)((const char*)(gbase) + (voff)[_i]), (PG8_LAS unsigned*)(lds + (bufoff) + ldsw + _i * 8192), 16, 0, 0); } while (0)
; #define PG8_WAIT_V(n) asm volatile("s_waitcnt vmcnt(" #n ")" ::: "memory")
; #define PG8_WAIT_L(n) asm volatile("s_waitcnt lgkmcnt(" #n ")" ::: "memory")
; #define PG8_BAR __builtin_amdgcn_s_barrier()
; #define PG8_SCHED __builtin_amdgcn_sched_barrier(0)
; template <class Epi, class Sched, bool ALIGN_EPI = true, bool SP2 = true>
; __device__ __forceinline__ void gemm_phase(PG8_LAS unsigned char* lds, const int K  , const Sched& S, const Epi& E) {
;     ...
;             PG8_LDA(At, 1, 1); PG8_STAGE(PG8_SB(1, 0), b3, voffB); PG8_STAGE(PG8_SB(1, 1), b3 + hstep, voffB); PG8_STAGE(PG8_SA(1, 0), a3, voffA);
;             PG8_WAIT_V(8); PG8_WAIT_L(0); PG8_BAR; PG8_MMA(1, 0, At, B0); PG8_MMA(1, 1, At, B1); PG8_BAR; PG8_SCHED;
	s_setprio 0
	s_add_i32 s24, s48, s29
	v_lshl_add_u64 v[220:221], v[220:221], 0, s[6:7]
	s_mov_b32 m0, s24
	ds_read_b128 v[188:191], v158 offset:49152
	ds_read_b128 v[192:195], v158 offset:50176
	ds_read_b128 v[196:199], v158 offset:51200
	ds_read_b128 v[200:203], v158 offset:52224
	ds_read_b128 v[204:207], v158 offset:53248
	ds_read_b128 v[208:211], v158 offset:54272
	ds_read_b128 v[212:215], v158 offset:55296
	ds_read_b128 v[216:219], v158 offset:56320
	global_load_lds_dwordx4 v[220:221], off
	s_add_i32 m0, s24, 0x2000
	s_add_u32 s22, s22, 0x80080
	v_lshl_add_u64 v[220:221], v[222:223], 0, s[6:7]
	s_addc_u32 s23, s23, 0
	s_add_i32 s24, s49, s29
	global_load_lds_dwordx4 v[220:221], off
	s_mov_b32 m0, s24
	v_lshl_add_u64 v[220:221], s[22:23], 0, v[136:137]
	global_load_lds_dwordx4 v[220:221], off
	s_add_i32 m0, s24, 0x2000
	v_lshl_add_u64 v[220:221], s[22:23], 0, v[132:133]
	global_load_lds_dwordx4 v[220:221], off
	s_mov_b32 m0, s37
	v_lshl_add_u64 v[220:221], v[224:225], 0, s[6:7]
	global_load_lds_dwordx4 v[220:221], off
	s_mov_b32 m0, s38
	v_lshl_add_u64 v[220:221], v[226:227], 0, s[6:7]
	global_load_lds_dwordx4 v[220:221], off
	s_waitcnt vmcnt(8)
	s_waitcnt lgkmcnt(0)
	s_setprio 1
	s_barrier
	v_mfma_f32_16x16x32_bf16 v[62:65], v[150:153], v[188:191], v[62:65]
	v_mfma_f32_16x16x32_bf16 v[58:61], v[164:167], v[188:191], v[58:61]
	v_mfma_f32_16x16x32_bf16 v[54:57], v[150:153], v[196:199], v[54:57]
	v_mfma_f32_16x16x32_bf16 v[46:49], v[164:167], v[196:199], v[46:49]
	v_mfma_f32_16x16x32_bf16 v[38:41], v[150:153], v[204:207], v[38:41]
	v_mfma_f32_16x16x32_bf16 v[30:33], v[164:167], v[204:207], v[30:33]
	v_mfma_f32_16x16x32_bf16 v[22:25], v[150:153], v[212:215], v[22:25]
	v_mfma_f32_16x16x32_bf16 v[14:17], v[164:167], v[212:215], v[14:17]
	v_mfma_f32_16x16x32_bf16 v[62:65], v[160:163], v[192:195], v[62:65]
	v_mfma_f32_16x16x32_bf16 v[58:61], v[168:171], v[192:195], v[58:61]
	v_mfma_f32_16x16x32_bf16 v[54:57], v[160:163], v[200:203], v[54:57]
	v_mfma_f32_16x16x32_bf16 v[46:49], v[168:171], v[200:203], v[46:49]
	v_mfma_f32_16x16x32_bf16 v[38:41], v[160:163], v[208:211], v[38:41]
	v_mfma_f32_16x16x32_bf16 v[30:33], v[168:171], v[208:211], v[30:33]
	v_mfma_f32_16x16x32_bf16 v[22:25], v[160:163], v[216:219], v[22:25]
	v_mfma_f32_16x16x32_bf16 v[14:17], v[168:171], v[216:219], v[14:17]
	s_setprio 0
	s_setprio 1
	v_mfma_f32_16x16x32_bf16 v[50:53], v[172:175], v[188:191], v[50:53]
	v_mfma_f32_16x16x32_bf16 v[42:45], v[180:183], v[188:191], v[42:45]
	v_mfma_f32_16x16x32_bf16 v[34:37], v[172:175], v[196:199], v[34:37]
	v_mfma_f32_16x16x32_bf16 v[26:29], v[180:183], v[196:199], v[26:29]
	v_mfma_f32_16x16x32_bf16 v[18:21], v[172:175], v[204:207], v[18:21]
	v_mfma_f32_16x16x32_bf16 v[10:13], v[180:183], v[204:207], v[10:13]
	v_mfma_f32_16x16x32_bf16 v[6:9], v[172:175], v[212:215], v[6:9]
	v_mfma_f32_16x16x32_bf16 v[2:5], v[180:183], v[212:215], v[2:5]
	v_mfma_f32_16x16x32_bf16 v[50:53], v[176:179], v[192:195], v[50:53]
	v_mfma_f32_16x16x32_bf16 v[42:45], v[184:187], v[192:195], v[42:45]
	v_mfma_f32_16x16x32_bf16 v[34:37], v[176:179], v[200:203], v[34:37]
	v_mfma_f32_16x16x32_bf16 v[26:29], v[184:187], v[200:203], v[26:29]
	v_mfma_f32_16x16x32_bf16 v[18:21], v[176:179], v[208:211], v[18:21]
	v_mfma_f32_16x16x32_bf16 v[10:13], v[184:187], v[208:211], v[10:13]
	v_mfma_f32_16x16x32_bf16 v[6:9], v[176:179], v[216:219], v[6:9]
	v_mfma_f32_16x16x32_bf16 v[2:5], v[184:187], v[216:219], v[2:5]
	s_barrier
	s_setprio 0
	s_add_i32 s47, s47, 2
	s_add_u32 s20, s20, 0x100
	s_addc_u32 s21, s21, 0
	s_add_u32 s45, s45, 0x100
	s_addc_u32 s46, s46, 0
	s_cmp_gt_u32 s47, 29
	s_cbranch_scc0 .LBB0_537
	s_and_b64 vcc, exec, s[8:9]
	s_cbranch_vccz .LBB0_540
	s_barrier

; #define PG8_STAGE(bufoff, gbase, voff) do { _Pragma("unroll") for (int _i = 0; _i < 2; ++_i) \
;         __builtin_amdgcn_global_load_lds((const unsigned*)((const char*)(gbase) + (voff)[_i]), (PG8_LAS unsigned*)(lds + (bufoff) + ldsw + _i * 8192), 16, 0, 0); } while (0)
; #define PG8_WAIT_V(n) asm volatile("s_waitcnt vmcnt(" #n ")" ::: "memory")
; #define PG8_WAIT_L(n) asm volatile("s_waitcnt lgkmcnt(" #n ")" ::: "memory")
; #define PG8_BAR __builtin_amdgcn_s_barrier()
; #define PG8_SCHED __builtin_amdgcn_sched_barrier(0)
; template <class Epi, class Sched, bool ALIGN_EPI = true, bool SP2 = true>
; __device__ __forceinline__ void gemm_phase(PG8_LAS unsigned char* lds, const int K  , const Sched& S, const Epi& E) {
;     ...
;             const char* a1 = cA + (size_t)(t + 1) * kstep;
;             const char* a2 = last ? nA : cA + (size_t)(t + 2) * kstep; const char* b2 = last ? nB : cB + (size_t)(t + 2) * kstep;
;             const char* a3 = a2 + kstep; const char* b3 = b2 + kstep;
;             if constexpr (SP2) {
;             PG8_LDB(B0, 0, 0); PG8_LDB(B1, 0, 1); PG8_SCHED; PG8_LDA(At, 0, 0); PG8_STAGE(PG8_SA(1, 1), a1 + hstep, voffA);
;             PG8_WAIT_V(8); PG8_WAIT_L(0); PG8_BAR; PG8_MMA(0, 0, At, B0); PG8_MMA(0, 1, At, B1); PG8_BAR; PG8_SCHED;
;             PG8_LDA(At, 0, 1); PG8_STAGE(PG8_SB(0, 0), b2, voffB); PG8_STAGE(PG8_SB(0, 1), b2 + hstep, voffB); PG8_STAGE(PG8_SA(0, 0), a2, voffA);
;             PG8_WAIT_V(8); PG8_WAIT_L(0); PG8_BAR; PG8_MMA(1, 0, At, B0); PG8_MMA(1, 1, At, B1); PG8_BAR; PG8_SCHED;
.LBB0_955:
	s_waitcnt vmcnt(0)
	ds_read_b128 v[130:133], v232
	ds_read_b128 v[134:137], v232 offset:1024
	ds_read_b128 v[138:141], v232 offset:2048
	ds_read_b128 v[142:145], v232 offset:3072
	ds_read_b128 v[146:149], v233
	ds_read_b128 v[150:153], v233 offset:1024
	ds_read_b128 v[154:157], v233 offset:2048
	ds_read_b128 v[158:161], v233 offset:3072
	s_add_i32 s73, s28, 2
	s_add_u32 s26, s24, 0xfff80080
	s_addc_u32 s27, s25, -1
	s_cmp_eq_u32 s13, s28
	s_cselect_b32 s28, s16, s26
	s_cselect_b32 s29, s17, s27
	s_cselect_b32 s27, s19, s21
	s_cselect_b32 s26, s18, s15
	v_lshl_add_u64 v[194:195], s[24:25], 0, v[214:215]
	s_add_i32 m0, s23, 0xc000
	ds_read_b128 v[162:165], v234
	ds_read_b128 v[166:169], v234 offset:1024
	ds_read_b128 v[170:173], v234 offset:2048
	ds_read_b128 v[174:177], v234 offset:3072
	ds_read_b128 v[178:181], v234 offset:4096
	ds_read_b128 v[182:185], v234 offset:5120
	ds_read_b128 v[186:189], v234 offset:6144
	ds_read_b128 v[190:193], v234 offset:7168
	global_load_lds_dwordx4 v[194:195], off
	s_add_i32 m0, s23, 0xe000
	v_lshl_add_u64 v[194:195], s[24:25], 0, v[216:217]
	global_load_lds_dwordx4 v[194:195], off
	s_waitcnt vmcnt(8)
	s_waitcnt lgkmcnt(0)
	s_setprio 1
	s_barrier
	v_mfma_f32_16x16x32_bf16 v[126:129], v[130:133], v[162:165], v[126:129]
	v_mfma_f32_16x16x32_bf16 v[122:125], v[138:141], v[162:165], v[122:125]
	v_mfma_f32_16x16x32_bf16 v[118:121], v[130:133], v[170:173], v[118:121]
	v_mfma_f32_16x16x32_bf16 v[110:113], v[138:141], v[170:173], v[110:113]
	v_mfma_f32_16x16x32_bf16 v[102:105], v[130:133], v[178:181], v[102:105]
	v_mfma_f32_16x16x32_bf16 v[94:97], v[138:141], v[178:181], v[94:97]
	v_mfma_f32_16x16x32_bf16 v[86:89], v[130:133], v[186:189], v[86:89]
	v_mfma_f32_16x16x32_bf16 v[78:81], v[138:141], v[186:189], v[78:81]
	v_mfma_f32_16x16x32_bf16 v[126:129], v[134:137], v[166:169], v[126:129]
	v_mfma_f32_16x16x32_bf16 v[122:125], v[142:145], v[166:169], v[122:125]
	v_mfma_f32_16x16x32_bf16 v[118:121], v[134:137], v[174:177], v[118:121]
	v_mfma_f32_16x16x32_bf16 v[110:113], v[142:145], v[174:177], v[110:113]
	v_mfma_f32_16x16x32_bf16 v[102:105], v[134:137], v[182:185], v[102:105]
	v_mfma_f32_16x16x32_bf16 v[94:97], v[142:145], v[182:185], v[94:97]
	v_mfma_f32_16x16x32_bf16 v[86:89], v[134:137], v[190:193], v[86:89]
	v_mfma_f32_16x16x32_bf16 v[78:81], v[142:145], v[190:193], v[78:81]
	s_setprio 0
	s_setprio 1
	v_mfma_f32_16x16x32_bf16 v[114:117], v[146:149], v[162:165], v[114:117]
	v_mfma_f32_16x16x32_bf16 v[106:109], v[154:157], v[162:165], v[106:109]
	v_mfma_f32_16x16x32_bf16 v[98:101], v[146:149], v[170:173], v[98:101]
	v_mfma_f32_16x16x32_bf16 v[90:93], v[154:157], v[170:173], v[90:93]
	v_mfma_f32_16x16x32_bf16 v[82:85], v[146:149], v[178:181], v[82:85]
	v_mfma_f32_16x16x32_bf16 v[74:77], v[154:157], v[178:181], v[74:77]
	v_mfma_f32_16x16x32_bf16 v[70:73], v[146:149], v[186:189], v[70:73]
	v_mfma_f32_16x16x32_bf16 v[66:69], v[154:157], v[186:189], v[66:69]
	v_mfma_f32_16x16x32_bf16 v[114:117], v[150:153], v[166:169], v[114:117]
	v_mfma_f32_16x16x32_bf16 v[106:109], v[158:161], v[166:169], v[106:109]
	v_mfma_f32_16x16x32_bf16 v[98:101], v[150:153], v[174:177], v[98:101]
	v_mfma_f32_16x16x32_bf16 v[90:93], v[158:161], v[174:177], v[90:93]
	v_mfma_f32_16x16x32_bf16 v[82:85], v[150:153], v[182:185], v[82:85]
	v_mfma_f32_16x16x32_bf16 v[74:77], v[158:161], v[182:185], v[74:77]
	v_mfma_f32_16x16x32_bf16 v[70:73], v[150:153], v[190:193], v[70:73]
	v_mfma_f32_16x16x32_bf16 v[66:69], v[158:161], v[190:193], v[66:69]
	s_barrier
	s_setprio 0
	s_add_i32 s74, s47, s33
	v_lshl_add_u64 v[194:195], s[26:27], 0, v[208:209]
	s_mov_b32 m0, s74
	ds_read_b128 v[162:165], v234 offset:16384
	ds_read_b128 v[166:169], v234 offset:17408
	ds_read_b128 v[170:173], v234 offset:18432
	ds_read_b128 v[174:177], v234 offset:19456
	ds_read_b128 v[178:181], v234 offset:20480
	ds_read_b128 v[182:185], v234 offset:21504
	ds_read_b128 v[186:189], v234 offset:22528
	ds_read_b128 v[190:193], v234 offset:23552
	global_load_lds_dwordx4 v[194:195], off
	s_add_i32 m0, s74, 0x2000
	s_add_u32 s74, s26, 0x80000
	v_lshl_add_u64 v[196:197], s[26:27], 0, v[212:213]
	s_addc_u32 s75, s27, 0
	s_add_i32 s76, s48, s33
	global_load_lds_dwordx4 v[196:197], off
	v_lshl_add_u64 v[198:199], s[74:75], 0, v[208:209]
	s_mov_b32 m0, s76
	v_lshl_add_u64 v[200:201], s[28:29], 0, v[210:211]
	global_load_lds_dwordx4 v[198:199], off
	s_add_i32 m0, s76, 0x2000
	v_lshl_add_u64 v[198:199], s[74:75], 0, v[212:213]
	global_load_lds_dwordx4 v[198:199], off
	s_mov_b32 m0, s23
	v_lshl_add_u64 v[198:199], s[28:29], 0, v[206:207]
	global_load_lds_dwordx4 v[198:199], off
	s_mov_b32 m0, s34
	s_nop 0
	global_load_lds_dwordx4 v[200:201], off
	s_waitcnt vmcnt(8)
	s_waitcnt lgkmcnt(0)
	s_setprio 1
	s_barrier
; #define PG8_STAGE(bufoff, gbase, voff) do { _Pragma("unroll") for (int _i = 0; _i < 2; ++_i) \
;         __builtin_amdgcn_global_load_lds((const unsigned*)((const char*)(gbase) + (voff)[_i]), (PG8_LAS unsigned*)(lds + (bufoff) + ldsw + _i * 8192), 16, 0, 0); } while (0)
; #define PG8_WAIT_V(n) asm volatile("s_waitcnt vmcnt(" #n ")" ::: "memory")
; #define PG8_WAIT_L(n) asm volatile("s_waitcnt lgkmcnt(" #n ")" ::: "memory")
; #define PG8_BAR __builtin_amdgcn_s_barrier()
; #define PG8_SCHED __builtin_amdgcn_sched_barrier(0)
; template <class Epi, class Sched, bool ALIGN_EPI = true, bool SP2 = true>
; __device__ __forceinline__ void gemm_phase(PG8_LAS unsigned char* lds, const int K  , const Sched& S, const Epi& E) {
;     ...
;             PG8_WAIT_V(8); PG8_WAIT_L(0); PG8_BAR; PG8_MMA(1, 0, At, B0); PG8_MMA(1, 1, At, B1); PG8_BAR; PG8_SCHED;
;             PG8_LDB(B0, 1, 0); PG8_LDB(B1, 1, 1); PG8_SCHED; PG8_LDA(At, 1, 0); PG8_STAGE(PG8_SA(0, 1), a2 + hstep, voffA);
;             PG8_WAIT_V(8); PG8_WAIT_L(0); PG8_BAR; PG8_MMA(0, 0, At, B0); PG8_MMA(0, 1, At, B1); PG8_BAR; PG8_SCHED;
	v_mfma_f32_16x16x32_bf16 v[62:65], v[130:133], v[162:165], v[62:65]
	v_mfma_f32_16x16x32_bf16 v[58:61], v[138:141], v[162:165], v[58:61]
	v_mfma_f32_16x16x32_bf16 v[54:57], v[130:133], v[170:173], v[54:57]
	v_mfma_f32_16x16x32_bf16 v[46:49], v[138:141], v[170:173], v[46:49]
	v_mfma_f32_16x16x32_bf16 v[38:41], v[130:133], v[178:181], v[38:41]
	v_mfma_f32_16x16x32_bf16 v[30:33], v[138:141], v[178:181], v[30:33]
	v_mfma_f32_16x16x32_bf16 v[22:25], v[130:133], v[186:189], v[22:25]
	v_mfma_f32_16x16x32_bf16 v[14:17], v[138:141], v[186:189], v[14:17]
	v_mfma_f32_16x16x32_bf16 v[62:65], v[134:137], v[166:169], v[62:65]
	v_mfma_f32_16x16x32_bf16 v[58:61], v[142:145], v[166:169], v[58:61]
	v_mfma_f32_16x16x32_bf16 v[54:57], v[134:137], v[174:177], v[54:57]
	v_mfma_f32_16x16x32_bf16 v[46:49], v[142:145], v[174:177], v[46:49]
	v_mfma_f32_16x16x32_bf16 v[38:41], v[134:137], v[182:185], v[38:41]
	v_mfma_f32_16x16x32_bf16 v[30:33], v[142:145], v[182:185], v[30:33]
	v_mfma_f32_16x16x32_bf16 v[22:25], v[134:137], v[190:193], v[22:25]
	v_mfma_f32_16x16x32_bf16 v[14:17], v[142:145], v[190:193], v[14:17]
	s_setprio 0
	s_setprio 1
	v_mfma_f32_16x16x32_bf16 v[50:53], v[146:149], v[162:165], v[50:53]
	v_mfma_f32_16x16x32_bf16 v[42:45], v[154:157], v[162:165], v[42:45]
	v_mfma_f32_16x16x32_bf16 v[34:37], v[146:149], v[170:173], v[34:37]
	v_mfma_f32_16x16x32_bf16 v[26:29], v[154:157], v[170:173], v[26:29]
	v_mfma_f32_16x16x32_bf16 v[18:21], v[146:149], v[178:181], v[18:21]
	v_mfma_f32_16x16x32_bf16 v[10:13], v[154:157], v[178:181], v[10:13]
	v_mfma_f32_16x16x32_bf16 v[6:9], v[146:149], v[186:189], v[6:9]
	v_mfma_f32_16x16x32_bf16 v[2:5], v[154:157], v[186:189], v[2:5]
	v_mfma_f32_16x16x32_bf16 v[50:53], v[150:153], v[166:169], v[50:53]
	v_mfma_f32_16x16x32_bf16 v[42:45], v[158:161], v[166:169], v[42:45]
	v_mfma_f32_16x16x32_bf16 v[34:37], v[150:153], v[174:177], v[34:37]
	v_mfma_f32_16x16x32_bf16 v[26:29], v[158:161], v[174:177], v[26:29]
	v_mfma_f32_16x16x32_bf16 v[18:21], v[150:153], v[182:185], v[18:21]
	v_mfma_f32_16x16x32_bf16 v[10:13], v[158:161], v[182:185], v[10:13]
	v_mfma_f32_16x16x32_bf16 v[6:9], v[150:153], v[190:193], v[6:9]
	v_mfma_f32_16x16x32_bf16 v[2:5], v[158:161], v[190:193], v[2:5]
	s_barrier
	s_setprio 0
	s_add_i32 s74, 0, 0x18000
	s_add_i32 s75, 0, 0x1c000
	v_add_u32_e32 v142, s74, v230
	v_add_u32_e32 v158, s75, v230
	ds_read_b128 v[130:133], v142
	ds_read_b128 v[134:137], v142 offset:1024
	ds_read_b128 v[138:141], v142 offset:2048
	ds_read_b128 v[142:145], v142 offset:3072
	ds_read_b128 v[146:149], v158
	ds_read_b128 v[150:153], v158 offset:1024
	ds_read_b128 v[154:157], v158 offset:2048
	ds_read_b128 v[158:161], v158 offset:3072
	s_add_u32 s28, s28, 0x80000
	s_addc_u32 s29, s29, 0
	s_mov_b32 m0, s35
	v_lshl_add_u64 v[202:203], s[28:29], 0, v[206:207]
	ds_read_b128 v[162:165], v234 offset:32768
	ds_read_b128 v[166:169], v234 offset:33792
	ds_read_b128 v[170:173], v234 offset:34816
	ds_read_b128 v[174:177], v234 offset:35840
	ds_read_b128 v[178:181], v234 offset:36864
	ds_read_b128 v[182:185], v234 offset:37888
	ds_read_b128 v[186:189], v234 offset:38912
	ds_read_b128 v[190:193], v234 offset:39936
	global_load_lds_dwordx4 v[202:203], off
	s_mov_b32 m0, s36
	v_lshl_add_u64 v[202:203], s[28:29], 0, v[210:211]
	global_load_lds_dwordx4 v[202:203], off
	s_waitcnt vmcnt(8)
	s_waitcnt lgkmcnt(0)
	s_setprio 1
	s_barrier
	v_mfma_f32_16x16x32_bf16 v[126:129], v[130:133], v[162:165], v[126:129]
	v_mfma_f32_16x16x32_bf16 v[122:125], v[138:141], v[162:165], v[122:125]
	v_mfma_f32_16x16x32_bf16 v[118:121], v[130:133], v[170:173], v[118:121]
	v_mfma_f32_16x16x32_bf16 v[110:113], v[138:141], v[170:173], v[110:113]
	v_mfma_f32_16x16x32_bf16 v[102:105], v[130:133], v[178:181], v[102:105]
	v_mfma_f32_16x16x32_bf16 v[94:97], v[138:141], v[178:181], v[94:97]
	v_mfma_f32_16x16x32_bf16 v[86:89], v[130:133], v[186:189], v[86:89]
	v_mfma_f32_16x16x32_bf16 v[78:81], v[138:141], v[186:189], v[78:81]
	v_mfma_f32_16x16x32_bf16 v[126:129], v[134:137], v[166:169], v[126:129]
	v_mfma_f32_16x16x32_bf16 v[122:125], v[142:145], v[166:169], v[122:125]
	v_mfma_f32_16x16x32_bf16 v[118:121], v[134:137], v[174:177], v[118:121]
	v_mfma_f32_16x16x32_bf16 v[110:113], v[142:145], v[174:177], v[110:113]
	v_mfma_f32_16x16x32_bf16 v[102:105], v[134:137], v[182:185], v[102:105]
	v_mfma_f32_16x16x32_bf16 v[94:97], v[142:145], v[182:185], v[94:97]
	v_mfma_f32_16x16x32_bf16 v[86:89], v[134:137], v[190:193], v[86:89]
	v_mfma_f32_16x16x32_bf16 v[78:81], v[142:145], v[190:193], v[78:81]
	s_setprio 0
	s_setprio 1
	v_mfma_f32_16x16x32_bf16 v[114:117], v[146:149], v[162:165], v[114:117]
	v_mfma_f32_16x16x32_bf16 v[106:109], v[154:157], v[162:165], v[106:109]
	v_mfma_f32_16x16x32_bf16 v[98:101], v[146:149], v[170:173], v[98:101]
	v_mfma_f32_16x16x32_bf16 v[90:93], v[154:157], v[170:173], v[90:93]
	v_mfma_f32_16x16x32_bf16 v[82:85], v[146:149], v[178:181], v[82:85]
	v_mfma_f32_16x16x32_bf16 v[74:77], v[154:157], v[178:181], v[74:77]
	v_mfma_f32_16x16x32_bf16 v[70:73], v[146:149], v[186:189], v[70:73]
	v_mfma_f32_16x16x32_bf16 v[66:69], v[154:157], v[186:189], v[66:69]
	v_mfma_f32_16x16x32_bf16 v[114:117], v[150:153], v[166:169], v[114:117]
	v_mfma_f32_16x16x32_bf16 v[106:109], v[158:161], v[166:169], v[106:109]
	v_mfma_f32_16x16x32_bf16 v[98:101], v[150:153], v[174:177], v[98:101]
	v_mfma_f32_16x16x32_bf16 v[90:93], v[158:161], v[174:177], v[90:93]
	v_mfma_f32_16x16x32_bf16 v[82:85], v[150:153], v[182:185], v[82:85]
	v_mfma_f32_16x16x32_bf16 v[74:77], v[158:161], v[182:185], v[74:77]
	v_mfma_f32_16x16x32_bf16 v[70:73], v[150:153], v[190:193], v[70:73]
	v_mfma_f32_16x16x32_bf16 v[66:69], v[158:161], v[190:193], v[66:69]
	s_barrier
; #define PG8_STAGE(bufoff, gbase, voff) do { _Pragma("unroll") for (int _i = 0; _i < 2; ++_i) \
;         __builtin_amdgcn_global_load_lds((const unsigned*)((const char*)(gbase) + (voff)[_i]), (PG8_LAS unsigned*)(lds + (bufoff) + ldsw + _i * 8192), 16, 0, 0); } while (0)
; #define PG8_WAIT_V(n) asm volatile("s_waitcnt vmcnt(" #n ")" ::: "memory")
; #define PG8_WAIT_L(n) asm volatile("s_waitcnt lgkmcnt(" #n ")" ::: "memory")
; #define PG8_BAR __builtin_amdgcn_s_barrier()
; #define PG8_SCHED __builtin_amdgcn_sched_barrier(0)
; template <class Epi, class Sched, bool ALIGN_EPI = true, bool SP2 = true>
; __device__ __forceinline__ void gemm_phase(PG8_LAS unsigned char* lds, const int K  , const Sched& S, const Epi& E) {
;     ...
;             PG8_LDA(At, 1, 1); PG8_STAGE(PG8_SB(1, 0), b3, voffB); PG8_STAGE(PG8_SB(1, 1), b3 + hstep, voffB); PG8_STAGE(PG8_SA(1, 0), a3, voffA);
;             PG8_WAIT_V(8); PG8_WAIT_L(0); PG8_BAR; PG8_MMA(1, 0, At, B0); PG8_MMA(1, 1, At, B1); PG8_BAR; PG8_SCHED;
;     ...
;         if constexpr (Epi::FP8) asm volatile("s_nop 15\n\ts_nop 15\n\ts_nop 15\n\ts_nop 15\n\ts_nop 15" ::: "memory");
;         if constexpr (ALIGN_EPI) { if (wr == 0) PG8_BAR; }
	s_setprio 0
	s_add_i32 s28, s74, s33
	v_lshl_add_u64 v[194:195], v[194:195], 0, s[8:9]
	s_mov_b32 m0, s28
	ds_read_b128 v[162:165], v234 offset:49152
	ds_read_b128 v[166:169], v234 offset:50176
	ds_read_b128 v[170:173], v234 offset:51200
	ds_read_b128 v[174:177], v234 offset:52224
	ds_read_b128 v[178:181], v234 offset:53248
	ds_read_b128 v[182:185], v234 offset:54272
	ds_read_b128 v[186:189], v234 offset:55296
	ds_read_b128 v[190:193], v234 offset:56320
	global_load_lds_dwordx4 v[194:195], off
	s_add_i32 m0, s28, 0x2000
	s_add_u32 s26, s26, 0x80080
	v_lshl_add_u64 v[194:195], v[196:197], 0, s[8:9]
	s_addc_u32 s27, s27, 0
	s_add_i32 s28, s75, s33
	global_load_lds_dwordx4 v[194:195], off
	s_mov_b32 m0, s28
	v_lshl_add_u64 v[194:195], s[26:27], 0, v[208:209]
	global_load_lds_dwordx4 v[194:195], off
	s_add_i32 m0, s28, 0x2000
	v_lshl_add_u64 v[194:195], s[26:27], 0, v[212:213]
	global_load_lds_dwordx4 v[194:195], off
	s_mov_b32 m0, s42
	v_lshl_add_u64 v[194:195], v[198:199], 0, s[8:9]
	global_load_lds_dwordx4 v[194:195], off
	s_mov_b32 m0, s43
	v_lshl_add_u64 v[194:195], v[200:201], 0, s[8:9]
	global_load_lds_dwordx4 v[194:195], off
	s_waitcnt vmcnt(8)
	s_waitcnt lgkmcnt(0)
	s_setprio 1
	s_barrier
	v_mfma_f32_16x16x32_bf16 v[62:65], v[130:133], v[162:165], v[62:65]
	v_mfma_f32_16x16x32_bf16 v[58:61], v[138:141], v[162:165], v[58:61]
	v_mfma_f32_16x16x32_bf16 v[54:57], v[130:133], v[170:173], v[54:57]
	v_mfma_f32_16x16x32_bf16 v[46:49], v[138:141], v[170:173], v[46:49]
	v_mfma_f32_16x16x32_bf16 v[38:41], v[130:133], v[178:181], v[38:41]
	v_mfma_f32_16x16x32_bf16 v[30:33], v[138:141], v[178:181], v[30:33]
	v_mfma_f32_16x16x32_bf16 v[22:25], v[130:133], v[186:189], v[22:25]
	v_mfma_f32_16x16x32_bf16 v[14:17], v[138:141], v[186:189], v[14:17]
	v_mfma_f32_16x16x32_bf16 v[62:65], v[134:137], v[166:169], v[62:65]
	v_mfma_f32_16x16x32_bf16 v[58:61], v[142:145], v[166:169], v[58:61]
	v_mfma_f32_16x16x32_bf16 v[54:57], v[134:137], v[174:177], v[54:57]
	v_mfma_f32_16x16x32_bf16 v[46:49], v[142:145], v[174:177], v[46:49]
	v_mfma_f32_16x16x32_bf16 v[38:41], v[134:137], v[182:185], v[38:41]
	v_mfma_f32_16x16x32_bf16 v[30:33], v[142:145], v[182:185], v[30:33]
	v_mfma_f32_16x16x32_bf16 v[22:25], v[134:137], v[190:193], v[22:25]
	v_mfma_f32_16x16x32_bf16 v[14:17], v[142:145], v[190:193], v[14:17]
	s_setprio 0
	s_setprio 1
	v_mfma_f32_16x16x32_bf16 v[50:53], v[146:149], v[162:165], v[50:53]
	v_mfma_f32_16x16x32_bf16 v[42:45], v[154:157], v[162:165], v[42:45]
	v_mfma_f32_16x16x32_bf16 v[34:37], v[146:149], v[170:173], v[34:37]
	v_mfma_f32_16x16x32_bf16 v[26:29], v[154:157], v[170:173], v[26:29]
	v_mfma_f32_16x16x32_bf16 v[18:21], v[146:149], v[178:181], v[18:21]
	v_mfma_f32_16x16x32_bf16 v[10:13], v[154:157], v[178:181], v[10:13]
	v_mfma_f32_16x16x32_bf16 v[6:9], v[146:149], v[186:189], v[6:9]
	v_mfma_f32_16x16x32_bf16 v[2:5], v[154:157], v[186:189], v[2:5]
	v_mfma_f32_16x16x32_bf16 v[50:53], v[150:153], v[166:169], v[50:53]
	v_mfma_f32_16x16x32_bf16 v[42:45], v[158:161], v[166:169], v[42:45]
	v_mfma_f32_16x16x32_bf16 v[34:37], v[150:153], v[174:177], v[34:37]
	v_mfma_f32_16x16x32_bf16 v[26:29], v[158:161], v[174:177], v[26:29]
	v_mfma_f32_16x16x32_bf16 v[18:21], v[150:153], v[182:185], v[18:21]
	v_mfma_f32_16x16x32_bf16 v[10:13], v[158:161], v[182:185], v[10:13]
	v_mfma_f32_16x16x32_bf16 v[6:9], v[150:153], v[190:193], v[6:9]
	v_mfma_f32_16x16x32_bf16 v[2:5], v[158:161], v[190:193], v[2:5]
	s_barrier
	s_setprio 0
	s_add_u32 s24, s24, 0x100
	s_addc_u32 s25, s25, 0
	s_add_u32 s15, s15, 0x100
	s_addc_u32 s21, s21, 0
	s_cmp_ge_u32 s73, s4
	s_mov_b32 s28, s73
	s_cbranch_scc0 .LBB0_955
	s_and_b64 vcc, exec, s[10:11]
	s_cbranch_vccz .LBB0_958
	s_barrier

; #define PG8_STAGE(bufoff, gbase, voff) do { _Pragma("unroll") for (int _i = 0; _i < 2; ++_i) \
;         __builtin_amdgcn_global_load_lds((const unsigned*)((const char*)(gbase) + (voff)[_i]), (PG8_LAS unsigned*)(lds + (bufoff) + ldsw + _i * 8192), 16, 0, 0); } while (0)
; #define PG8_WAIT_V(n) asm volatile("s_waitcnt vmcnt(" #n ")" ::: "memory")
; #define PG8_WAIT_L(n) asm volatile("s_waitcnt lgkmcnt(" #n ")" ::: "memory")
; #define PG8_BAR __builtin_amdgcn_s_barrier()
; #define PG8_SCHED __builtin_amdgcn_sched_barrier(0)
;     __device__ __forceinline__ int nt(const pg8::Unit& u) const { return u.kind == 0 ? ntiles : q_nt(u.kind - 1); }
; template <class Epi, class Sched, bool ALIGN_EPI = true, bool SP2 = true>
; __device__ __forceinline__ void gemm_phase(PG8_LAS unsigned char* lds, const int K  , const Sched& S, const Epi& E) {
;     ...
;         for (int t = 0; t < nt; t += 2) {
;             const bool last = (t == nt - 2);
;             const char* a1 = cA + (size_t)(t + 1) * kstep;
;             const char* a2 = last ? nA : cA + (size_t)(t + 2) * kstep; const char* b2 = last ? nB : cB + (size_t)(t + 2) * kstep;
;             const char* a3 = a2 + kstep; const char* b3 = b2 + kstep;
;             if constexpr (SP2) {
;             PG8_LDB(B0, 0, 0); PG8_LDB(B1, 0, 1); PG8_SCHED; PG8_LDA(At, 0, 0); PG8_STAGE(PG8_SA(1, 1), a1 + hstep, voffA);
;             PG8_WAIT_V(8); PG8_WAIT_L(0); PG8_BAR; PG8_MMA(0, 0, At, B0); PG8_MMA(0, 1, At, B1); PG8_BAR; PG8_SCHED;
;             PG8_LDA(At, 0, 1); PG8_STAGE(PG8_SB(0, 0), b2, voffB); PG8_STAGE(PG8_SB(0, 1), b2 + hstep, voffB); PG8_STAGE(PG8_SA(0, 0), a2, voffA);
.LBB0_1099:
	ds_read_b128 v[148:151], v154
	ds_read_b128 v[160:163], v154 offset:1024
	ds_read_b128 v[164:167], v154 offset:2048
	ds_read_b128 v[168:171], v154 offset:3072
	ds_read_b128 v[172:175], v155
	ds_read_b128 v[176:179], v155 offset:1024
	ds_read_b128 v[180:183], v155 offset:2048
	ds_read_b128 v[184:187], v155 offset:3072
	s_add_u32 s24, s22, 0xfff80080
	s_addc_u32 s25, s23, -1
	s_cmp_eq_u32 s48, 28
	s_cselect_b32 s27, s15, s25
	s_cselect_b32 s26, s44, s24
	s_cselect_b32 s25, s11, s47
	s_cselect_b32 s24, s45, s46
	v_lshl_add_u64 v[220:221], s[22:23], 0, v[140:141]
	s_add_i32 m0, s21, 0xc000
	ds_read_b128 v[188:191], v156
	ds_read_b128 v[192:195], v156 offset:1024
	ds_read_b128 v[196:199], v156 offset:2048
	ds_read_b128 v[200:203], v156 offset:3072
	ds_read_b128 v[204:207], v156 offset:4096
	ds_read_b128 v[208:211], v156 offset:5120
	ds_read_b128 v[212:215], v156 offset:6144
	ds_read_b128 v[216:219], v156 offset:7168
	global_load_lds_dwordx4 v[220:221], off
	s_add_i32 m0, s21, 0xe000
	v_lshl_add_u64 v[220:221], s[22:23], 0, v[142:143]
	global_load_lds_dwordx4 v[220:221], off
	s_waitcnt vmcnt(8)
	s_waitcnt lgkmcnt(0)
	s_setprio 1
	s_barrier
	v_mfma_f32_16x16x32_bf16 v[126:129], v[148:151], v[188:191], v[126:129]
	v_mfma_f32_16x16x32_bf16 v[118:121], v[164:167], v[188:191], v[118:121]
	v_mfma_f32_16x16x32_bf16 v[110:113], v[148:151], v[196:199], v[110:113]
	v_mfma_f32_16x16x32_bf16 v[102:105], v[164:167], v[196:199], v[102:105]
	v_mfma_f32_16x16x32_bf16 v[94:97], v[148:151], v[204:207], v[94:97]
	v_mfma_f32_16x16x32_bf16 v[86:89], v[164:167], v[204:207], v[86:89]
	v_mfma_f32_16x16x32_bf16 v[78:81], v[148:151], v[212:215], v[78:81]
	v_mfma_f32_16x16x32_bf16 v[70:73], v[164:167], v[212:215], v[70:73]
	v_mfma_f32_16x16x32_bf16 v[126:129], v[160:163], v[192:195], v[126:129]
	v_mfma_f32_16x16x32_bf16 v[118:121], v[168:171], v[192:195], v[118:121]
	v_mfma_f32_16x16x32_bf16 v[110:113], v[160:163], v[200:203], v[110:113]
	v_mfma_f32_16x16x32_bf16 v[102:105], v[168:171], v[200:203], v[102:105]
	v_mfma_f32_16x16x32_bf16 v[94:97], v[160:163], v[208:211], v[94:97]
	v_mfma_f32_16x16x32_bf16 v[86:89], v[168:171], v[208:211], v[86:89]
	v_mfma_f32_16x16x32_bf16 v[78:81], v[160:163], v[216:219], v[78:81]
	v_mfma_f32_16x16x32_bf16 v[70:73], v[168:171], v[216:219], v[70:73]
	s_setprio 0
	s_setprio 1
	v_mfma_f32_16x16x32_bf16 v[122:125], v[172:175], v[188:191], v[122:125]
	v_mfma_f32_16x16x32_bf16 v[114:117], v[180:183], v[188:191], v[114:117]
	v_mfma_f32_16x16x32_bf16 v[106:109], v[172:175], v[196:199], v[106:109]
	v_mfma_f32_16x16x32_bf16 v[98:101], v[180:183], v[196:199], v[98:101]
	v_mfma_f32_16x16x32_bf16 v[90:93], v[172:175], v[204:207], v[90:93]
	v_mfma_f32_16x16x32_bf16 v[82:85], v[180:183], v[204:207], v[82:85]
	v_mfma_f32_16x16x32_bf16 v[74:77], v[172:175], v[212:215], v[74:77]
	v_mfma_f32_16x16x32_bf16 v[66:69], v[180:183], v[212:215], v[66:69]
	v_mfma_f32_16x16x32_bf16 v[122:125], v[176:179], v[192:195], v[122:125]
	v_mfma_f32_16x16x32_bf16 v[114:117], v[184:187], v[192:195], v[114:117]
	v_mfma_f32_16x16x32_bf16 v[106:109], v[176:179], v[200:203], v[106:109]
	v_mfma_f32_16x16x32_bf16 v[98:101], v[184:187], v[200:203], v[98:101]
	v_mfma_f32_16x16x32_bf16 v[90:93], v[176:179], v[208:211], v[90:93]
	v_mfma_f32_16x16x32_bf16 v[82:85], v[184:187], v[208:211], v[82:85]
	v_mfma_f32_16x16x32_bf16 v[74:77], v[176:179], v[216:219], v[74:77]
	v_mfma_f32_16x16x32_bf16 v[66:69], v[184:187], v[216:219], v[66:69]
	s_barrier
	s_setprio 0
	s_add_i32 s49, s39, s29
	v_lshl_add_u64 v[220:221], s[24:25], 0, v[136:137]
	s_mov_b32 m0, s49
	ds_read_b128 v[188:191], v156 offset:16384
	ds_read_b128 v[192:195], v156 offset:17408
	ds_read_b128 v[196:199], v156 offset:18432
	ds_read_b128 v[200:203], v156 offset:19456
	ds_read_b128 v[204:207], v156 offset:20480
	ds_read_b128 v[208:211], v156 offset:21504
	ds_read_b128 v[212:215], v156 offset:22528
	ds_read_b128 v[216:219], v156 offset:23552
	global_load_lds_dwordx4 v[220:221], off
	s_add_i32 m0, s49, 0x2000
	s_add_u32 s50, s24, 0x80000
	v_lshl_add_u64 v[222:223], s[24:25], 0, v[132:133]
	s_addc_u32 s51, s25, 0
	s_add_i32 s49, s40, s29
	global_load_lds_dwordx4 v[222:223], off
	v_lshl_add_u64 v[224:225], s[50:51], 0, v[136:137]
	s_mov_b32 m0, s49
	v_lshl_add_u64 v[226:227], s[26:27], 0, v[134:135]
	global_load_lds_dwordx4 v[224:225], off
	s_add_i32 m0, s49, 0x2000
	v_lshl_add_u64 v[224:225], s[50:51], 0, v[132:133]
	global_load_lds_dwordx4 v[224:225], off
	s_mov_b32 m0, s21
	v_lshl_add_u64 v[224:225], s[26:27], 0, v[138:139]
	global_load_lds_dwordx4 v[224:225], off
	s_mov_b32 m0, s31
	s_nop 0
	global_load_lds_dwordx4 v[226:227], off
	s_waitcnt vmcnt(8)
	s_waitcnt lgkmcnt(0)
	s_setprio 1
	s_barrier
; #define PG8_STAGE(bufoff, gbase, voff) do { _Pragma("unroll") for (int _i = 0; _i < 2; ++_i) \
;         __builtin_amdgcn_global_load_lds((const unsigned*)((const char*)(gbase) + (voff)[_i]), (PG8_LAS unsigned*)(lds + (bufoff) + ldsw + _i * 8192), 16, 0, 0); } while (0)
; #define PG8_WAIT_V(n) asm volatile("s_waitcnt vmcnt(" #n ")" ::: "memory")
; #define PG8_WAIT_L(n) asm volatile("s_waitcnt lgkmcnt(" #n ")" ::: "memory")
; #define PG8_BAR __builtin_amdgcn_s_barrier()
; #define PG8_SCHED __builtin_amdgcn_sched_barrier(0)
; template <class Epi, class Sched, bool ALIGN_EPI = true, bool SP2 = true>
; __device__ __forceinline__ void gemm_phase(PG8_LAS unsigned char* lds, const int K  , const Sched& S, const Epi& E) {
;     ...
;             PG8_WAIT_V(8); PG8_WAIT_L(0); PG8_BAR; PG8_MMA(1, 0, At, B0); PG8_MMA(1, 1, At, B1); PG8_BAR; PG8_SCHED;
;             PG8_LDB(B0, 1, 0); PG8_LDB(B1, 1, 1); PG8_SCHED; PG8_LDA(At, 1, 0); PG8_STAGE(PG8_SA(0, 1), a2 + hstep, voffA);
;             PG8_WAIT_V(8); PG8_WAIT_L(0); PG8_BAR; PG8_MMA(0, 0, At, B0); PG8_MMA(0, 1, At, B1); PG8_BAR; PG8_SCHED;
	v_mfma_f32_16x16x32_bf16 v[62:65], v[148:151], v[188:191], v[62:65]
	v_mfma_f32_16x16x32_bf16 v[54:57], v[164:167], v[188:191], v[54:57]
	v_mfma_f32_16x16x32_bf16 v[46:49], v[148:151], v[196:199], v[46:49]
	v_mfma_f32_16x16x32_bf16 v[38:41], v[164:167], v[196:199], v[38:41]
	v_mfma_f32_16x16x32_bf16 v[30:33], v[148:151], v[204:207], v[30:33]
	v_mfma_f32_16x16x32_bf16 v[22:25], v[164:167], v[204:207], v[22:25]
	v_mfma_f32_16x16x32_bf16 v[14:17], v[148:151], v[212:215], v[14:17]
	v_mfma_f32_16x16x32_bf16 v[6:9], v[164:167], v[212:215], v[6:9]
	v_mfma_f32_16x16x32_bf16 v[62:65], v[160:163], v[192:195], v[62:65]
	v_mfma_f32_16x16x32_bf16 v[54:57], v[168:171], v[192:195], v[54:57]
	v_mfma_f32_16x16x32_bf16 v[46:49], v[160:163], v[200:203], v[46:49]
	v_mfma_f32_16x16x32_bf16 v[38:41], v[168:171], v[200:203], v[38:41]
	v_mfma_f32_16x16x32_bf16 v[30:33], v[160:163], v[208:211], v[30:33]
	v_mfma_f32_16x16x32_bf16 v[22:25], v[168:171], v[208:211], v[22:25]
	v_mfma_f32_16x16x32_bf16 v[14:17], v[160:163], v[216:219], v[14:17]
	v_mfma_f32_16x16x32_bf16 v[6:9], v[168:171], v[216:219], v[6:9]
	s_setprio 0
	s_setprio 1
	v_mfma_f32_16x16x32_bf16 v[58:61], v[172:175], v[188:191], v[58:61]
	v_mfma_f32_16x16x32_bf16 v[50:53], v[180:183], v[188:191], v[50:53]
	v_mfma_f32_16x16x32_bf16 v[42:45], v[172:175], v[196:199], v[42:45]
	v_mfma_f32_16x16x32_bf16 v[34:37], v[180:183], v[196:199], v[34:37]
	v_mfma_f32_16x16x32_bf16 v[26:29], v[172:175], v[204:207], v[26:29]
	v_mfma_f32_16x16x32_bf16 v[18:21], v[180:183], v[204:207], v[18:21]
	v_mfma_f32_16x16x32_bf16 v[10:13], v[172:175], v[212:215], v[10:13]
	v_mfma_f32_16x16x32_bf16 v[2:5], v[180:183], v[212:215], v[2:5]
	v_mfma_f32_16x16x32_bf16 v[58:61], v[176:179], v[192:195], v[58:61]
	v_mfma_f32_16x16x32_bf16 v[50:53], v[184:187], v[192:195], v[50:53]
	v_mfma_f32_16x16x32_bf16 v[42:45], v[176:179], v[200:203], v[42:45]
	v_mfma_f32_16x16x32_bf16 v[34:37], v[184:187], v[200:203], v[34:37]
	v_mfma_f32_16x16x32_bf16 v[26:29], v[176:179], v[208:211], v[26:29]
	v_mfma_f32_16x16x32_bf16 v[18:21], v[184:187], v[208:211], v[18:21]
	v_mfma_f32_16x16x32_bf16 v[10:13], v[176:179], v[216:219], v[10:13]
	v_mfma_f32_16x16x32_bf16 v[2:5], v[184:187], v[216:219], v[2:5]
	s_barrier
	s_setprio 0
	s_add_i32 s49, 0, 0x18000
	v_add_u32_e32 v159, s49, v152
	s_add_i32 s50, 0, 0x1c000
	ds_read_b128 v[148:151], v159
	ds_read_b128 v[160:163], v159 offset:1024
	ds_read_b128 v[164:167], v159 offset:2048
	ds_read_b128 v[168:171], v159 offset:3072
	v_add_u32_e32 v159, s50, v152
	ds_read_b128 v[172:175], v159
	ds_read_b128 v[176:179], v159 offset:1024
	ds_read_b128 v[180:183], v159 offset:2048
	ds_read_b128 v[184:187], v159 offset:3072
	s_add_u32 s26, s26, 0x80000
	s_addc_u32 s27, s27, 0
	s_mov_b32 m0, s33
	v_lshl_add_u64 v[230:231], s[26:27], 0, v[138:139]
	ds_read_b128 v[188:191], v156 offset:32768
	ds_read_b128 v[192:195], v156 offset:33792
	ds_read_b128 v[196:199], v156 offset:34816
	ds_read_b128 v[200:203], v156 offset:35840
	ds_read_b128 v[204:207], v156 offset:36864
	ds_read_b128 v[208:211], v156 offset:37888
	ds_read_b128 v[212:215], v156 offset:38912
	ds_read_b128 v[216:219], v156 offset:39936
	global_load_lds_dwordx4 v[230:231], off
	s_mov_b32 m0, s34
	v_lshl_add_u64 v[230:231], s[26:27], 0, v[134:135]
	global_load_lds_dwordx4 v[230:231], off
	s_waitcnt vmcnt(8)
	s_waitcnt lgkmcnt(0)
	s_setprio 1
	s_barrier
	v_mfma_f32_16x16x32_bf16 v[126:129], v[148:151], v[188:191], v[126:129]
	v_mfma_f32_16x16x32_bf16 v[118:121], v[164:167], v[188:191], v[118:121]
	v_mfma_f32_16x16x32_bf16 v[110:113], v[148:151], v[196:199], v[110:113]
	v_mfma_f32_16x16x32_bf16 v[102:105], v[164:167], v[196:199], v[102:105]
	v_mfma_f32_16x16x32_bf16 v[94:97], v[148:151], v[204:207], v[94:97]
	v_mfma_f32_16x16x32_bf16 v[86:89], v[164:167], v[204:207], v[86:89]
	v_mfma_f32_16x16x32_bf16 v[78:81], v[148:151], v[212:215], v[78:81]
	v_mfma_f32_16x16x32_bf16 v[70:73], v[164:167], v[212:215], v[70:73]
	v_mfma_f32_16x16x32_bf16 v[126:129], v[160:163], v[192:195], v[126:129]
	v_mfma_f32_16x16x32_bf16 v[118:121], v[168:171], v[192:195], v[118:121]
	v_mfma_f32_16x16x32_bf16 v[110:113], v[160:163], v[200:203], v[110:113]
	v_mfma_f32_16x16x32_bf16 v[102:105], v[168:171], v[200:203], v[102:105]
	v_mfma_f32_16x16x32_bf16 v[94:97], v[160:163], v[208:211], v[94:97]
	v_mfma_f32_16x16x32_bf16 v[86:89], v[168:171], v[208:211], v[86:89]
	v_mfma_f32_16x16x32_bf16 v[78:81], v[160:163], v[216:219], v[78:81]
	v_mfma_f32_16x16x32_bf16 v[70:73], v[168:171], v[216:219], v[70:73]
	s_setprio 0
	s_setprio 1
	v_mfma_f32_16x16x32_bf16 v[122:125], v[172:175], v[188:191], v[122:125]
	v_mfma_f32_16x16x32_bf16 v[114:117], v[180:183], v[188:191], v[114:117]
	v_mfma_f32_16x16x32_bf16 v[106:109], v[172:175], v[196:199], v[106:109]
	v_mfma_f32_16x16x32_bf16 v[98:101], v[180:183], v[196:199], v[98:101]
	v_mfma_f32_16x16x32_bf16 v[90:93], v[172:175], v[204:207], v[90:93]
	v_mfma_f32_16x16x32_bf16 v[82:85], v[180:183], v[204:207], v[82:85]
	v_mfma_f32_16x16x32_bf16 v[74:77], v[172:175], v[212:215], v[74:77]
	v_mfma_f32_16x16x32_bf16 v[66:69], v[180:183], v[212:215], v[66:69]
	v_mfma_f32_16x16x32_bf16 v[122:125], v[176:179], v[192:195], v[122:125]
	v_mfma_f32_16x16x32_bf16 v[114:117], v[184:187], v[192:195], v[114:117]
	v_mfma_f32_16x16x32_bf16 v[106:109], v[176:179], v[200:203], v[106:109]
	v_mfma_f32_16x16x32_bf16 v[98:101], v[184:187], v[200:203], v[98:101]
	v_mfma_f32_16x16x32_bf16 v[90:93], v[176:179], v[208:211], v[90:93]
	v_mfma_f32_16x16x32_bf16 v[82:85], v[184:187], v[208:211], v[82:85]
	v_mfma_f32_16x16x32_bf16 v[74:77], v[176:179], v[216:219], v[74:77]
	v_mfma_f32_16x16x32_bf16 v[66:69], v[184:187], v[216:219], v[66:69]
	s_barrier
; #define PG8_STAGE(bufoff, gbase, voff) do { _Pragma("unroll") for (int _i = 0; _i < 2; ++_i) \
;         __builtin_amdgcn_global_load_lds((const unsigned*)((const char*)(gbase) + (voff)[_i]), (PG8_LAS unsigned*)(lds + (bufoff) + ldsw + _i * 8192), 16, 0, 0); } while (0)
; #define PG8_WAIT_V(n) asm volatile("s_waitcnt vmcnt(" #n ")" ::: "memory")
; #define PG8_WAIT_L(n) asm volatile("s_waitcnt lgkmcnt(" #n ")" ::: "memory")
; #define PG8_BAR __builtin_amdgcn_s_barrier()
; #define PG8_SCHED __builtin_amdgcn_sched_barrier(0)
; template <class Epi, class Sched, bool ALIGN_EPI = true, bool SP2 = true>
; __device__ __forceinline__ void gemm_phase(PG8_LAS unsigned char* lds, const int K  , const Sched& S, const Epi& E) {
;     ...
;             PG8_LDA(At, 1, 1); PG8_STAGE(PG8_SB(1, 0), b3, voffB); PG8_STAGE(PG8_SB(1, 1), b3 + hstep, voffB); PG8_STAGE(PG8_SA(1, 0), a3, voffA);
;             PG8_WAIT_V(8); PG8_WAIT_L(0); PG8_BAR; PG8_MMA(1, 0, At, B0); PG8_MMA(1, 1, At, B1); PG8_BAR; PG8_SCHED;
;     ...
;         if constexpr (ALIGN_EPI) { if (wr == 0) PG8_BAR; }
	s_setprio 0
	s_add_i32 s26, s49, s29
	v_lshl_add_u64 v[220:221], v[220:221], 0, s[4:5]
	s_mov_b32 m0, s26
	ds_read_b128 v[188:191], v156 offset:49152
	ds_read_b128 v[192:195], v156 offset:50176
	ds_read_b128 v[196:199], v156 offset:51200
	ds_read_b128 v[200:203], v156 offset:52224
	ds_read_b128 v[204:207], v156 offset:53248
	ds_read_b128 v[208:211], v156 offset:54272
	ds_read_b128 v[212:215], v156 offset:55296
	ds_read_b128 v[216:219], v156 offset:56320
	global_load_lds_dwordx4 v[220:221], off
	s_add_i32 m0, s26, 0x2000
	s_add_u32 s24, s24, 0x80080
	v_lshl_add_u64 v[220:221], v[222:223], 0, s[4:5]
	s_addc_u32 s25, s25, 0
	s_add_i32 s26, s50, s29
	global_load_lds_dwordx4 v[220:221], off
	s_mov_b32 m0, s26
	v_lshl_add_u64 v[220:221], s[24:25], 0, v[136:137]
	global_load_lds_dwordx4 v[220:221], off
	s_add_i32 m0, s26, 0x2000
	v_lshl_add_u64 v[220:221], s[24:25], 0, v[132:133]
	global_load_lds_dwordx4 v[220:221], off
	s_mov_b32 m0, s36
	v_lshl_add_u64 v[220:221], v[224:225], 0, s[4:5]
	global_load_lds_dwordx4 v[220:221], off
	s_mov_b32 m0, s37
	v_lshl_add_u64 v[220:221], v[226:227], 0, s[4:5]
	global_load_lds_dwordx4 v[220:221], off
	s_waitcnt vmcnt(8)
	s_waitcnt lgkmcnt(0)
	s_setprio 1
	s_barrier
	v_mfma_f32_16x16x32_bf16 v[62:65], v[148:151], v[188:191], v[62:65]
	v_mfma_f32_16x16x32_bf16 v[54:57], v[164:167], v[188:191], v[54:57]
	v_mfma_f32_16x16x32_bf16 v[46:49], v[148:151], v[196:199], v[46:49]
	v_mfma_f32_16x16x32_bf16 v[38:41], v[164:167], v[196:199], v[38:41]
	v_mfma_f32_16x16x32_bf16 v[30:33], v[148:151], v[204:207], v[30:33]
	v_mfma_f32_16x16x32_bf16 v[22:25], v[164:167], v[204:207], v[22:25]
	v_mfma_f32_16x16x32_bf16 v[14:17], v[148:151], v[212:215], v[14:17]
	v_mfma_f32_16x16x32_bf16 v[6:9], v[164:167], v[212:215], v[6:9]
	v_mfma_f32_16x16x32_bf16 v[62:65], v[160:163], v[192:195], v[62:65]
	v_mfma_f32_16x16x32_bf16 v[54:57], v[168:171], v[192:195], v[54:57]
	v_mfma_f32_16x16x32_bf16 v[46:49], v[160:163], v[200:203], v[46:49]
	v_mfma_f32_16x16x32_bf16 v[38:41], v[168:171], v[200:203], v[38:41]
	v_mfma_f32_16x16x32_bf16 v[30:33], v[160:163], v[208:211], v[30:33]
	v_mfma_f32_16x16x32_bf16 v[22:25], v[168:171], v[208:211], v[22:25]
	v_mfma_f32_16x16x32_bf16 v[14:17], v[160:163], v[216:219], v[14:17]
	v_mfma_f32_16x16x32_bf16 v[6:9], v[168:171], v[216:219], v[6:9]
	s_setprio 0
	s_setprio 1
	v_mfma_f32_16x16x32_bf16 v[58:61], v[172:175], v[188:191], v[58:61]
	v_mfma_f32_16x16x32_bf16 v[50:53], v[180:183], v[188:191], v[50:53]
	v_mfma_f32_16x16x32_bf16 v[42:45], v[172:175], v[196:199], v[42:45]
	v_mfma_f32_16x16x32_bf16 v[34:37], v[180:183], v[196:199], v[34:37]
	v_mfma_f32_16x16x32_bf16 v[26:29], v[172:175], v[204:207], v[26:29]
	v_mfma_f32_16x16x32_bf16 v[18:21], v[180:183], v[204:207], v[18:21]
	v_mfma_f32_16x16x32_bf16 v[10:13], v[172:175], v[212:215], v[10:13]
	v_mfma_f32_16x16x32_bf16 v[2:5], v[180:183], v[212:215], v[2:5]
	v_mfma_f32_16x16x32_bf16 v[58:61], v[176:179], v[192:195], v[58:61]
	v_mfma_f32_16x16x32_bf16 v[50:53], v[184:187], v[192:195], v[50:53]
	v_mfma_f32_16x16x32_bf16 v[42:45], v[176:179], v[200:203], v[42:45]
	v_mfma_f32_16x16x32_bf16 v[34:37], v[184:187], v[200:203], v[34:37]
	v_mfma_f32_16x16x32_bf16 v[26:29], v[176:179], v[208:211], v[26:29]
	v_mfma_f32_16x16x32_bf16 v[18:21], v[184:187], v[208:211], v[18:21]
	v_mfma_f32_16x16x32_bf16 v[10:13], v[176:179], v[216:219], v[10:13]
	v_mfma_f32_16x16x32_bf16 v[2:5], v[184:187], v[216:219], v[2:5]
	s_barrier
	s_setprio 0
	s_add_i32 s48, s48, 2
	s_add_u32 s22, s22, 0x100
	s_addc_u32 s23, s23, 0
	s_add_u32 s46, s46, 0x100
	s_addc_u32 s47, s47, 0
	s_cmp_gt_u32 s48, 29
	s_cbranch_scc0 .LBB0_1099
	s_and_b64 vcc, exec, s[8:9]
	s_cbranch_vccz .LBB0_1102
	s_barrier

; #define PG8_STAGE(bufoff, gbase, voff) do { _Pragma("unroll") for (int _i = 0; _i < 2; ++_i) \
;         __builtin_amdgcn_global_load_lds((const unsigned*)((const char*)(gbase) + (voff)[_i]), (PG8_LAS unsigned*)(lds + (bufoff) + ldsw + _i * 8192), 16, 0, 0); } while (0)
; #define PG8_WAIT_V(n) asm volatile("s_waitcnt vmcnt(" #n ")" ::: "memory")
; #define PG8_WAIT_L(n) asm volatile("s_waitcnt lgkmcnt(" #n ")" ::: "memory")
; #define PG8_BAR __builtin_amdgcn_s_barrier()
; #define PG8_SCHED __builtin_amdgcn_sched_barrier(0)
;     __device__ __forceinline__ int nt(const pg8::Unit& u) const { return u.kind == 0 ? ntiles : q_nt(u.kind - 1); }
; template <class Epi, class Sched, bool ALIGN_EPI = true, bool SP2 = true>
; __device__ __forceinline__ void gemm_phase(PG8_LAS unsigned char* lds, const int K  , const Sched& S, const Epi& E) {
;     ...
;         for (int t = 0; t < nt; t += 2) {
;             const bool last = (t == nt - 2);
;             const char* a1 = cA + (size_t)(t + 1) * kstep;
;             const char* a2 = last ? nA : cA + (size_t)(t + 2) * kstep; const char* b2 = last ? nB : cB + (size_t)(t + 2) * kstep;
;             const char* a3 = a2 + kstep; const char* b3 = b2 + kstep;
;             if constexpr (SP2) {
;             PG8_LDB(B0, 0, 0); PG8_LDB(B1, 0, 1); PG8_SCHED; PG8_LDA(At, 0, 0); PG8_STAGE(PG8_SA(1, 1), a1 + hstep, voffA);
;             PG8_WAIT_V(8); PG8_WAIT_L(0); PG8_BAR; PG8_MMA(0, 0, At, B0); PG8_MMA(0, 1, At, B1); PG8_BAR; PG8_SCHED;
;             PG8_LDA(At, 0, 1); PG8_STAGE(PG8_SB(0, 0), b2, voffB); PG8_STAGE(PG8_SB(0, 1), b2 + hstep, voffB); PG8_STAGE(PG8_SA(0, 0), a2, voffA);
;             PG8_WAIT_V(8); PG8_WAIT_L(0); PG8_BAR; PG8_MMA(1, 0, At, B0); PG8_MMA(1, 1, At, B1); PG8_BAR; PG8_SCHED;
.LBB0_1304:
	ds_read_b128 v[18:21], v233
	ds_read_b128 v[22:25], v233 offset:1024
	ds_read_b128 v[26:29], v233 offset:2048
	ds_read_b128 v[30:33], v233 offset:3072
	ds_read_b128 v[2:5], v234
	ds_read_b128 v[6:9], v234 offset:1024
	ds_read_b128 v[10:13], v234 offset:2048
	ds_read_b128 v[14:17], v234 offset:3072
	s_add_i32 s74, s22, 2
	s_add_u32 s20, s18, 0xfff50080
	s_addc_u32 s21, s19, -1
	s_cmp_eq_u32 s71, s22
	s_cselect_b32 s22, s14, s20
	s_cselect_b32 s23, s15, s21
	s_cselect_b32 s21, s17, s73
	s_cselect_b32 s20, s16, s72
	v_lshl_add_u64 v[186:187], s[18:19], 0, v[198:199]
	s_add_i32 m0, s26, 0xc000
	ds_read_b128 v[162:165], v235
	ds_read_b128 v[166:169], v235 offset:1024
	ds_read_b128 v[170:173], v235 offset:2048
	ds_read_b128 v[174:177], v235 offset:3072
	ds_read_b128 v[178:181], v235 offset:4096
	ds_read_b128 v[182:185], v235 offset:5120
	ds_read_b128 v[206:209], v235 offset:6144
	ds_read_b128 v[210:213], v235 offset:7168
	global_load_lds_dwordx4 v[186:187], off
	s_add_i32 m0, s26, 0xe000
	v_lshl_add_u64 v[186:187], s[18:19], 0, v[200:201]
	global_load_lds_dwordx4 v[186:187], off
	s_waitcnt vmcnt(8)
	s_waitcnt lgkmcnt(0)
	s_setprio 1
	s_barrier
	v_mfma_scale_f32_16x16x128_f8f6f4 v[158:161], v[18:25], v[162:169], v[158:161], v229, v229 op_sel_hi:[0,0,0]
	v_mfma_scale_f32_16x16x128_f8f6f4 v[154:157], v[26:33], v[162:169], v[154:157], v229, v229 op_sel_hi:[0,0,0]
	v_mfma_scale_f32_16x16x128_f8f6f4 v[150:153], v[18:25], v[170:177], v[150:153], v229, v229 op_sel_hi:[0,0,0]
	v_mfma_scale_f32_16x16x128_f8f6f4 v[142:145], v[26:33], v[170:177], v[142:145], v229, v229 op_sel_hi:[0,0,0]
	v_mfma_scale_f32_16x16x128_f8f6f4 v[134:137], v[18:25], v[178:185], v[134:137], v229, v229 op_sel_hi:[0,0,0]
	v_mfma_scale_f32_16x16x128_f8f6f4 v[126:129], v[26:33], v[178:185], v[126:129], v229, v229 op_sel_hi:[0,0,0]
	v_mfma_scale_f32_16x16x128_f8f6f4 v[118:121], v[18:25], v[206:213], v[118:121], v229, v229 op_sel_hi:[0,0,0]
	v_mfma_scale_f32_16x16x128_f8f6f4 v[110:113], v[26:33], v[206:213], v[110:113], v229, v229 op_sel_hi:[0,0,0]
	s_setprio 0
	s_setprio 1
	v_mfma_scale_f32_16x16x128_f8f6f4 v[146:149], v[2:9], v[162:169], v[146:149], v229, v229 op_sel_hi:[0,0,0]
	v_mfma_scale_f32_16x16x128_f8f6f4 v[138:141], v[10:17], v[162:169], v[138:141], v229, v229 op_sel_hi:[0,0,0]
	v_mfma_scale_f32_16x16x128_f8f6f4 v[130:133], v[2:9], v[170:177], v[130:133], v229, v229 op_sel_hi:[0,0,0]
	v_mfma_scale_f32_16x16x128_f8f6f4 v[122:125], v[10:17], v[170:177], v[122:125], v229, v229 op_sel_hi:[0,0,0]
	v_mfma_scale_f32_16x16x128_f8f6f4 v[114:117], v[2:9], v[178:185], v[114:117], v229, v229 op_sel_hi:[0,0,0]
	v_mfma_scale_f32_16x16x128_f8f6f4 v[106:109], v[10:17], v[178:185], v[106:109], v229, v229 op_sel_hi:[0,0,0]
	v_mfma_scale_f32_16x16x128_f8f6f4 v[102:105], v[2:9], v[206:213], v[102:105], v229, v229 op_sel_hi:[0,0,0]
	v_mfma_scale_f32_16x16x128_f8f6f4 v[98:101], v[10:17], v[206:213], v[98:101], v229, v229 op_sel_hi:[0,0,0]
	s_barrier
	s_setprio 0
	s_add_i32 s75, s40, s25
	v_lshl_add_u64 v[162:163], s[20:21], 0, v[192:193]
	s_mov_b32 m0, s75
	ds_read_b128 v[170:173], v235 offset:16384
	ds_read_b128 v[174:177], v235 offset:17408
	ds_read_b128 v[178:181], v235 offset:18432
	ds_read_b128 v[182:185], v235 offset:19456
	ds_read_b128 v[206:209], v235 offset:20480
	ds_read_b128 v[210:213], v235 offset:21504
	ds_read_b128 v[214:217], v235 offset:22528
	ds_read_b128 v[218:221], v235 offset:23552
	global_load_lds_dwordx4 v[162:163], off
	s_add_i32 m0, s75, 0x2000
	s_add_u32 s76, s20, 0xb0000
	v_lshl_add_u64 v[164:165], s[20:21], 0, v[196:197]
	s_addc_u32 s77, s21, 0
	s_add_i32 s75, s41, s25
	global_load_lds_dwordx4 v[164:165], off
	v_lshl_add_u64 v[166:167], s[76:77], 0, v[192:193]
	s_mov_b32 m0, s75
	v_lshl_add_u64 v[168:169], s[22:23], 0, v[194:195]
	global_load_lds_dwordx4 v[166:167], off
	s_add_i32 m0, s75, 0x2000
	v_lshl_add_u64 v[166:167], s[76:77], 0, v[196:197]
	global_load_lds_dwordx4 v[166:167], off
	s_mov_b32 m0, s26
	v_lshl_add_u64 v[166:167], s[22:23], 0, v[190:191]
	global_load_lds_dwordx4 v[166:167], off
	s_mov_b32 m0, s27
	s_nop 0
	global_load_lds_dwordx4 v[168:169], off
	s_waitcnt vmcnt(8)
	s_waitcnt lgkmcnt(0)
	s_setprio 1
	s_barrier
	v_mfma_scale_f32_16x16x128_f8f6f4 v[94:97], v[18:25], v[170:177], v[94:97], v229, v229 op_sel_hi:[0,0,0]
	v_mfma_scale_f32_16x16x128_f8f6f4 v[90:93], v[26:33], v[170:177], v[90:93], v229, v229 op_sel_hi:[0,0,0]
	v_mfma_scale_f32_16x16x128_f8f6f4 v[86:89], v[18:25], v[178:185], v[86:89], v229, v229 op_sel_hi:[0,0,0]
	v_mfma_scale_f32_16x16x128_f8f6f4 v[78:81], v[26:33], v[178:185], v[78:81], v229, v229 op_sel_hi:[0,0,0]
	v_mfma_scale_f32_16x16x128_f8f6f4 v[70:73], v[18:25], v[206:213], v[70:73], v229, v229 op_sel_hi:[0,0,0]
	v_mfma_scale_f32_16x16x128_f8f6f4 v[62:65], v[26:33], v[206:213], v[62:65], v229, v229 op_sel_hi:[0,0,0]
	v_mfma_scale_f32_16x16x128_f8f6f4 v[54:57], v[18:25], v[214:221], v[54:57], v229, v229 op_sel_hi:[0,0,0]
	v_mfma_scale_f32_16x16x128_f8f6f4 v[46:49], v[26:33], v[214:221], v[46:49], v229, v229 op_sel_hi:[0,0,0]
	s_setprio 0
	s_setprio 1
	v_mfma_scale_f32_16x16x128_f8f6f4 v[82:85], v[2:9], v[170:177], v[82:85], v229, v229 op_sel_hi:[0,0,0]
	v_mfma_scale_f32_16x16x128_f8f6f4 v[74:77], v[10:17], v[170:177], v[74:77], v229, v229 op_sel_hi:[0,0,0]
	v_mfma_scale_f32_16x16x128_f8f6f4 v[66:69], v[2:9], v[178:185], v[66:69], v229, v229 op_sel_hi:[0,0,0]
	v_mfma_scale_f32_16x16x128_f8f6f4 v[58:61], v[10:17], v[178:185], v[58:61], v229, v229 op_sel_hi:[0,0,0]
	v_mfma_scale_f32_16x16x128_f8f6f4 v[50:53], v[2:9], v[206:213], v[50:53], v229, v229 op_sel_hi:[0,0,0]
	v_mfma_scale_f32_16x16x128_f8f6f4 v[42:45], v[10:17], v[206:213], v[42:45], v229, v229 op_sel_hi:[0,0,0]
	v_mfma_scale_f32_16x16x128_f8f6f4 v[38:41], v[2:9], v[214:221], v[38:41], v229, v229 op_sel_hi:[0,0,0]
	v_mfma_scale_f32_16x16x128_f8f6f4 v[34:37], v[10:17], v[214:221], v[34:37], v229, v229 op_sel_hi:[0,0,0]
	s_barrier
; #define PG8_STAGE(bufoff, gbase, voff) do { _Pragma("unroll") for (int _i = 0; _i < 2; ++_i) \
;         __builtin_amdgcn_global_load_lds((const unsigned*)((const char*)(gbase) + (voff)[_i]), (PG8_LAS unsigned*)(lds + (bufoff) + ldsw + _i * 8192), 16, 0, 0); } while (0)
; #define PG8_WAIT_V(n) asm volatile("s_waitcnt vmcnt(" #n ")" ::: "memory")
; #define PG8_WAIT_L(n) asm volatile("s_waitcnt lgkmcnt(" #n ")" ::: "memory")
; #define PG8_BAR __builtin_amdgcn_s_barrier()
; #define PG8_SCHED __builtin_amdgcn_sched_barrier(0)
; template <class Epi, class Sched, bool ALIGN_EPI = true, bool SP2 = true>
; __device__ __forceinline__ void gemm_phase(PG8_LAS unsigned char* lds, const int K  , const Sched& S, const Epi& E) {
;     ...
;             PG8_LDB(B0, 1, 0); PG8_LDB(B1, 1, 1); PG8_SCHED; PG8_LDA(At, 1, 0); PG8_STAGE(PG8_SA(0, 1), a2 + hstep, voffA);
;             PG8_WAIT_V(8); PG8_WAIT_L(0); PG8_BAR; PG8_MMA(0, 0, At, B0); PG8_MMA(0, 1, At, B1); PG8_BAR; PG8_SCHED;
;             PG8_LDA(At, 1, 1); PG8_STAGE(PG8_SB(1, 0), b3, voffB); PG8_STAGE(PG8_SB(1, 1), b3 + hstep, voffB); PG8_STAGE(PG8_SA(1, 0), a3, voffA);
;             PG8_WAIT_V(8); PG8_WAIT_L(0); PG8_BAR; PG8_MMA(1, 0, At, B0); PG8_MMA(1, 1, At, B1); PG8_BAR; PG8_SCHED;
;     ...
;         if constexpr (Epi::FP8) asm volatile("s_nop 15\n\ts_nop 15\n\ts_nop 15\n\ts_nop 15\n\ts_nop 15" ::: "memory");
;         if constexpr (ALIGN_EPI) { if (wr == 0) PG8_BAR; }
	s_setprio 0
	s_add_i32 s75, 0, 0x18000
	s_add_i32 s76, 0, 0x1c000
	v_add_u32_e32 v14, s75, v231
	v_add_u32_e32 v30, s76, v231
	ds_read_b128 v[2:5], v14
	ds_read_b128 v[6:9], v14 offset:1024
	ds_read_b128 v[10:13], v14 offset:2048
	ds_read_b128 v[14:17], v14 offset:3072
	ds_read_b128 v[18:21], v30
	ds_read_b128 v[22:25], v30 offset:1024
	ds_read_b128 v[26:29], v30 offset:2048
	ds_read_b128 v[30:33], v30 offset:3072
	s_add_u32 s22, s22, 0xb0000
	s_addc_u32 s23, s23, 0
	s_mov_b32 m0, s28
	v_lshl_add_u64 v[186:187], s[22:23], 0, v[190:191]
	ds_read_b128 v[170:173], v235 offset:32768
	ds_read_b128 v[174:177], v235 offset:33792
	ds_read_b128 v[178:181], v235 offset:34816
	ds_read_b128 v[182:185], v235 offset:35840
	ds_read_b128 v[206:209], v235 offset:36864
	ds_read_b128 v[210:213], v235 offset:37888
	ds_read_b128 v[214:217], v235 offset:38912
	ds_read_b128 v[218:221], v235 offset:39936
	global_load_lds_dwordx4 v[186:187], off
	s_mov_b32 m0, s29
	v_lshl_add_u64 v[186:187], s[22:23], 0, v[194:195]
	global_load_lds_dwordx4 v[186:187], off
	s_waitcnt vmcnt(8)
	s_waitcnt lgkmcnt(0)
	s_setprio 1
	s_barrier
	v_mfma_scale_f32_16x16x128_f8f6f4 v[158:161], v[2:9], v[170:177], v[158:161], v229, v229 op_sel_hi:[0,0,0]
	v_mfma_scale_f32_16x16x128_f8f6f4 v[154:157], v[10:17], v[170:177], v[154:157], v229, v229 op_sel_hi:[0,0,0]
	v_mfma_scale_f32_16x16x128_f8f6f4 v[150:153], v[2:9], v[178:185], v[150:153], v229, v229 op_sel_hi:[0,0,0]
	v_mfma_scale_f32_16x16x128_f8f6f4 v[142:145], v[10:17], v[178:185], v[142:145], v229, v229 op_sel_hi:[0,0,0]
	v_mfma_scale_f32_16x16x128_f8f6f4 v[134:137], v[2:9], v[206:213], v[134:137], v229, v229 op_sel_hi:[0,0,0]
	v_mfma_scale_f32_16x16x128_f8f6f4 v[126:129], v[10:17], v[206:213], v[126:129], v229, v229 op_sel_hi:[0,0,0]
	v_mfma_scale_f32_16x16x128_f8f6f4 v[118:121], v[2:9], v[214:221], v[118:121], v229, v229 op_sel_hi:[0,0,0]
	v_mfma_scale_f32_16x16x128_f8f6f4 v[110:113], v[10:17], v[214:221], v[110:113], v229, v229 op_sel_hi:[0,0,0]
	s_setprio 0
	s_setprio 1
	v_mfma_scale_f32_16x16x128_f8f6f4 v[146:149], v[18:25], v[170:177], v[146:149], v229, v229 op_sel_hi:[0,0,0]
	v_mfma_scale_f32_16x16x128_f8f6f4 v[138:141], v[26:33], v[170:177], v[138:141], v229, v229 op_sel_hi:[0,0,0]
	v_mfma_scale_f32_16x16x128_f8f6f4 v[130:133], v[18:25], v[178:185], v[130:133], v229, v229 op_sel_hi:[0,0,0]
	v_mfma_scale_f32_16x16x128_f8f6f4 v[122:125], v[26:33], v[178:185], v[122:125], v229, v229 op_sel_hi:[0,0,0]
	v_mfma_scale_f32_16x16x128_f8f6f4 v[114:117], v[18:25], v[206:213], v[114:117], v229, v229 op_sel_hi:[0,0,0]
	v_mfma_scale_f32_16x16x128_f8f6f4 v[106:109], v[26:33], v[206:213], v[106:109], v229, v229 op_sel_hi:[0,0,0]
	v_mfma_scale_f32_16x16x128_f8f6f4 v[102:105], v[18:25], v[214:221], v[102:105], v229, v229 op_sel_hi:[0,0,0]
	v_mfma_scale_f32_16x16x128_f8f6f4 v[98:101], v[26:33], v[214:221], v[98:101], v229, v229 op_sel_hi:[0,0,0]
	s_barrier
	s_setprio 0
	s_add_i32 s22, s75, s25
	v_lshl_add_u64 v[162:163], v[162:163], 0, s[8:9]
	s_mov_b32 m0, s22
	ds_read_b128 v[170:173], v235 offset:49152
	ds_read_b128 v[174:177], v235 offset:50176
	ds_read_b128 v[178:181], v235 offset:51200
	ds_read_b128 v[182:185], v235 offset:52224
	ds_read_b128 v[206:209], v235 offset:53248
	ds_read_b128 v[210:213], v235 offset:54272
	ds_read_b128 v[214:217], v235 offset:55296
	ds_read_b128 v[218:221], v235 offset:56320
	global_load_lds_dwordx4 v[162:163], off
	s_add_i32 m0, s22, 0x2000
	s_add_u32 s20, s20, 0xb0080
	v_lshl_add_u64 v[162:163], v[164:165], 0, s[8:9]
	s_addc_u32 s21, s21, 0
	s_add_i32 s22, s76, s25
	global_load_lds_dwordx4 v[162:163], off
	s_mov_b32 m0, s22
	v_lshl_add_u64 v[162:163], s[20:21], 0, v[192:193]
	global_load_lds_dwordx4 v[162:163], off
	s_add_i32 m0, s22, 0x2000
	v_lshl_add_u64 v[162:163], s[20:21], 0, v[196:197]
	global_load_lds_dwordx4 v[162:163], off
	s_mov_b32 m0, s36
	v_lshl_add_u64 v[162:163], v[166:167], 0, s[8:9]
	global_load_lds_dwordx4 v[162:163], off
	s_mov_b32 m0, s37
	v_lshl_add_u64 v[162:163], v[168:169], 0, s[8:9]
	global_load_lds_dwordx4 v[162:163], off
	s_waitcnt vmcnt(8)
	s_waitcnt lgkmcnt(0)
	s_setprio 1
	s_barrier
	v_mfma_scale_f32_16x16x128_f8f6f4 v[94:97], v[2:9], v[170:177], v[94:97], v229, v229 op_sel_hi:[0,0,0]
	v_mfma_scale_f32_16x16x128_f8f6f4 v[90:93], v[10:17], v[170:177], v[90:93], v229, v229 op_sel_hi:[0,0,0]
	v_mfma_scale_f32_16x16x128_f8f6f4 v[86:89], v[2:9], v[178:185], v[86:89], v229, v229 op_sel_hi:[0,0,0]
	v_mfma_scale_f32_16x16x128_f8f6f4 v[78:81], v[10:17], v[178:185], v[78:81], v229, v229 op_sel_hi:[0,0,0]
	v_mfma_scale_f32_16x16x128_f8f6f4 v[70:73], v[2:9], v[206:213], v[70:73], v229, v229 op_sel_hi:[0,0,0]
	v_mfma_scale_f32_16x16x128_f8f6f4 v[62:65], v[10:17], v[206:213], v[62:65], v229, v229 op_sel_hi:[0,0,0]
	v_mfma_scale_f32_16x16x128_f8f6f4 v[54:57], v[2:9], v[214:221], v[54:57], v229, v229 op_sel_hi:[0,0,0]
	v_mfma_scale_f32_16x16x128_f8f6f4 v[46:49], v[10:17], v[214:221], v[46:49], v229, v229 op_sel_hi:[0,0,0]
	s_setprio 0
	s_setprio 1
	v_mfma_scale_f32_16x16x128_f8f6f4 v[82:85], v[18:25], v[170:177], v[82:85], v229, v229 op_sel_hi:[0,0,0]
	v_mfma_scale_f32_16x16x128_f8f6f4 v[74:77], v[26:33], v[170:177], v[74:77], v229, v229 op_sel_hi:[0,0,0]
	v_mfma_scale_f32_16x16x128_f8f6f4 v[66:69], v[18:25], v[178:185], v[66:69], v229, v229 op_sel_hi:[0,0,0]
	v_mfma_scale_f32_16x16x128_f8f6f4 v[58:61], v[26:33], v[178:185], v[58:61], v229, v229 op_sel_hi:[0,0,0]
	v_mfma_scale_f32_16x16x128_f8f6f4 v[50:53], v[18:25], v[206:213], v[50:53], v229, v229 op_sel_hi:[0,0,0]
	v_mfma_scale_f32_16x16x128_f8f6f4 v[42:45], v[26:33], v[206:213], v[42:45], v229, v229 op_sel_hi:[0,0,0]
	v_mfma_scale_f32_16x16x128_f8f6f4 v[38:41], v[18:25], v[214:221], v[38:41], v229, v229 op_sel_hi:[0,0,0]
	v_mfma_scale_f32_16x16x128_f8f6f4 v[34:37], v[26:33], v[214:221], v[34:37], v229, v229 op_sel_hi:[0,0,0]
	s_barrier
	s_setprio 0
	s_add_u32 s18, s18, 0x100
	s_addc_u32 s19, s19, 0
	s_add_u32 s72, s72, 0x100
	s_addc_u32 s73, s73, 0
	s_cmp_ge_u32 s74, s4
	s_mov_b32 s22, s74
	s_cbranch_scc0 .LBB0_1304
	s_nop 15
	s_nop 15
	s_nop 15
	s_nop 15
	s_nop 15
	s_and_b64 vcc, exec, s[10:11]
	s_cbranch_vccz .LBB0_1307
	s_barrier

; #define PG8_STAGE(bufoff, gbase, voff) do { _Pragma("unroll") for (int _i = 0; _i < 2; ++_i) \
;         __builtin_amdgcn_global_load_lds((const unsigned*)((const char*)(gbase) + (voff)[_i]), (PG8_LAS unsigned*)(lds + (bufoff) + ldsw + _i * 8192), 16, 0, 0); } while (0)
; #define PG8_WAIT_V(n) asm volatile("s_waitcnt vmcnt(" #n ")" ::: "memory")
; #define PG8_WAIT_L(n) asm volatile("s_waitcnt lgkmcnt(" #n ")" ::: "memory")
; #define PG8_BAR __builtin_amdgcn_s_barrier()
; #define PG8_SCHED __builtin_amdgcn_sched_barrier(0)
;     __device__ __forceinline__ int nt(const pg8::Unit& u) const { return u.kind == 0 ? ntiles : q_nt(u.kind - 1); }
; template <class Epi, class Sched, bool ALIGN_EPI = true, bool SP2 = true>
; __device__ __forceinline__ void gemm_phase(PG8_LAS unsigned char* lds, const int K  , const Sched& S, const Epi& E) {
;     ...
;         for (int t = 0; t < nt; t += 2) {
;             const bool last = (t == nt - 2);
;             const char* a1 = cA + (size_t)(t + 1) * kstep;
;             const char* a2 = last ? nA : cA + (size_t)(t + 2) * kstep; const char* b2 = last ? nB : cB + (size_t)(t + 2) * kstep;
;             const char* a3 = a2 + kstep; const char* b3 = b2 + kstep;
;             if constexpr (SP2) {
;             PG8_LDB(B0, 0, 0); PG8_LDB(B1, 0, 1); PG8_SCHED; PG8_LDA(At, 0, 0); PG8_STAGE(PG8_SA(1, 1), a1 + hstep, voffA);
;             PG8_WAIT_V(8); PG8_WAIT_L(0); PG8_BAR; PG8_MMA(0, 0, At, B0); PG8_MMA(0, 1, At, B1); PG8_BAR; PG8_SCHED;
;             PG8_LDA(At, 0, 1); PG8_STAGE(PG8_SB(0, 0), b2, voffB); PG8_STAGE(PG8_SB(0, 1), b2 + hstep, voffB); PG8_STAGE(PG8_SA(0, 0), a2, voffA);
.LBB0_1448:
	ds_read_b128 v[148:151], v154
	ds_read_b128 v[160:163], v154 offset:1024
	ds_read_b128 v[164:167], v154 offset:2048
	ds_read_b128 v[168:171], v154 offset:3072
	ds_read_b128 v[172:175], v155
	ds_read_b128 v[176:179], v155 offset:1024
	ds_read_b128 v[180:183], v155 offset:2048
	ds_read_b128 v[184:187], v155 offset:3072
	s_add_u32 s26, s24, 0xfff80080
	s_addc_u32 s27, s25, -1
	s_cmp_eq_u32 s50, 28
	s_cselect_b32 s29, s17, s27
	s_cselect_b32 s28, s46, s26
	s_cselect_b32 s27, s11, s49
	s_cselect_b32 s26, s47, s48
	v_lshl_add_u64 v[220:221], s[24:25], 0, v[140:141]
	s_add_i32 m0, s23, 0xc000
	ds_read_b128 v[188:191], v156
	ds_read_b128 v[192:195], v156 offset:1024
	ds_read_b128 v[196:199], v156 offset:2048
	ds_read_b128 v[200:203], v156 offset:3072
	ds_read_b128 v[204:207], v156 offset:4096
	ds_read_b128 v[208:211], v156 offset:5120
	ds_read_b128 v[212:215], v156 offset:6144
	ds_read_b128 v[216:219], v156 offset:7168
	global_load_lds_dwordx4 v[220:221], off
	s_add_i32 m0, s23, 0xe000
	v_lshl_add_u64 v[220:221], s[24:25], 0, v[142:143]
	global_load_lds_dwordx4 v[220:221], off
	s_waitcnt vmcnt(8)
	s_waitcnt lgkmcnt(0)
	s_setprio 1
	s_barrier
	v_mfma_f32_16x16x32_bf16 v[126:129], v[148:151], v[188:191], v[126:129]
	v_mfma_f32_16x16x32_bf16 v[118:121], v[164:167], v[188:191], v[118:121]
	v_mfma_f32_16x16x32_bf16 v[110:113], v[148:151], v[196:199], v[110:113]
	v_mfma_f32_16x16x32_bf16 v[102:105], v[164:167], v[196:199], v[102:105]
	v_mfma_f32_16x16x32_bf16 v[94:97], v[148:151], v[204:207], v[94:97]
	v_mfma_f32_16x16x32_bf16 v[86:89], v[164:167], v[204:207], v[86:89]
	v_mfma_f32_16x16x32_bf16 v[78:81], v[148:151], v[212:215], v[78:81]
	v_mfma_f32_16x16x32_bf16 v[70:73], v[164:167], v[212:215], v[70:73]
	v_mfma_f32_16x16x32_bf16 v[126:129], v[160:163], v[192:195], v[126:129]
	v_mfma_f32_16x16x32_bf16 v[118:121], v[168:171], v[192:195], v[118:121]
	v_mfma_f32_16x16x32_bf16 v[110:113], v[160:163], v[200:203], v[110:113]
	v_mfma_f32_16x16x32_bf16 v[102:105], v[168:171], v[200:203], v[102:105]
	v_mfma_f32_16x16x32_bf16 v[94:97], v[160:163], v[208:211], v[94:97]
	v_mfma_f32_16x16x32_bf16 v[86:89], v[168:171], v[208:211], v[86:89]
	v_mfma_f32_16x16x32_bf16 v[78:81], v[160:163], v[216:219], v[78:81]
	v_mfma_f32_16x16x32_bf16 v[70:73], v[168:171], v[216:219], v[70:73]
	s_setprio 0
	s_setprio 1
	v_mfma_f32_16x16x32_bf16 v[122:125], v[172:175], v[188:191], v[122:125]
	v_mfma_f32_16x16x32_bf16 v[114:117], v[180:183], v[188:191], v[114:117]
	v_mfma_f32_16x16x32_bf16 v[106:109], v[172:175], v[196:199], v[106:109]
	v_mfma_f32_16x16x32_bf16 v[98:101], v[180:183], v[196:199], v[98:101]
	v_mfma_f32_16x16x32_bf16 v[90:93], v[172:175], v[204:207], v[90:93]
	v_mfma_f32_16x16x32_bf16 v[82:85], v[180:183], v[204:207], v[82:85]
	v_mfma_f32_16x16x32_bf16 v[74:77], v[172:175], v[212:215], v[74:77]
	v_mfma_f32_16x16x32_bf16 v[66:69], v[180:183], v[212:215], v[66:69]
	v_mfma_f32_16x16x32_bf16 v[122:125], v[176:179], v[192:195], v[122:125]
	v_mfma_f32_16x16x32_bf16 v[114:117], v[184:187], v[192:195], v[114:117]
	v_mfma_f32_16x16x32_bf16 v[106:109], v[176:179], v[200:203], v[106:109]
	v_mfma_f32_16x16x32_bf16 v[98:101], v[184:187], v[200:203], v[98:101]
	v_mfma_f32_16x16x32_bf16 v[90:93], v[176:179], v[208:211], v[90:93]
	v_mfma_f32_16x16x32_bf16 v[82:85], v[184:187], v[208:211], v[82:85]
	v_mfma_f32_16x16x32_bf16 v[74:77], v[176:179], v[216:219], v[74:77]
	v_mfma_f32_16x16x32_bf16 v[66:69], v[184:187], v[216:219], v[66:69]
	s_barrier
	s_setprio 0
	s_add_i32 s51, s41, s31
	v_lshl_add_u64 v[220:221], s[26:27], 0, v[136:137]
	s_mov_b32 m0, s51
	ds_read_b128 v[188:191], v156 offset:16384
	ds_read_b128 v[192:195], v156 offset:17408
	ds_read_b128 v[196:199], v156 offset:18432
	ds_read_b128 v[200:203], v156 offset:19456
	ds_read_b128 v[204:207], v156 offset:20480
	ds_read_b128 v[208:211], v156 offset:21504
	ds_read_b128 v[212:215], v156 offset:22528
	ds_read_b128 v[216:219], v156 offset:23552
	global_load_lds_dwordx4 v[220:221], off
	s_add_i32 m0, s51, 0x2000
	s_add_u32 s68, s26, 0x80000
	v_lshl_add_u64 v[222:223], s[26:27], 0, v[132:133]
	s_addc_u32 s69, s27, 0
	s_add_i32 s51, s42, s31
	global_load_lds_dwordx4 v[222:223], off
	v_lshl_add_u64 v[224:225], s[68:69], 0, v[136:137]
	s_mov_b32 m0, s51
	v_lshl_add_u64 v[226:227], s[28:29], 0, v[134:135]
	global_load_lds_dwordx4 v[224:225], off
	s_add_i32 m0, s51, 0x2000
	v_lshl_add_u64 v[224:225], s[68:69], 0, v[132:133]
	global_load_lds_dwordx4 v[224:225], off
	s_mov_b32 m0, s23
	v_lshl_add_u64 v[224:225], s[28:29], 0, v[138:139]
	global_load_lds_dwordx4 v[224:225], off
	s_mov_b32 m0, s34
	s_nop 0
	global_load_lds_dwordx4 v[226:227], off
	s_waitcnt vmcnt(8)
	s_waitcnt lgkmcnt(0)
	s_setprio 1
	s_barrier
; #define PG8_STAGE(bufoff, gbase, voff) do { _Pragma("unroll") for (int _i = 0; _i < 2; ++_i) \
;         __builtin_amdgcn_global_load_lds((const unsigned*)((const char*)(gbase) + (voff)[_i]), (PG8_LAS unsigned*)(lds + (bufoff) + ldsw + _i * 8192), 16, 0, 0); } while (0)
; #define PG8_WAIT_V(n) asm volatile("s_waitcnt vmcnt(" #n ")" ::: "memory")
; #define PG8_WAIT_L(n) asm volatile("s_waitcnt lgkmcnt(" #n ")" ::: "memory")
; #define PG8_BAR __builtin_amdgcn_s_barrier()
; #define PG8_SCHED __builtin_amdgcn_sched_barrier(0)
; template <class Epi, class Sched, bool ALIGN_EPI = true, bool SP2 = true>
; __device__ __forceinline__ void gemm_phase(PG8_LAS unsigned char* lds, const int K  , const Sched& S, const Epi& E) {
;     ...
;             PG8_WAIT_V(8); PG8_WAIT_L(0); PG8_BAR; PG8_MMA(1, 0, At, B0); PG8_MMA(1, 1, At, B1); PG8_BAR; PG8_SCHED;
;             PG8_LDB(B0, 1, 0); PG8_LDB(B1, 1, 1); PG8_SCHED; PG8_LDA(At, 1, 0); PG8_STAGE(PG8_SA(0, 1), a2 + hstep, voffA);
;             PG8_WAIT_V(8); PG8_WAIT_L(0); PG8_BAR; PG8_MMA(0, 0, At, B0); PG8_MMA(0, 1, At, B1); PG8_BAR; PG8_SCHED;
	v_mfma_f32_16x16x32_bf16 v[62:65], v[148:151], v[188:191], v[62:65]
	v_mfma_f32_16x16x32_bf16 v[54:57], v[164:167], v[188:191], v[54:57]
	v_mfma_f32_16x16x32_bf16 v[46:49], v[148:151], v[196:199], v[46:49]
	v_mfma_f32_16x16x32_bf16 v[38:41], v[164:167], v[196:199], v[38:41]
	v_mfma_f32_16x16x32_bf16 v[30:33], v[148:151], v[204:207], v[30:33]
	v_mfma_f32_16x16x32_bf16 v[22:25], v[164:167], v[204:207], v[22:25]
	v_mfma_f32_16x16x32_bf16 v[14:17], v[148:151], v[212:215], v[14:17]
	v_mfma_f32_16x16x32_bf16 v[6:9], v[164:167], v[212:215], v[6:9]
	v_mfma_f32_16x16x32_bf16 v[62:65], v[160:163], v[192:195], v[62:65]
	v_mfma_f32_16x16x32_bf16 v[54:57], v[168:171], v[192:195], v[54:57]
	v_mfma_f32_16x16x32_bf16 v[46:49], v[160:163], v[200:203], v[46:49]
	v_mfma_f32_16x16x32_bf16 v[38:41], v[168:171], v[200:203], v[38:41]
	v_mfma_f32_16x16x32_bf16 v[30:33], v[160:163], v[208:211], v[30:33]
	v_mfma_f32_16x16x32_bf16 v[22:25], v[168:171], v[208:211], v[22:25]
	v_mfma_f32_16x16x32_bf16 v[14:17], v[160:163], v[216:219], v[14:17]
	v_mfma_f32_16x16x32_bf16 v[6:9], v[168:171], v[216:219], v[6:9]
	s_setprio 0
	s_setprio 1
	v_mfma_f32_16x16x32_bf16 v[58:61], v[172:175], v[188:191], v[58:61]
	v_mfma_f32_16x16x32_bf16 v[50:53], v[180:183], v[188:191], v[50:53]
	v_mfma_f32_16x16x32_bf16 v[42:45], v[172:175], v[196:199], v[42:45]
	v_mfma_f32_16x16x32_bf16 v[34:37], v[180:183], v[196:199], v[34:37]
	v_mfma_f32_16x16x32_bf16 v[26:29], v[172:175], v[204:207], v[26:29]
	v_mfma_f32_16x16x32_bf16 v[18:21], v[180:183], v[204:207], v[18:21]
	v_mfma_f32_16x16x32_bf16 v[10:13], v[172:175], v[212:215], v[10:13]
	v_mfma_f32_16x16x32_bf16 v[2:5], v[180:183], v[212:215], v[2:5]
	v_mfma_f32_16x16x32_bf16 v[58:61], v[176:179], v[192:195], v[58:61]
	v_mfma_f32_16x16x32_bf16 v[50:53], v[184:187], v[192:195], v[50:53]
	v_mfma_f32_16x16x32_bf16 v[42:45], v[176:179], v[200:203], v[42:45]
	v_mfma_f32_16x16x32_bf16 v[34:37], v[184:187], v[200:203], v[34:37]
	v_mfma_f32_16x16x32_bf16 v[26:29], v[176:179], v[208:211], v[26:29]
	v_mfma_f32_16x16x32_bf16 v[18:21], v[184:187], v[208:211], v[18:21]
	v_mfma_f32_16x16x32_bf16 v[10:13], v[176:179], v[216:219], v[10:13]
	v_mfma_f32_16x16x32_bf16 v[2:5], v[184:187], v[216:219], v[2:5]
	s_barrier
	s_setprio 0
	s_add_i32 s51, 0, 0x18000
	v_add_u32_e32 v159, s51, v152
	s_add_i32 s68, 0, 0x1c000
	ds_read_b128 v[148:151], v159
	ds_read_b128 v[160:163], v159 offset:1024
	ds_read_b128 v[164:167], v159 offset:2048
	ds_read_b128 v[168:171], v159 offset:3072
	v_add_u32_e32 v159, s68, v152
	ds_read_b128 v[172:175], v159
	ds_read_b128 v[176:179], v159 offset:1024
	ds_read_b128 v[180:183], v159 offset:2048
	ds_read_b128 v[184:187], v159 offset:3072
	s_add_u32 s28, s28, 0x80000
	s_addc_u32 s29, s29, 0
	s_mov_b32 m0, s35
	v_lshl_add_u64 v[230:231], s[28:29], 0, v[138:139]
	ds_read_b128 v[188:191], v156 offset:32768
	ds_read_b128 v[192:195], v156 offset:33792
	ds_read_b128 v[196:199], v156 offset:34816
	ds_read_b128 v[200:203], v156 offset:35840
	ds_read_b128 v[204:207], v156 offset:36864
	ds_read_b128 v[208:211], v156 offset:37888
	ds_read_b128 v[212:215], v156 offset:38912
	ds_read_b128 v[216:219], v156 offset:39936
	global_load_lds_dwordx4 v[230:231], off
	s_mov_b32 m0, s36
	v_lshl_add_u64 v[230:231], s[28:29], 0, v[134:135]
	global_load_lds_dwordx4 v[230:231], off
	s_waitcnt vmcnt(8)
	s_waitcnt lgkmcnt(0)
	s_setprio 1
	s_barrier
	v_mfma_f32_16x16x32_bf16 v[126:129], v[148:151], v[188:191], v[126:129]
	v_mfma_f32_16x16x32_bf16 v[118:121], v[164:167], v[188:191], v[118:121]
	v_mfma_f32_16x16x32_bf16 v[110:113], v[148:151], v[196:199], v[110:113]
	v_mfma_f32_16x16x32_bf16 v[102:105], v[164:167], v[196:199], v[102:105]
	v_mfma_f32_16x16x32_bf16 v[94:97], v[148:151], v[204:207], v[94:97]
	v_mfma_f32_16x16x32_bf16 v[86:89], v[164:167], v[204:207], v[86:89]
	v_mfma_f32_16x16x32_bf16 v[78:81], v[148:151], v[212:215], v[78:81]
	v_mfma_f32_16x16x32_bf16 v[70:73], v[164:167], v[212:215], v[70:73]
	v_mfma_f32_16x16x32_bf16 v[126:129], v[160:163], v[192:195], v[126:129]
	v_mfma_f32_16x16x32_bf16 v[118:121], v[168:171], v[192:195], v[118:121]
	v_mfma_f32_16x16x32_bf16 v[110:113], v[160:163], v[200:203], v[110:113]
	v_mfma_f32_16x16x32_bf16 v[102:105], v[168:171], v[200:203], v[102:105]
	v_mfma_f32_16x16x32_bf16 v[94:97], v[160:163], v[208:211], v[94:97]
	v_mfma_f32_16x16x32_bf16 v[86:89], v[168:171], v[208:211], v[86:89]
	v_mfma_f32_16x16x32_bf16 v[78:81], v[160:163], v[216:219], v[78:81]
	v_mfma_f32_16x16x32_bf16 v[70:73], v[168:171], v[216:219], v[70:73]
	s_setprio 0
	s_setprio 1
	v_mfma_f32_16x16x32_bf16 v[122:125], v[172:175], v[188:191], v[122:125]
	v_mfma_f32_16x16x32_bf16 v[114:117], v[180:183], v[188:191], v[114:117]
	v_mfma_f32_16x16x32_bf16 v[106:109], v[172:175], v[196:199], v[106:109]
	v_mfma_f32_16x16x32_bf16 v[98:101], v[180:183], v[196:199], v[98:101]
	v_mfma_f32_16x16x32_bf16 v[90:93], v[172:175], v[204:207], v[90:93]
	v_mfma_f32_16x16x32_bf16 v[82:85], v[180:183], v[204:207], v[82:85]
	v_mfma_f32_16x16x32_bf16 v[74:77], v[172:175], v[212:215], v[74:77]
	v_mfma_f32_16x16x32_bf16 v[66:69], v[180:183], v[212:215], v[66:69]
	v_mfma_f32_16x16x32_bf16 v[122:125], v[176:179], v[192:195], v[122:125]
	v_mfma_f32_16x16x32_bf16 v[114:117], v[184:187], v[192:195], v[114:117]
	v_mfma_f32_16x16x32_bf16 v[106:109], v[176:179], v[200:203], v[106:109]
	v_mfma_f32_16x16x32_bf16 v[98:101], v[184:187], v[200:203], v[98:101]
	v_mfma_f32_16x16x32_bf16 v[90:93], v[176:179], v[208:211], v[90:93]
	v_mfma_f32_16x16x32_bf16 v[82:85], v[184:187], v[208:211], v[82:85]
	v_mfma_f32_16x16x32_bf16 v[74:77], v[176:179], v[216:219], v[74:77]
	v_mfma_f32_16x16x32_bf16 v[66:69], v[184:187], v[216:219], v[66:69]
	s_barrier
; #define PG8_STAGE(bufoff, gbase, voff) do { _Pragma("unroll") for (int _i = 0; _i < 2; ++_i) \
;         __builtin_amdgcn_global_load_lds((const unsigned*)((const char*)(gbase) + (voff)[_i]), (PG8_LAS unsigned*)(lds + (bufoff) + ldsw + _i * 8192), 16, 0, 0); } while (0)
; #define PG8_WAIT_V(n) asm volatile("s_waitcnt vmcnt(" #n ")" ::: "memory")
; #define PG8_WAIT_L(n) asm volatile("s_waitcnt lgkmcnt(" #n ")" ::: "memory")
; #define PG8_BAR __builtin_amdgcn_s_barrier()
; #define PG8_SCHED __builtin_amdgcn_sched_barrier(0)
; template <class Epi, class Sched, bool ALIGN_EPI = true, bool SP2 = true>
; __device__ __forceinline__ void gemm_phase(PG8_LAS unsigned char* lds, const int K  , const Sched& S, const Epi& E) {
;     ...
;             PG8_LDA(At, 1, 1); PG8_STAGE(PG8_SB(1, 0), b3, voffB); PG8_STAGE(PG8_SB(1, 1), b3 + hstep, voffB); PG8_STAGE(PG8_SA(1, 0), a3, voffA);
;             PG8_WAIT_V(8); PG8_WAIT_L(0); PG8_BAR; PG8_MMA(1, 0, At, B0); PG8_MMA(1, 1, At, B1); PG8_BAR; PG8_SCHED;
;     ...
;         if constexpr (ALIGN_EPI) { if (wr == 0) PG8_BAR; }
	s_setprio 0
	s_add_i32 s28, s51, s31
	v_lshl_add_u64 v[220:221], v[220:221], 0, s[4:5]
	s_mov_b32 m0, s28
	ds_read_b128 v[188:191], v156 offset:49152
	ds_read_b128 v[192:195], v156 offset:50176
	ds_read_b128 v[196:199], v156 offset:51200
	ds_read_b128 v[200:203], v156 offset:52224
	ds_read_b128 v[204:207], v156 offset:53248
	ds_read_b128 v[208:211], v156 offset:54272
	ds_read_b128 v[212:215], v156 offset:55296
	ds_read_b128 v[216:219], v156 offset:56320
	global_load_lds_dwordx4 v[220:221], off
	s_add_i32 m0, s28, 0x2000
	s_add_u32 s26, s26, 0x80080
	v_lshl_add_u64 v[220:221], v[222:223], 0, s[4:5]
	s_addc_u32 s27, s27, 0
	s_add_i32 s28, s68, s31
	global_load_lds_dwordx4 v[220:221], off
	s_mov_b32 m0, s28
	v_lshl_add_u64 v[220:221], s[26:27], 0, v[136:137]
	global_load_lds_dwordx4 v[220:221], off
	s_add_i32 m0, s28, 0x2000
	v_lshl_add_u64 v[220:221], s[26:27], 0, v[132:133]
	global_load_lds_dwordx4 v[220:221], off
	s_mov_b32 m0, s38
	v_lshl_add_u64 v[220:221], v[224:225], 0, s[4:5]
	global_load_lds_dwordx4 v[220:221], off
	s_mov_b32 m0, s39
	v_lshl_add_u64 v[220:221], v[226:227], 0, s[4:5]
	global_load_lds_dwordx4 v[220:221], off
	s_waitcnt vmcnt(8)
	s_waitcnt lgkmcnt(0)
	s_setprio 1
	s_barrier
	v_mfma_f32_16x16x32_bf16 v[62:65], v[148:151], v[188:191], v[62:65]
	v_mfma_f32_16x16x32_bf16 v[54:57], v[164:167], v[188:191], v[54:57]
	v_mfma_f32_16x16x32_bf16 v[46:49], v[148:151], v[196:199], v[46:49]
	v_mfma_f32_16x16x32_bf16 v[38:41], v[164:167], v[196:199], v[38:41]
	v_mfma_f32_16x16x32_bf16 v[30:33], v[148:151], v[204:207], v[30:33]
	v_mfma_f32_16x16x32_bf16 v[22:25], v[164:167], v[204:207], v[22:25]
	v_mfma_f32_16x16x32_bf16 v[14:17], v[148:151], v[212:215], v[14:17]
	v_mfma_f32_16x16x32_bf16 v[6:9], v[164:167], v[212:215], v[6:9]
	v_mfma_f32_16x16x32_bf16 v[62:65], v[160:163], v[192:195], v[62:65]
	v_mfma_f32_16x16x32_bf16 v[54:57], v[168:171], v[192:195], v[54:57]
	v_mfma_f32_16x16x32_bf16 v[46:49], v[160:163], v[200:203], v[46:49]
	v_mfma_f32_16x16x32_bf16 v[38:41], v[168:171], v[200:203], v[38:41]
	v_mfma_f32_16x16x32_bf16 v[30:33], v[160:163], v[208:211], v[30:33]
	v_mfma_f32_16x16x32_bf16 v[22:25], v[168:171], v[208:211], v[22:25]
	v_mfma_f32_16x16x32_bf16 v[14:17], v[160:163], v[216:219], v[14:17]
	v_mfma_f32_16x16x32_bf16 v[6:9], v[168:171], v[216:219], v[6:9]
	s_setprio 0
	s_setprio 1
	v_mfma_f32_16x16x32_bf16 v[58:61], v[172:175], v[188:191], v[58:61]
	v_mfma_f32_16x16x32_bf16 v[50:53], v[180:183], v[188:191], v[50:53]
	v_mfma_f32_16x16x32_bf16 v[42:45], v[172:175], v[196:199], v[42:45]
	v_mfma_f32_16x16x32_bf16 v[34:37], v[180:183], v[196:199], v[34:37]
	v_mfma_f32_16x16x32_bf16 v[26:29], v[172:175], v[204:207], v[26:29]
	v_mfma_f32_16x16x32_bf16 v[18:21], v[180:183], v[204:207], v[18:21]
	v_mfma_f32_16x16x32_bf16 v[10:13], v[172:175], v[212:215], v[10:13]
	v_mfma_f32_16x16x32_bf16 v[2:5], v[180:183], v[212:215], v[2:5]
	v_mfma_f32_16x16x32_bf16 v[58:61], v[176:179], v[192:195], v[58:61]
	v_mfma_f32_16x16x32_bf16 v[50:53], v[184:187], v[192:195], v[50:53]
	v_mfma_f32_16x16x32_bf16 v[42:45], v[176:179], v[200:203], v[42:45]
	v_mfma_f32_16x16x32_bf16 v[34:37], v[184:187], v[200:203], v[34:37]
	v_mfma_f32_16x16x32_bf16 v[26:29], v[176:179], v[208:211], v[26:29]
	v_mfma_f32_16x16x32_bf16 v[18:21], v[184:187], v[208:211], v[18:21]
	v_mfma_f32_16x16x32_bf16 v[10:13], v[176:179], v[216:219], v[10:13]
	v_mfma_f32_16x16x32_bf16 v[2:5], v[184:187], v[216:219], v[2:5]
	s_barrier
	s_setprio 0
	s_add_i32 s50, s50, 2
	s_add_u32 s24, s24, 0x100
	s_addc_u32 s25, s25, 0
	s_add_u32 s48, s48, 0x100
	s_addc_u32 s49, s49, 0
	s_cmp_gt_u32 s50, 29
	s_cbranch_scc0 .LBB0_1448
	s_and_b64 vcc, exec, s[8:9]
	s_cbranch_vccz .LBB0_1451
	s_barrier

; #define PG8_STAGE(bufoff, gbase, voff) do { _Pragma("unroll") for (int _i = 0; _i < 2; ++_i) \
;         __builtin_amdgcn_global_load_lds((const unsigned*)((const char*)(gbase) + (voff)[_i]), (PG8_LAS unsigned*)(lds + (bufoff) + ldsw + _i * 8192), 16, 0, 0); } while (0)
; #define PG8_WAIT_V(n) asm volatile("s_waitcnt vmcnt(" #n ")" ::: "memory")
; #define PG8_WAIT_L(n) asm volatile("s_waitcnt lgkmcnt(" #n ")" ::: "memory")
; #define PG8_BAR __builtin_amdgcn_s_barrier()
; #define PG8_SCHED __builtin_amdgcn_sched_barrier(0)
;     __device__ __forceinline__ int nt(const pg8::Unit& u) const { return u.kind == 0 ? ntiles : q_nt(u.kind - 1); }
; template <class Epi, class Sched, bool ALIGN_EPI = true, bool SP2 = true>
; __device__ __forceinline__ void gemm_phase(PG8_LAS unsigned char* lds, const int K  , const Sched& S, const Epi& E) {
;     ...
;         for (int t = 0; t < nt; t += 2) {
;             const bool last = (t == nt - 2);
;             const char* a1 = cA + (size_t)(t + 1) * kstep;
;             const char* a2 = last ? nA : cA + (size_t)(t + 2) * kstep; const char* b2 = last ? nB : cB + (size_t)(t + 2) * kstep;
;             const char* a3 = a2 + kstep; const char* b3 = b2 + kstep;
;             if constexpr (SP2) {
;             PG8_LDB(B0, 0, 0); PG8_LDB(B1, 0, 1); PG8_SCHED; PG8_LDA(At, 0, 0); PG8_STAGE(PG8_SA(1, 1), a1 + hstep, voffA);
;             PG8_WAIT_V(8); PG8_WAIT_L(0); PG8_BAR; PG8_MMA(0, 0, At, B0); PG8_MMA(0, 1, At, B1); PG8_BAR; PG8_SCHED;
;             PG8_LDA(At, 0, 1); PG8_STAGE(PG8_SB(0, 0), b2, voffB); PG8_STAGE(PG8_SB(0, 1), b2 + hstep, voffB); PG8_STAGE(PG8_SA(0, 0), a2, voffA);
;             PG8_WAIT_V(8); PG8_WAIT_L(0); PG8_BAR; PG8_MMA(1, 0, At, B0); PG8_MMA(1, 1, At, B1); PG8_BAR; PG8_SCHED;
.LBB0_1695:
	ds_read_b128 v[18:21], v233
	ds_read_b128 v[22:25], v233 offset:1024
	ds_read_b128 v[26:29], v233 offset:2048
	ds_read_b128 v[30:33], v233 offset:3072
	ds_read_b128 v[2:5], v234
	ds_read_b128 v[6:9], v234 offset:1024
	ds_read_b128 v[10:13], v234 offset:2048
	ds_read_b128 v[14:17], v234 offset:3072
	s_add_i32 s74, s24, 2
	s_add_u32 s22, s20, 0xfff50080
	s_addc_u32 s23, s21, -1
	s_cmp_eq_u32 s71, s24
	s_cselect_b32 s24, s16, s22
	s_cselect_b32 s25, s17, s23
	s_cselect_b32 s23, s19, s73
	s_cselect_b32 s22, s18, s72
	v_lshl_add_u64 v[186:187], s[20:21], 0, v[198:199]
	s_add_i32 m0, s28, 0xc000
	ds_read_b128 v[162:165], v235
	ds_read_b128 v[166:169], v235 offset:1024
	ds_read_b128 v[170:173], v235 offset:2048
	ds_read_b128 v[174:177], v235 offset:3072
	ds_read_b128 v[178:181], v235 offset:4096
	ds_read_b128 v[182:185], v235 offset:5120
	ds_read_b128 v[206:209], v235 offset:6144
	ds_read_b128 v[210:213], v235 offset:7168
	global_load_lds_dwordx4 v[186:187], off
	s_add_i32 m0, s28, 0xe000
	v_lshl_add_u64 v[186:187], s[20:21], 0, v[200:201]
	global_load_lds_dwordx4 v[186:187], off
	s_waitcnt vmcnt(8)
	s_waitcnt lgkmcnt(0)
	s_setprio 1
	s_barrier
	v_mfma_scale_f32_16x16x128_f8f6f4 v[158:161], v[18:25], v[162:169], v[158:161], v229, v229 op_sel_hi:[0,0,0]
	v_mfma_scale_f32_16x16x128_f8f6f4 v[154:157], v[26:33], v[162:169], v[154:157], v229, v229 op_sel_hi:[0,0,0]
	v_mfma_scale_f32_16x16x128_f8f6f4 v[150:153], v[18:25], v[170:177], v[150:153], v229, v229 op_sel_hi:[0,0,0]
	v_mfma_scale_f32_16x16x128_f8f6f4 v[142:145], v[26:33], v[170:177], v[142:145], v229, v229 op_sel_hi:[0,0,0]
	v_mfma_scale_f32_16x16x128_f8f6f4 v[134:137], v[18:25], v[178:185], v[134:137], v229, v229 op_sel_hi:[0,0,0]
	v_mfma_scale_f32_16x16x128_f8f6f4 v[126:129], v[26:33], v[178:185], v[126:129], v229, v229 op_sel_hi:[0,0,0]
	v_mfma_scale_f32_16x16x128_f8f6f4 v[118:121], v[18:25], v[206:213], v[118:121], v229, v229 op_sel_hi:[0,0,0]
	v_mfma_scale_f32_16x16x128_f8f6f4 v[110:113], v[26:33], v[206:213], v[110:113], v229, v229 op_sel_hi:[0,0,0]
	s_setprio 0
	s_setprio 1
	v_mfma_scale_f32_16x16x128_f8f6f4 v[146:149], v[2:9], v[162:169], v[146:149], v229, v229 op_sel_hi:[0,0,0]
	v_mfma_scale_f32_16x16x128_f8f6f4 v[138:141], v[10:17], v[162:169], v[138:141], v229, v229 op_sel_hi:[0,0,0]
	v_mfma_scale_f32_16x16x128_f8f6f4 v[130:133], v[2:9], v[170:177], v[130:133], v229, v229 op_sel_hi:[0,0,0]
	v_mfma_scale_f32_16x16x128_f8f6f4 v[122:125], v[10:17], v[170:177], v[122:125], v229, v229 op_sel_hi:[0,0,0]
	v_mfma_scale_f32_16x16x128_f8f6f4 v[114:117], v[2:9], v[178:185], v[114:117], v229, v229 op_sel_hi:[0,0,0]
	v_mfma_scale_f32_16x16x128_f8f6f4 v[106:109], v[10:17], v[178:185], v[106:109], v229, v229 op_sel_hi:[0,0,0]
	v_mfma_scale_f32_16x16x128_f8f6f4 v[102:105], v[2:9], v[206:213], v[102:105], v229, v229 op_sel_hi:[0,0,0]
	v_mfma_scale_f32_16x16x128_f8f6f4 v[98:101], v[10:17], v[206:213], v[98:101], v229, v229 op_sel_hi:[0,0,0]
	s_barrier
	s_setprio 0
	s_add_i32 s75, s40, s27
	v_lshl_add_u64 v[162:163], s[22:23], 0, v[192:193]
	s_mov_b32 m0, s75
	ds_read_b128 v[170:173], v235 offset:16384
	ds_read_b128 v[174:177], v235 offset:17408
	ds_read_b128 v[178:181], v235 offset:18432
	ds_read_b128 v[182:185], v235 offset:19456
	ds_read_b128 v[206:209], v235 offset:20480
	ds_read_b128 v[210:213], v235 offset:21504
	ds_read_b128 v[214:217], v235 offset:22528
	ds_read_b128 v[218:221], v235 offset:23552
	global_load_lds_dwordx4 v[162:163], off
	s_add_i32 m0, s75, 0x2000
	s_add_u32 s78, s22, 0xb0000
	v_lshl_add_u64 v[164:165], s[22:23], 0, v[196:197]
	s_addc_u32 s79, s23, 0
	s_add_i32 s75, s41, s27
	global_load_lds_dwordx4 v[164:165], off
	v_lshl_add_u64 v[166:167], s[78:79], 0, v[192:193]
	s_mov_b32 m0, s75
	v_lshl_add_u64 v[168:169], s[24:25], 0, v[194:195]
	global_load_lds_dwordx4 v[166:167], off
	s_add_i32 m0, s75, 0x2000
	v_lshl_add_u64 v[166:167], s[78:79], 0, v[196:197]
	global_load_lds_dwordx4 v[166:167], off
	s_mov_b32 m0, s28
	v_lshl_add_u64 v[166:167], s[24:25], 0, v[190:191]
	global_load_lds_dwordx4 v[166:167], off
	s_mov_b32 m0, s29
	s_nop 0
	global_load_lds_dwordx4 v[168:169], off
	s_waitcnt vmcnt(8)
	s_waitcnt lgkmcnt(0)
	s_setprio 1
	s_barrier
	v_mfma_scale_f32_16x16x128_f8f6f4 v[94:97], v[18:25], v[170:177], v[94:97], v229, v229 op_sel_hi:[0,0,0]
	v_mfma_scale_f32_16x16x128_f8f6f4 v[90:93], v[26:33], v[170:177], v[90:93], v229, v229 op_sel_hi:[0,0,0]
	v_mfma_scale_f32_16x16x128_f8f6f4 v[86:89], v[18:25], v[178:185], v[86:89], v229, v229 op_sel_hi:[0,0,0]
	v_mfma_scale_f32_16x16x128_f8f6f4 v[78:81], v[26:33], v[178:185], v[78:81], v229, v229 op_sel_hi:[0,0,0]
	v_mfma_scale_f32_16x16x128_f8f6f4 v[70:73], v[18:25], v[206:213], v[70:73], v229, v229 op_sel_hi:[0,0,0]
	v_mfma_scale_f32_16x16x128_f8f6f4 v[62:65], v[26:33], v[206:213], v[62:65], v229, v229 op_sel_hi:[0,0,0]
	v_mfma_scale_f32_16x16x128_f8f6f4 v[54:57], v[18:25], v[214:221], v[54:57], v229, v229 op_sel_hi:[0,0,0]
	v_mfma_scale_f32_16x16x128_f8f6f4 v[46:49], v[26:33], v[214:221], v[46:49], v229, v229 op_sel_hi:[0,0,0]
	s_setprio 0
	s_setprio 1
	v_mfma_scale_f32_16x16x128_f8f6f4 v[82:85], v[2:9], v[170:177], v[82:85], v229, v229 op_sel_hi:[0,0,0]
	v_mfma_scale_f32_16x16x128_f8f6f4 v[74:77], v[10:17], v[170:177], v[74:77], v229, v229 op_sel_hi:[0,0,0]
	v_mfma_scale_f32_16x16x128_f8f6f4 v[66:69], v[2:9], v[178:185], v[66:69], v229, v229 op_sel_hi:[0,0,0]
	v_mfma_scale_f32_16x16x128_f8f6f4 v[58:61], v[10:17], v[178:185], v[58:61], v229, v229 op_sel_hi:[0,0,0]
	v_mfma_scale_f32_16x16x128_f8f6f4 v[50:53], v[2:9], v[206:213], v[50:53], v229, v229 op_sel_hi:[0,0,0]
	v_mfma_scale_f32_16x16x128_f8f6f4 v[42:45], v[10:17], v[206:213], v[42:45], v229, v229 op_sel_hi:[0,0,0]
	v_mfma_scale_f32_16x16x128_f8f6f4 v[38:41], v[2:9], v[214:221], v[38:41], v229, v229 op_sel_hi:[0,0,0]
	v_mfma_scale_f32_16x16x128_f8f6f4 v[34:37], v[10:17], v[214:221], v[34:37], v229, v229 op_sel_hi:[0,0,0]
	s_barrier
; #define PG8_STAGE(bufoff, gbase, voff) do { _Pragma("unroll") for (int _i = 0; _i < 2; ++_i) \
;         __builtin_amdgcn_global_load_lds((const unsigned*)((const char*)(gbase) + (voff)[_i]), (PG8_LAS unsigned*)(lds + (bufoff) + ldsw + _i * 8192), 16, 0, 0); } while (0)
; #define PG8_WAIT_V(n) asm volatile("s_waitcnt vmcnt(" #n ")" ::: "memory")
; #define PG8_WAIT_L(n) asm volatile("s_waitcnt lgkmcnt(" #n ")" ::: "memory")
; #define PG8_BAR __builtin_amdgcn_s_barrier()
; #define PG8_SCHED __builtin_amdgcn_sched_barrier(0)
; template <class Epi, class Sched, bool ALIGN_EPI = true, bool SP2 = true>
; __device__ __forceinline__ void gemm_phase(PG8_LAS unsigned char* lds, const int K  , const Sched& S, const Epi& E) {
;     ...
;             PG8_LDB(B0, 1, 0); PG8_LDB(B1, 1, 1); PG8_SCHED; PG8_LDA(At, 1, 0); PG8_STAGE(PG8_SA(0, 1), a2 + hstep, voffA);
;             PG8_WAIT_V(8); PG8_WAIT_L(0); PG8_BAR; PG8_MMA(0, 0, At, B0); PG8_MMA(0, 1, At, B1); PG8_BAR; PG8_SCHED;
;             PG8_LDA(At, 1, 1); PG8_STAGE(PG8_SB(1, 0), b3, voffB); PG8_STAGE(PG8_SB(1, 1), b3 + hstep, voffB); PG8_STAGE(PG8_SA(1, 0), a3, voffA);
;             PG8_WAIT_V(8); PG8_WAIT_L(0); PG8_BAR; PG8_MMA(1, 0, At, B0); PG8_MMA(1, 1, At, B1); PG8_BAR; PG8_SCHED;
;     ...
;         if constexpr (Epi::FP8) asm volatile("s_nop 15\n\ts_nop 15\n\ts_nop 15\n\ts_nop 15\n\ts_nop 15" ::: "memory");
;         if constexpr (ALIGN_EPI) { if (wr == 0) PG8_BAR; }
	s_setprio 0
	s_add_i32 s75, 0, 0x18000
	s_add_i32 s78, 0, 0x1c000
	v_add_u32_e32 v14, s75, v231
	v_add_u32_e32 v30, s78, v231
	ds_read_b128 v[2:5], v14
	ds_read_b128 v[6:9], v14 offset:1024
	ds_read_b128 v[10:13], v14 offset:2048
	ds_read_b128 v[14:17], v14 offset:3072
	ds_read_b128 v[18:21], v30
	ds_read_b128 v[22:25], v30 offset:1024
	ds_read_b128 v[26:29], v30 offset:2048
	ds_read_b128 v[30:33], v30 offset:3072
	s_add_u32 s24, s24, 0xb0000
	s_addc_u32 s25, s25, 0
	s_mov_b32 m0, s30
	v_lshl_add_u64 v[186:187], s[24:25], 0, v[190:191]
	ds_read_b128 v[170:173], v235 offset:32768
	ds_read_b128 v[174:177], v235 offset:33792
	ds_read_b128 v[178:181], v235 offset:34816
	ds_read_b128 v[182:185], v235 offset:35840
	ds_read_b128 v[206:209], v235 offset:36864
	ds_read_b128 v[210:213], v235 offset:37888
	ds_read_b128 v[214:217], v235 offset:38912
	ds_read_b128 v[218:221], v235 offset:39936
	global_load_lds_dwordx4 v[186:187], off
	s_mov_b32 m0, s31
	v_lshl_add_u64 v[186:187], s[24:25], 0, v[194:195]
	global_load_lds_dwordx4 v[186:187], off
	s_waitcnt vmcnt(8)
	s_waitcnt lgkmcnt(0)
	s_setprio 1
	s_barrier
	v_mfma_scale_f32_16x16x128_f8f6f4 v[158:161], v[2:9], v[170:177], v[158:161], v229, v229 op_sel_hi:[0,0,0]
	v_mfma_scale_f32_16x16x128_f8f6f4 v[154:157], v[10:17], v[170:177], v[154:157], v229, v229 op_sel_hi:[0,0,0]
	v_mfma_scale_f32_16x16x128_f8f6f4 v[150:153], v[2:9], v[178:185], v[150:153], v229, v229 op_sel_hi:[0,0,0]
	v_mfma_scale_f32_16x16x128_f8f6f4 v[142:145], v[10:17], v[178:185], v[142:145], v229, v229 op_sel_hi:[0,0,0]
	v_mfma_scale_f32_16x16x128_f8f6f4 v[134:137], v[2:9], v[206:213], v[134:137], v229, v229 op_sel_hi:[0,0,0]
	v_mfma_scale_f32_16x16x128_f8f6f4 v[126:129], v[10:17], v[206:213], v[126:129], v229, v229 op_sel_hi:[0,0,0]
	v_mfma_scale_f32_16x16x128_f8f6f4 v[118:121], v[2:9], v[214:221], v[118:121], v229, v229 op_sel_hi:[0,0,0]
	v_mfma_scale_f32_16x16x128_f8f6f4 v[110:113], v[10:17], v[214:221], v[110:113], v229, v229 op_sel_hi:[0,0,0]
	s_setprio 0
	s_setprio 1
	v_mfma_scale_f32_16x16x128_f8f6f4 v[146:149], v[18:25], v[170:177], v[146:149], v229, v229 op_sel_hi:[0,0,0]
	v_mfma_scale_f32_16x16x128_f8f6f4 v[138:141], v[26:33], v[170:177], v[138:141], v229, v229 op_sel_hi:[0,0,0]
	v_mfma_scale_f32_16x16x128_f8f6f4 v[130:133], v[18:25], v[178:185], v[130:133], v229, v229 op_sel_hi:[0,0,0]
	v_mfma_scale_f32_16x16x128_f8f6f4 v[122:125], v[26:33], v[178:185], v[122:125], v229, v229 op_sel_hi:[0,0,0]
	v_mfma_scale_f32_16x16x128_f8f6f4 v[114:117], v[18:25], v[206:213], v[114:117], v229, v229 op_sel_hi:[0,0,0]
	v_mfma_scale_f32_16x16x128_f8f6f4 v[106:109], v[26:33], v[206:213], v[106:109], v229, v229 op_sel_hi:[0,0,0]
	v_mfma_scale_f32_16x16x128_f8f6f4 v[102:105], v[18:25], v[214:221], v[102:105], v229, v229 op_sel_hi:[0,0,0]
	v_mfma_scale_f32_16x16x128_f8f6f4 v[98:101], v[26:33], v[214:221], v[98:101], v229, v229 op_sel_hi:[0,0,0]
	s_barrier
	s_setprio 0
	s_add_i32 s24, s75, s27
	v_lshl_add_u64 v[162:163], v[162:163], 0, s[10:11]
	s_mov_b32 m0, s24
	ds_read_b128 v[170:173], v235 offset:49152
	ds_read_b128 v[174:177], v235 offset:50176
	ds_read_b128 v[178:181], v235 offset:51200
	ds_read_b128 v[182:185], v235 offset:52224
	ds_read_b128 v[206:209], v235 offset:53248
	ds_read_b128 v[210:213], v235 offset:54272
	ds_read_b128 v[214:217], v235 offset:55296
	ds_read_b128 v[218:221], v235 offset:56320
	global_load_lds_dwordx4 v[162:163], off
	s_add_i32 m0, s24, 0x2000
	s_add_u32 s22, s22, 0xb0080
	v_lshl_add_u64 v[162:163], v[164:165], 0, s[10:11]
	s_addc_u32 s23, s23, 0
	s_add_i32 s24, s78, s27
	global_load_lds_dwordx4 v[162:163], off
	s_mov_b32 m0, s24
	v_lshl_add_u64 v[162:163], s[22:23], 0, v[192:193]
	global_load_lds_dwordx4 v[162:163], off
	s_add_i32 m0, s24, 0x2000
	v_lshl_add_u64 v[162:163], s[22:23], 0, v[196:197]
	global_load_lds_dwordx4 v[162:163], off
	s_mov_b32 m0, s36
	v_lshl_add_u64 v[162:163], v[166:167], 0, s[10:11]
	global_load_lds_dwordx4 v[162:163], off
	s_mov_b32 m0, s37
	v_lshl_add_u64 v[162:163], v[168:169], 0, s[10:11]
	global_load_lds_dwordx4 v[162:163], off
	s_waitcnt vmcnt(8)
	s_waitcnt lgkmcnt(0)
	s_setprio 1
	s_barrier
	v_mfma_scale_f32_16x16x128_f8f6f4 v[94:97], v[2:9], v[170:177], v[94:97], v229, v229 op_sel_hi:[0,0,0]
	v_mfma_scale_f32_16x16x128_f8f6f4 v[90:93], v[10:17], v[170:177], v[90:93], v229, v229 op_sel_hi:[0,0,0]
	v_mfma_scale_f32_16x16x128_f8f6f4 v[86:89], v[2:9], v[178:185], v[86:89], v229, v229 op_sel_hi:[0,0,0]
	v_mfma_scale_f32_16x16x128_f8f6f4 v[78:81], v[10:17], v[178:185], v[78:81], v229, v229 op_sel_hi:[0,0,0]
	v_mfma_scale_f32_16x16x128_f8f6f4 v[70:73], v[2:9], v[206:213], v[70:73], v229, v229 op_sel_hi:[0,0,0]
	v_mfma_scale_f32_16x16x128_f8f6f4 v[62:65], v[10:17], v[206:213], v[62:65], v229, v229 op_sel_hi:[0,0,0]
	v_mfma_scale_f32_16x16x128_f8f6f4 v[54:57], v[2:9], v[214:221], v[54:57], v229, v229 op_sel_hi:[0,0,0]
	v_mfma_scale_f32_16x16x128_f8f6f4 v[46:49], v[10:17], v[214:221], v[46:49], v229, v229 op_sel_hi:[0,0,0]
	s_setprio 0
	s_setprio 1
	v_mfma_scale_f32_16x16x128_f8f6f4 v[82:85], v[18:25], v[170:177], v[82:85], v229, v229 op_sel_hi:[0,0,0]
	v_mfma_scale_f32_16x16x128_f8f6f4 v[74:77], v[26:33], v[170:177], v[74:77], v229, v229 op_sel_hi:[0,0,0]
	v_mfma_scale_f32_16x16x128_f8f6f4 v[66:69], v[18:25], v[178:185], v[66:69], v229, v229 op_sel_hi:[0,0,0]
	v_mfma_scale_f32_16x16x128_f8f6f4 v[58:61], v[26:33], v[178:185], v[58:61], v229, v229 op_sel_hi:[0,0,0]
	v_mfma_scale_f32_16x16x128_f8f6f4 v[50:53], v[18:25], v[206:213], v[50:53], v229, v229 op_sel_hi:[0,0,0]
	v_mfma_scale_f32_16x16x128_f8f6f4 v[42:45], v[26:33], v[206:213], v[42:45], v229, v229 op_sel_hi:[0,0,0]
	v_mfma_scale_f32_16x16x128_f8f6f4 v[38:41], v[18:25], v[214:221], v[38:41], v229, v229 op_sel_hi:[0,0,0]
	v_mfma_scale_f32_16x16x128_f8f6f4 v[34:37], v[26:33], v[214:221], v[34:37], v229, v229 op_sel_hi:[0,0,0]
	s_barrier
	s_setprio 0
	s_add_u32 s20, s20, 0x100
	s_addc_u32 s21, s21, 0
	s_add_u32 s72, s72, 0x100
	s_addc_u32 s73, s73, 0
	s_cmp_ge_u32 s74, s4
	s_mov_b32 s24, s74
	s_cbranch_scc0 .LBB0_1695
	s_nop 15
	s_nop 15
	s_nop 15
	s_nop 15
	s_nop 15
	s_and_b64 vcc, exec, s[12:13]
	s_cbranch_vccz .LBB0_1698
	s_barrier

; #define PG8_STAGE(bufoff, gbase, voff) do { _Pragma("unroll") for (int _i = 0; _i < 2; ++_i) \
;         __builtin_amdgcn_global_load_lds((const unsigned*)((const char*)(gbase) + (voff)[_i]), (PG8_LAS unsigned*)(lds + (bufoff) + ldsw + _i * 8192), 16, 0, 0); } while (0)
; #define PG8_WAIT_V(n) asm volatile("s_waitcnt vmcnt(" #n ")" ::: "memory")
; #define PG8_WAIT_L(n) asm volatile("s_waitcnt lgkmcnt(" #n ")" ::: "memory")
; #define PG8_BAR __builtin_amdgcn_s_barrier()
; #define PG8_SCHED __builtin_amdgcn_sched_barrier(0)
;     __device__ __forceinline__ int nt(const pg8::Unit& u) const { return u.kind == 0 ? ntiles : q_nt(u.kind - 1); }
; template <class Epi, class Sched, bool ALIGN_EPI = true, bool SP2 = true>
; __device__ __forceinline__ void gemm_phase(PG8_LAS unsigned char* lds, const int K  , const Sched& S, const Epi& E) {
;     ...
;         for (int t = 0; t < nt; t += 2) {
;             const bool last = (t == nt - 2);
;             const char* a1 = cA + (size_t)(t + 1) * kstep;
;             const char* a2 = last ? nA : cA + (size_t)(t + 2) * kstep; const char* b2 = last ? nB : cB + (size_t)(t + 2) * kstep;
;             const char* a3 = a2 + kstep; const char* b3 = b2 + kstep;
;             if constexpr (SP2) {
;             PG8_LDB(B0, 0, 0); PG8_LDB(B1, 0, 1); PG8_SCHED; PG8_LDA(At, 0, 0); PG8_STAGE(PG8_SA(1, 1), a1 + hstep, voffA);
;             PG8_WAIT_V(8); PG8_WAIT_L(0); PG8_BAR; PG8_MMA(0, 0, At, B0); PG8_MMA(0, 1, At, B1); PG8_BAR; PG8_SCHED;
;             PG8_LDA(At, 0, 1); PG8_STAGE(PG8_SB(0, 0), b2, voffB); PG8_STAGE(PG8_SB(0, 1), b2 + hstep, voffB); PG8_STAGE(PG8_SA(0, 0), a2, voffA);
.LBB0_1847:
	ds_read_b128 v[130:133], v176
	ds_read_b128 v[134:137], v176 offset:1024
	ds_read_b128 v[138:141], v176 offset:2048
	ds_read_b128 v[142:145], v176 offset:3072
	ds_read_b128 v[168:171], v177
	ds_read_b128 v[184:187], v177 offset:1024
	ds_read_b128 v[188:191], v177 offset:2048
	ds_read_b128 v[192:195], v177 offset:3072
	s_add_u32 s22, s0, 0xfff80080
	s_addc_u32 s23, s1, -1
	s_cmp_eq_u32 s51, 28
	s_cselect_b32 s25, s7, s23
	s_cselect_b32 s24, s47, s22
	s_cselect_b32 s23, s11, s50
	s_cselect_b32 s22, s48, s49
	v_lshl_add_u64 v[230:231], s[0:1], 0, v[160:161]
	s_add_i32 m0, s27, 0xc000
	ds_read_b128 v[196:199], v178
	ds_read_b128 v[200:203], v178 offset:1024
	ds_read_b128 v[204:207], v178 offset:2048
	ds_read_b128 v[208:211], v178 offset:3072
	ds_read_b128 v[212:215], v178 offset:4096
	ds_read_b128 v[216:219], v178 offset:5120
	ds_read_b128 v[220:223], v178 offset:6144
	ds_read_b128 v[224:227], v178 offset:7168
	global_load_lds_dwordx4 v[230:231], off
	s_add_i32 m0, s27, 0xe000
	v_lshl_add_u64 v[230:231], s[0:1], 0, v[162:163]
	global_load_lds_dwordx4 v[230:231], off
	s_waitcnt vmcnt(8)
	s_waitcnt lgkmcnt(0)
	s_setprio 1
	s_barrier
	v_mfma_f32_16x16x32_bf16 v[126:129], v[130:133], v[196:199], v[126:129]
	v_mfma_f32_16x16x32_bf16 v[122:125], v[138:141], v[196:199], v[122:125]
	v_mfma_f32_16x16x32_bf16 v[110:113], v[130:133], v[204:207], v[110:113]
	v_mfma_f32_16x16x32_bf16 v[106:109], v[138:141], v[204:207], v[106:109]
	v_mfma_f32_16x16x32_bf16 v[94:97], v[130:133], v[212:215], v[94:97]
	v_mfma_f32_16x16x32_bf16 v[90:93], v[138:141], v[212:215], v[90:93]
	v_mfma_f32_16x16x32_bf16 v[78:81], v[130:133], v[220:223], v[78:81]
	v_mfma_f32_16x16x32_bf16 v[74:77], v[138:141], v[220:223], v[74:77]
	v_mfma_f32_16x16x32_bf16 v[126:129], v[134:137], v[200:203], v[126:129]
	v_mfma_f32_16x16x32_bf16 v[122:125], v[142:145], v[200:203], v[122:125]
	v_mfma_f32_16x16x32_bf16 v[110:113], v[134:137], v[208:211], v[110:113]
	v_mfma_f32_16x16x32_bf16 v[106:109], v[142:145], v[208:211], v[106:109]
	v_mfma_f32_16x16x32_bf16 v[94:97], v[134:137], v[216:219], v[94:97]
	v_mfma_f32_16x16x32_bf16 v[90:93], v[142:145], v[216:219], v[90:93]
	v_mfma_f32_16x16x32_bf16 v[78:81], v[134:137], v[224:227], v[78:81]
	v_mfma_f32_16x16x32_bf16 v[74:77], v[142:145], v[224:227], v[74:77]
	s_setprio 0
	s_setprio 1
	v_mfma_f32_16x16x32_bf16 v[118:121], v[168:171], v[196:199], v[118:121]
	v_mfma_f32_16x16x32_bf16 v[114:117], v[188:191], v[196:199], v[114:117]
	v_mfma_f32_16x16x32_bf16 v[102:105], v[168:171], v[204:207], v[102:105]
	v_mfma_f32_16x16x32_bf16 v[98:101], v[188:191], v[204:207], v[98:101]
	v_mfma_f32_16x16x32_bf16 v[86:89], v[168:171], v[212:215], v[86:89]
	v_mfma_f32_16x16x32_bf16 v[82:85], v[188:191], v[212:215], v[82:85]
	v_mfma_f32_16x16x32_bf16 v[70:73], v[168:171], v[220:223], v[70:73]
	v_mfma_f32_16x16x32_bf16 v[66:69], v[188:191], v[220:223], v[66:69]
	v_mfma_f32_16x16x32_bf16 v[118:121], v[184:187], v[200:203], v[118:121]
	v_mfma_f32_16x16x32_bf16 v[114:117], v[192:195], v[200:203], v[114:117]
	v_mfma_f32_16x16x32_bf16 v[102:105], v[184:187], v[208:211], v[102:105]
	v_mfma_f32_16x16x32_bf16 v[98:101], v[192:195], v[208:211], v[98:101]
	v_mfma_f32_16x16x32_bf16 v[86:89], v[184:187], v[216:219], v[86:89]
	v_mfma_f32_16x16x32_bf16 v[82:85], v[192:195], v[216:219], v[82:85]
	v_mfma_f32_16x16x32_bf16 v[70:73], v[184:187], v[224:227], v[70:73]
	v_mfma_f32_16x16x32_bf16 v[66:69], v[192:195], v[224:227], v[66:69]
	s_barrier
	s_setprio 0
	s_add_i32 s68, s39, s26
	v_lshl_add_u64 v[230:231], s[22:23], 0, v[150:151]
	s_mov_b32 m0, s68
	ds_read_b128 v[196:199], v178 offset:16384
	ds_read_b128 v[200:203], v178 offset:17408
	ds_read_b128 v[204:207], v178 offset:18432
	ds_read_b128 v[208:211], v178 offset:19456
	ds_read_b128 v[212:215], v178 offset:20480
	ds_read_b128 v[216:219], v178 offset:21504
	ds_read_b128 v[220:223], v178 offset:22528
	ds_read_b128 v[224:227], v178 offset:23552
	global_load_lds_dwordx4 v[230:231], off
	s_add_i32 m0, s68, 0x2000
	s_add_u32 s68, s22, 0x80000
	v_lshl_add_u64 v[232:233], s[22:23], 0, v[154:155]
	s_addc_u32 s69, s23, 0
	s_add_i32 s70, s40, s26
	global_load_lds_dwordx4 v[232:233], off
	v_lshl_add_u64 v[234:235], s[68:69], 0, v[150:151]
	s_mov_b32 m0, s70
	v_lshl_add_u64 v[236:237], s[24:25], 0, v[152:153]
	global_load_lds_dwordx4 v[234:235], off
	s_add_i32 m0, s70, 0x2000
	v_lshl_add_u64 v[234:235], s[68:69], 0, v[154:155]
	global_load_lds_dwordx4 v[234:235], off
	s_mov_b32 m0, s27
	v_lshl_add_u64 v[234:235], s[24:25], 0, v[148:149]
	global_load_lds_dwordx4 v[234:235], off
	s_mov_b32 m0, s28
	s_nop 0
	global_load_lds_dwordx4 v[236:237], off
	s_waitcnt vmcnt(8)
	s_waitcnt lgkmcnt(0)
	s_setprio 1
	s_barrier
; #define PG8_STAGE(bufoff, gbase, voff) do { _Pragma("unroll") for (int _i = 0; _i < 2; ++_i) \
;         __builtin_amdgcn_global_load_lds((const unsigned*)((const char*)(gbase) + (voff)[_i]), (PG8_LAS unsigned*)(lds + (bufoff) + ldsw + _i * 8192), 16, 0, 0); } while (0)
; #define PG8_WAIT_V(n) asm volatile("s_waitcnt vmcnt(" #n ")" ::: "memory")
; #define PG8_WAIT_L(n) asm volatile("s_waitcnt lgkmcnt(" #n ")" ::: "memory")
; #define PG8_BAR __builtin_amdgcn_s_barrier()
; #define PG8_SCHED __builtin_amdgcn_sched_barrier(0)
; template <class Epi, class Sched, bool ALIGN_EPI = true, bool SP2 = true>
; __device__ __forceinline__ void gemm_phase(PG8_LAS unsigned char* lds, const int K  , const Sched& S, const Epi& E) {
;     ...
;             PG8_WAIT_V(8); PG8_WAIT_L(0); PG8_BAR; PG8_MMA(1, 0, At, B0); PG8_MMA(1, 1, At, B1); PG8_BAR; PG8_SCHED;
;             PG8_LDB(B0, 1, 0); PG8_LDB(B1, 1, 1); PG8_SCHED; PG8_LDA(At, 1, 0); PG8_STAGE(PG8_SA(0, 1), a2 + hstep, voffA);
;             PG8_WAIT_V(8); PG8_WAIT_L(0); PG8_BAR; PG8_MMA(0, 0, At, B0); PG8_MMA(0, 1, At, B1); PG8_BAR; PG8_SCHED;
	v_mfma_f32_16x16x32_bf16 v[62:65], v[130:133], v[196:199], v[62:65]
	v_mfma_f32_16x16x32_bf16 v[58:61], v[138:141], v[196:199], v[58:61]
	v_mfma_f32_16x16x32_bf16 v[46:49], v[130:133], v[204:207], v[46:49]
	v_mfma_f32_16x16x32_bf16 v[42:45], v[138:141], v[204:207], v[42:45]
	v_mfma_f32_16x16x32_bf16 v[30:33], v[130:133], v[212:215], v[30:33]
	v_mfma_f32_16x16x32_bf16 v[26:29], v[138:141], v[212:215], v[26:29]
	v_mfma_f32_16x16x32_bf16 v[14:17], v[130:133], v[220:223], v[14:17]
	v_mfma_f32_16x16x32_bf16 v[10:13], v[138:141], v[220:223], v[10:13]
	v_mfma_f32_16x16x32_bf16 v[62:65], v[134:137], v[200:203], v[62:65]
	v_mfma_f32_16x16x32_bf16 v[58:61], v[142:145], v[200:203], v[58:61]
	v_mfma_f32_16x16x32_bf16 v[46:49], v[134:137], v[208:211], v[46:49]
	v_mfma_f32_16x16x32_bf16 v[42:45], v[142:145], v[208:211], v[42:45]
	v_mfma_f32_16x16x32_bf16 v[30:33], v[134:137], v[216:219], v[30:33]
	v_mfma_f32_16x16x32_bf16 v[26:29], v[142:145], v[216:219], v[26:29]
	v_mfma_f32_16x16x32_bf16 v[14:17], v[134:137], v[224:227], v[14:17]
	v_mfma_f32_16x16x32_bf16 v[10:13], v[142:145], v[224:227], v[10:13]
	s_setprio 0
	s_setprio 1
	v_mfma_f32_16x16x32_bf16 v[54:57], v[168:171], v[196:199], v[54:57]
	v_mfma_f32_16x16x32_bf16 v[50:53], v[188:191], v[196:199], v[50:53]
	v_mfma_f32_16x16x32_bf16 v[38:41], v[168:171], v[204:207], v[38:41]
	v_mfma_f32_16x16x32_bf16 v[34:37], v[188:191], v[204:207], v[34:37]
	v_mfma_f32_16x16x32_bf16 v[22:25], v[168:171], v[212:215], v[22:25]
	v_mfma_f32_16x16x32_bf16 v[18:21], v[188:191], v[212:215], v[18:21]
	v_mfma_f32_16x16x32_bf16 v[6:9], v[168:171], v[220:223], v[6:9]
	v_mfma_f32_16x16x32_bf16 v[2:5], v[188:191], v[220:223], v[2:5]
	v_mfma_f32_16x16x32_bf16 v[54:57], v[184:187], v[200:203], v[54:57]
	v_mfma_f32_16x16x32_bf16 v[50:53], v[192:195], v[200:203], v[50:53]
	v_mfma_f32_16x16x32_bf16 v[38:41], v[184:187], v[208:211], v[38:41]
	v_mfma_f32_16x16x32_bf16 v[34:37], v[192:195], v[208:211], v[34:37]
	v_mfma_f32_16x16x32_bf16 v[22:25], v[184:187], v[216:219], v[22:25]
	v_mfma_f32_16x16x32_bf16 v[18:21], v[192:195], v[216:219], v[18:21]
	v_mfma_f32_16x16x32_bf16 v[6:9], v[184:187], v[224:227], v[6:9]
	v_mfma_f32_16x16x32_bf16 v[2:5], v[192:195], v[224:227], v[2:5]
	s_barrier
	s_setprio 0
	s_add_i32 s68, 0, 0x18000
	s_add_i32 s69, 0, 0x1c000
	v_add_u32_e32 v142, s68, v172
	v_add_u32_e32 v192, s69, v172
	ds_read_b128 v[130:133], v142
	ds_read_b128 v[134:137], v142 offset:1024
	ds_read_b128 v[138:141], v142 offset:2048
	ds_read_b128 v[142:145], v142 offset:3072
	ds_read_b128 v[168:171], v192
	ds_read_b128 v[184:187], v192 offset:1024
	ds_read_b128 v[188:191], v192 offset:2048
	ds_read_b128 v[192:195], v192 offset:3072
	s_add_u32 s24, s24, 0x80000
	s_addc_u32 s25, s25, 0
	s_mov_b32 m0, s29
	v_lshl_add_u64 v[238:239], s[24:25], 0, v[148:149]
	ds_read_b128 v[196:199], v178 offset:32768
	ds_read_b128 v[200:203], v178 offset:33792
	ds_read_b128 v[204:207], v178 offset:34816
	ds_read_b128 v[208:211], v178 offset:35840
	ds_read_b128 v[212:215], v178 offset:36864
	ds_read_b128 v[216:219], v178 offset:37888
	ds_read_b128 v[220:223], v178 offset:38912
	ds_read_b128 v[224:227], v178 offset:39936
	global_load_lds_dwordx4 v[238:239], off
	s_mov_b32 m0, s30
	v_lshl_add_u64 v[238:239], s[24:25], 0, v[152:153]
	global_load_lds_dwordx4 v[238:239], off
	s_waitcnt vmcnt(8)
	s_waitcnt lgkmcnt(0)
	s_setprio 1
	s_barrier
	v_mfma_f32_16x16x32_bf16 v[126:129], v[130:133], v[196:199], v[126:129]
	v_mfma_f32_16x16x32_bf16 v[122:125], v[138:141], v[196:199], v[122:125]
	v_mfma_f32_16x16x32_bf16 v[110:113], v[130:133], v[204:207], v[110:113]
	v_mfma_f32_16x16x32_bf16 v[106:109], v[138:141], v[204:207], v[106:109]
	v_mfma_f32_16x16x32_bf16 v[94:97], v[130:133], v[212:215], v[94:97]
	v_mfma_f32_16x16x32_bf16 v[90:93], v[138:141], v[212:215], v[90:93]
	v_mfma_f32_16x16x32_bf16 v[78:81], v[130:133], v[220:223], v[78:81]
	v_mfma_f32_16x16x32_bf16 v[74:77], v[138:141], v[220:223], v[74:77]
	v_mfma_f32_16x16x32_bf16 v[126:129], v[134:137], v[200:203], v[126:129]
	v_mfma_f32_16x16x32_bf16 v[122:125], v[142:145], v[200:203], v[122:125]
	v_mfma_f32_16x16x32_bf16 v[110:113], v[134:137], v[208:211], v[110:113]
	v_mfma_f32_16x16x32_bf16 v[106:109], v[142:145], v[208:211], v[106:109]
	v_mfma_f32_16x16x32_bf16 v[94:97], v[134:137], v[216:219], v[94:97]
	v_mfma_f32_16x16x32_bf16 v[90:93], v[142:145], v[216:219], v[90:93]
	v_mfma_f32_16x16x32_bf16 v[78:81], v[134:137], v[224:227], v[78:81]
	v_mfma_f32_16x16x32_bf16 v[74:77], v[142:145], v[224:227], v[74:77]
	s_setprio 0
	s_setprio 1
	v_mfma_f32_16x16x32_bf16 v[118:121], v[168:171], v[196:199], v[118:121]
	v_mfma_f32_16x16x32_bf16 v[114:117], v[188:191], v[196:199], v[114:117]
	v_mfma_f32_16x16x32_bf16 v[102:105], v[168:171], v[204:207], v[102:105]
	v_mfma_f32_16x16x32_bf16 v[98:101], v[188:191], v[204:207], v[98:101]
	v_mfma_f32_16x16x32_bf16 v[86:89], v[168:171], v[212:215], v[86:89]
	v_mfma_f32_16x16x32_bf16 v[82:85], v[188:191], v[212:215], v[82:85]
	v_mfma_f32_16x16x32_bf16 v[70:73], v[168:171], v[220:223], v[70:73]
	v_mfma_f32_16x16x32_bf16 v[66:69], v[188:191], v[220:223], v[66:69]
	v_mfma_f32_16x16x32_bf16 v[118:121], v[184:187], v[200:203], v[118:121]
	v_mfma_f32_16x16x32_bf16 v[114:117], v[192:195], v[200:203], v[114:117]
	v_mfma_f32_16x16x32_bf16 v[102:105], v[184:187], v[208:211], v[102:105]
	v_mfma_f32_16x16x32_bf16 v[98:101], v[192:195], v[208:211], v[98:101]
	v_mfma_f32_16x16x32_bf16 v[86:89], v[184:187], v[216:219], v[86:89]
	v_mfma_f32_16x16x32_bf16 v[82:85], v[192:195], v[216:219], v[82:85]
	v_mfma_f32_16x16x32_bf16 v[70:73], v[184:187], v[224:227], v[70:73]
	v_mfma_f32_16x16x32_bf16 v[66:69], v[192:195], v[224:227], v[66:69]
	s_barrier
; #define PG8_STAGE(bufoff, gbase, voff) do { _Pragma("unroll") for (int _i = 0; _i < 2; ++_i) \
;         __builtin_amdgcn_global_load_lds((const unsigned*)((const char*)(gbase) + (voff)[_i]), (PG8_LAS unsigned*)(lds + (bufoff) + ldsw + _i * 8192), 16, 0, 0); } while (0)
; #define PG8_WAIT_V(n) asm volatile("s_waitcnt vmcnt(" #n ")" ::: "memory")
; #define PG8_WAIT_L(n) asm volatile("s_waitcnt lgkmcnt(" #n ")" ::: "memory")
; #define PG8_BAR __builtin_amdgcn_s_barrier()
; #define PG8_SCHED __builtin_amdgcn_sched_barrier(0)
; template <class Epi, class Sched, bool ALIGN_EPI = true, bool SP2 = true>
; __device__ __forceinline__ void gemm_phase(PG8_LAS unsigned char* lds, const int K  , const Sched& S, const Epi& E) {
;     ...
;             PG8_LDA(At, 1, 1); PG8_STAGE(PG8_SB(1, 0), b3, voffB); PG8_STAGE(PG8_SB(1, 1), b3 + hstep, voffB); PG8_STAGE(PG8_SA(1, 0), a3, voffA);
;             PG8_WAIT_V(8); PG8_WAIT_L(0); PG8_BAR; PG8_MMA(1, 0, At, B0); PG8_MMA(1, 1, At, B1); PG8_BAR; PG8_SCHED;
;     ...
;         if constexpr (ALIGN_EPI) { if (wr == 0) PG8_BAR; }
	s_setprio 0
	s_add_i32 s24, s68, s26
	v_lshl_add_u64 v[230:231], v[230:231], 0, s[4:5]
	s_mov_b32 m0, s24
	ds_read_b128 v[196:199], v178 offset:49152
	ds_read_b128 v[200:203], v178 offset:50176
	ds_read_b128 v[204:207], v178 offset:51200
	ds_read_b128 v[208:211], v178 offset:52224
	ds_read_b128 v[212:215], v178 offset:53248
	ds_read_b128 v[216:219], v178 offset:54272
	ds_read_b128 v[220:223], v178 offset:55296
	ds_read_b128 v[224:227], v178 offset:56320
	global_load_lds_dwordx4 v[230:231], off
	s_add_i32 m0, s24, 0x2000
	s_add_u32 s22, s22, 0x80080
	v_lshl_add_u64 v[230:231], v[232:233], 0, s[4:5]
	s_addc_u32 s23, s23, 0
	s_add_i32 s24, s69, s26
	global_load_lds_dwordx4 v[230:231], off
	s_mov_b32 m0, s24
	v_lshl_add_u64 v[230:231], s[22:23], 0, v[150:151]
	global_load_lds_dwordx4 v[230:231], off
	s_add_i32 m0, s24, 0x2000
	v_lshl_add_u64 v[230:231], s[22:23], 0, v[154:155]
	global_load_lds_dwordx4 v[230:231], off
	s_mov_b32 m0, s35
	v_lshl_add_u64 v[230:231], v[234:235], 0, s[4:5]
	global_load_lds_dwordx4 v[230:231], off
	s_mov_b32 m0, s36
	v_lshl_add_u64 v[230:231], v[236:237], 0, s[4:5]
	global_load_lds_dwordx4 v[230:231], off
	s_waitcnt vmcnt(8)
	s_waitcnt lgkmcnt(0)
	s_setprio 1
	s_barrier
	v_mfma_f32_16x16x32_bf16 v[62:65], v[130:133], v[196:199], v[62:65]
	v_mfma_f32_16x16x32_bf16 v[58:61], v[138:141], v[196:199], v[58:61]
	v_mfma_f32_16x16x32_bf16 v[46:49], v[130:133], v[204:207], v[46:49]
	v_mfma_f32_16x16x32_bf16 v[42:45], v[138:141], v[204:207], v[42:45]
	v_mfma_f32_16x16x32_bf16 v[30:33], v[130:133], v[212:215], v[30:33]
	v_mfma_f32_16x16x32_bf16 v[26:29], v[138:141], v[212:215], v[26:29]
	v_mfma_f32_16x16x32_bf16 v[14:17], v[130:133], v[220:223], v[14:17]
	v_mfma_f32_16x16x32_bf16 v[10:13], v[138:141], v[220:223], v[10:13]
	v_mfma_f32_16x16x32_bf16 v[62:65], v[134:137], v[200:203], v[62:65]
	v_mfma_f32_16x16x32_bf16 v[58:61], v[142:145], v[200:203], v[58:61]
	v_mfma_f32_16x16x32_bf16 v[46:49], v[134:137], v[208:211], v[46:49]
	v_mfma_f32_16x16x32_bf16 v[42:45], v[142:145], v[208:211], v[42:45]
	v_mfma_f32_16x16x32_bf16 v[30:33], v[134:137], v[216:219], v[30:33]
	v_mfma_f32_16x16x32_bf16 v[26:29], v[142:145], v[216:219], v[26:29]
	v_mfma_f32_16x16x32_bf16 v[14:17], v[134:137], v[224:227], v[14:17]
	v_mfma_f32_16x16x32_bf16 v[10:13], v[142:145], v[224:227], v[10:13]
	s_setprio 0
	s_setprio 1
	v_mfma_f32_16x16x32_bf16 v[54:57], v[168:171], v[196:199], v[54:57]
	v_mfma_f32_16x16x32_bf16 v[50:53], v[188:191], v[196:199], v[50:53]
	v_mfma_f32_16x16x32_bf16 v[38:41], v[168:171], v[204:207], v[38:41]
	v_mfma_f32_16x16x32_bf16 v[34:37], v[188:191], v[204:207], v[34:37]
	v_mfma_f32_16x16x32_bf16 v[22:25], v[168:171], v[212:215], v[22:25]
	v_mfma_f32_16x16x32_bf16 v[18:21], v[188:191], v[212:215], v[18:21]
	v_mfma_f32_16x16x32_bf16 v[6:9], v[168:171], v[220:223], v[6:9]
	v_mfma_f32_16x16x32_bf16 v[2:5], v[188:191], v[220:223], v[2:5]
	v_mfma_f32_16x16x32_bf16 v[54:57], v[184:187], v[200:203], v[54:57]
	v_mfma_f32_16x16x32_bf16 v[50:53], v[192:195], v[200:203], v[50:53]
	v_mfma_f32_16x16x32_bf16 v[38:41], v[184:187], v[208:211], v[38:41]
	v_mfma_f32_16x16x32_bf16 v[34:37], v[192:195], v[208:211], v[34:37]
	v_mfma_f32_16x16x32_bf16 v[22:25], v[184:187], v[216:219], v[22:25]
	v_mfma_f32_16x16x32_bf16 v[18:21], v[192:195], v[216:219], v[18:21]
	v_mfma_f32_16x16x32_bf16 v[6:9], v[184:187], v[224:227], v[6:9]
	v_mfma_f32_16x16x32_bf16 v[2:5], v[192:195], v[224:227], v[2:5]
	s_barrier
	s_setprio 0
	s_add_i32 s51, s51, 2
	s_add_u32 s0, s0, 0x100
	s_addc_u32 s1, s1, 0
	s_add_u32 s49, s49, 0x100
	s_addc_u32 s50, s50, 0
	s_cmp_gt_u32 s51, 29
	s_cbranch_scc0 .LBB0_1847
	s_and_b64 vcc, exec, s[8:9]
	s_cbranch_vccz .LBB0_1850
	s_barrier

; #define PG8_STAGE(bufoff, gbase, voff) do { _Pragma("unroll") for (int _i = 0; _i < 2; ++_i) \
;         __builtin_amdgcn_global_load_lds((const unsigned*)((const char*)(gbase) + (voff)[_i]), (PG8_LAS unsigned*)(lds + (bufoff) + ldsw + _i * 8192), 16, 0, 0); } while (0)
; #define PG8_WAIT_V(n) asm volatile("s_waitcnt vmcnt(" #n ")" ::: "memory")
; #define PG8_WAIT_L(n) asm volatile("s_waitcnt lgkmcnt(" #n ")" ::: "memory")
; #define PG8_BAR __builtin_amdgcn_s_barrier()
; #define PG8_SCHED __builtin_amdgcn_sched_barrier(0)
;     __device__ __forceinline__ int nt(const pg8::Unit& u) const { return u.kind == 0 ? ntiles : q_nt(u.kind - 1); }
; template <class Epi, class Sched, bool ALIGN_EPI = true, bool SP2 = true>
; __device__ __forceinline__ void gemm_phase(PG8_LAS unsigned char* lds, const int K  , const Sched& S, const Epi& E) {
;     ...
;         for (int t = 0; t < nt; t += 2) {
;             const bool last = (t == nt - 2);
;             const char* a1 = cA + (size_t)(t + 1) * kstep;
;             const char* a2 = last ? nA : cA + (size_t)(t + 2) * kstep; const char* b2 = last ? nB : cB + (size_t)(t + 2) * kstep;
;             const char* a3 = a2 + kstep; const char* b3 = b2 + kstep;
;             if constexpr (SP2) {
;             PG8_LDB(B0, 0, 0); PG8_LDB(B1, 0, 1); PG8_SCHED; PG8_LDA(At, 0, 0); PG8_STAGE(PG8_SA(1, 1), a1 + hstep, voffA);
;             PG8_WAIT_V(8); PG8_WAIT_L(0); PG8_BAR; PG8_MMA(0, 0, At, B0); PG8_MMA(0, 1, At, B1); PG8_BAR; PG8_SCHED;
;             PG8_LDA(At, 0, 1); PG8_STAGE(PG8_SB(0, 0), b2, voffB); PG8_STAGE(PG8_SB(0, 1), b2 + hstep, voffB); PG8_STAGE(PG8_SA(0, 0), a2, voffA);
.LBB0_2296:
	ds_read_b128 v[130:133], v203
	ds_read_b128 v[134:137], v203 offset:1024
	ds_read_b128 v[138:141], v203 offset:2048
	ds_read_b128 v[142:145], v203 offset:3072
	ds_read_b128 v[146:149], v204
	ds_read_b128 v[150:153], v204 offset:1024
	ds_read_b128 v[154:157], v204 offset:2048
	ds_read_b128 v[158:161], v204 offset:3072
	s_add_u32 s22, s20, 0xfff80080
	s_addc_u32 s23, s21, -1
	s_cmp_eq_u32 s54, 28
	s_cselect_b32 s25, s13, s23
	s_cselect_b32 s24, s50, s22
	s_cselect_b32 s23, s11, s53
	s_cselect_b32 s22, s51, s52
	v_lshl_add_u64 v[198:199], s[20:21], 0, v[190:191]
	s_add_i32 m0, s19, 0xc000
	ds_read_b128 v[162:165], v205
	ds_read_b128 v[166:169], v205 offset:1024
	ds_read_b128 v[170:173], v205 offset:2048
	ds_read_b128 v[174:177], v205 offset:3072
	ds_read_b128 v[178:181], v205 offset:4096
	ds_read_b128 v[206:209], v205 offset:5120
	ds_read_b128 v[210:213], v205 offset:6144
	ds_read_b128 v[214:217], v205 offset:7168
	global_load_lds_dwordx4 v[198:199], off
	s_add_i32 m0, s19, 0xe000
	v_lshl_add_u64 v[198:199], s[20:21], 0, v[192:193]
	global_load_lds_dwordx4 v[198:199], off
	s_waitcnt vmcnt(8)
	s_waitcnt lgkmcnt(0)
	s_setprio 1
	s_barrier
	v_mfma_f32_16x16x32_bf16 v[126:129], v[130:133], v[162:165], v[126:129]
	v_mfma_f32_16x16x32_bf16 v[122:125], v[138:141], v[162:165], v[122:125]
	v_mfma_f32_16x16x32_bf16 v[114:117], v[130:133], v[170:173], v[114:117]
	v_mfma_f32_16x16x32_bf16 v[106:109], v[138:141], v[170:173], v[106:109]
	v_mfma_f32_16x16x32_bf16 v[98:101], v[130:133], v[178:181], v[98:101]
	v_mfma_f32_16x16x32_bf16 v[90:93], v[138:141], v[178:181], v[90:93]
	v_mfma_f32_16x16x32_bf16 v[82:85], v[130:133], v[210:213], v[82:85]
	v_mfma_f32_16x16x32_bf16 v[74:77], v[138:141], v[210:213], v[74:77]
	v_mfma_f32_16x16x32_bf16 v[126:129], v[134:137], v[166:169], v[126:129]
	v_mfma_f32_16x16x32_bf16 v[122:125], v[142:145], v[166:169], v[122:125]
	v_mfma_f32_16x16x32_bf16 v[114:117], v[134:137], v[174:177], v[114:117]
	v_mfma_f32_16x16x32_bf16 v[106:109], v[142:145], v[174:177], v[106:109]
	v_mfma_f32_16x16x32_bf16 v[98:101], v[134:137], v[206:209], v[98:101]
	v_mfma_f32_16x16x32_bf16 v[90:93], v[142:145], v[206:209], v[90:93]
	v_mfma_f32_16x16x32_bf16 v[82:85], v[134:137], v[214:217], v[82:85]
	v_mfma_f32_16x16x32_bf16 v[74:77], v[142:145], v[214:217], v[74:77]
	s_setprio 0
	s_setprio 1
	v_mfma_f32_16x16x32_bf16 v[118:121], v[146:149], v[162:165], v[118:121]
	v_mfma_f32_16x16x32_bf16 v[110:113], v[154:157], v[162:165], v[110:113]
	v_mfma_f32_16x16x32_bf16 v[102:105], v[146:149], v[170:173], v[102:105]
	v_mfma_f32_16x16x32_bf16 v[94:97], v[154:157], v[170:173], v[94:97]
	v_mfma_f32_16x16x32_bf16 v[86:89], v[146:149], v[178:181], v[86:89]
	v_mfma_f32_16x16x32_bf16 v[78:81], v[154:157], v[178:181], v[78:81]
	v_mfma_f32_16x16x32_bf16 v[70:73], v[146:149], v[210:213], v[70:73]
	v_mfma_f32_16x16x32_bf16 v[66:69], v[154:157], v[210:213], v[66:69]
	v_mfma_f32_16x16x32_bf16 v[118:121], v[150:153], v[166:169], v[118:121]
	v_mfma_f32_16x16x32_bf16 v[110:113], v[158:161], v[166:169], v[110:113]
	v_mfma_f32_16x16x32_bf16 v[102:105], v[150:153], v[174:177], v[102:105]
	v_mfma_f32_16x16x32_bf16 v[94:97], v[158:161], v[174:177], v[94:97]
	v_mfma_f32_16x16x32_bf16 v[86:89], v[150:153], v[206:209], v[86:89]
	v_mfma_f32_16x16x32_bf16 v[78:81], v[158:161], v[206:209], v[78:81]
	v_mfma_f32_16x16x32_bf16 v[70:73], v[150:153], v[214:217], v[70:73]
	v_mfma_f32_16x16x32_bf16 v[66:69], v[158:161], v[214:217], v[66:69]
	s_barrier
	s_setprio 0
	s_add_i32 s55, s42, s29
	v_lshl_add_u64 v[198:199], s[22:23], 0, v[184:185]
	s_mov_b32 m0, s55
	ds_read_b128 v[162:165], v205 offset:16384
	ds_read_b128 v[166:169], v205 offset:17408
	ds_read_b128 v[170:173], v205 offset:18432
	ds_read_b128 v[174:177], v205 offset:19456
	ds_read_b128 v[178:181], v205 offset:20480
	ds_read_b128 v[206:209], v205 offset:21504
	ds_read_b128 v[210:213], v205 offset:22528
	ds_read_b128 v[214:217], v205 offset:23552
	global_load_lds_dwordx4 v[198:199], off
	s_add_i32 m0, s55, 0x2000
	s_add_u32 s56, s22, 0x80000
	v_lshl_add_u64 v[218:219], s[22:23], 0, v[188:189]
	s_addc_u32 s57, s23, 0
	s_add_i32 s55, s43, s29
	global_load_lds_dwordx4 v[218:219], off
	v_lshl_add_u64 v[220:221], s[56:57], 0, v[184:185]
	s_mov_b32 m0, s55
	v_lshl_add_u64 v[222:223], s[24:25], 0, v[186:187]
	global_load_lds_dwordx4 v[220:221], off
	s_add_i32 m0, s55, 0x2000
	v_lshl_add_u64 v[220:221], s[56:57], 0, v[188:189]
	global_load_lds_dwordx4 v[220:221], off
	s_mov_b32 m0, s19
	v_lshl_add_u64 v[220:221], s[24:25], 0, v[182:183]
	global_load_lds_dwordx4 v[220:221], off
	s_mov_b32 m0, s30
	s_nop 0
	global_load_lds_dwordx4 v[222:223], off
	s_waitcnt vmcnt(8)
	s_waitcnt lgkmcnt(0)
	s_setprio 1
	s_barrier
; #define PG8_STAGE(bufoff, gbase, voff) do { _Pragma("unroll") for (int _i = 0; _i < 2; ++_i) \
;         __builtin_amdgcn_global_load_lds((const unsigned*)((const char*)(gbase) + (voff)[_i]), (PG8_LAS unsigned*)(lds + (bufoff) + ldsw + _i * 8192), 16, 0, 0); } while (0)
; #define PG8_WAIT_V(n) asm volatile("s_waitcnt vmcnt(" #n ")" ::: "memory")
; #define PG8_WAIT_L(n) asm volatile("s_waitcnt lgkmcnt(" #n ")" ::: "memory")
; #define PG8_BAR __builtin_amdgcn_s_barrier()
; #define PG8_SCHED __builtin_amdgcn_sched_barrier(0)
; template <class Epi, class Sched, bool ALIGN_EPI = true, bool SP2 = true>
; __device__ __forceinline__ void gemm_phase(PG8_LAS unsigned char* lds, const int K  , const Sched& S, const Epi& E) {
;     ...
;             PG8_WAIT_V(8); PG8_WAIT_L(0); PG8_BAR; PG8_MMA(1, 0, At, B0); PG8_MMA(1, 1, At, B1); PG8_BAR; PG8_SCHED;
;             PG8_LDB(B0, 1, 0); PG8_LDB(B1, 1, 1); PG8_SCHED; PG8_LDA(At, 1, 0); PG8_STAGE(PG8_SA(0, 1), a2 + hstep, voffA);
;             PG8_WAIT_V(8); PG8_WAIT_L(0); PG8_BAR; PG8_MMA(0, 0, At, B0); PG8_MMA(0, 1, At, B1); PG8_BAR; PG8_SCHED;
	v_mfma_f32_16x16x32_bf16 v[62:65], v[130:133], v[162:165], v[62:65]
	v_mfma_f32_16x16x32_bf16 v[58:61], v[138:141], v[162:165], v[58:61]
	v_mfma_f32_16x16x32_bf16 v[50:53], v[130:133], v[170:173], v[50:53]
	v_mfma_f32_16x16x32_bf16 v[42:45], v[138:141], v[170:173], v[42:45]
	v_mfma_f32_16x16x32_bf16 v[34:37], v[130:133], v[178:181], v[34:37]
	v_mfma_f32_16x16x32_bf16 v[26:29], v[138:141], v[178:181], v[26:29]
	v_mfma_f32_16x16x32_bf16 v[18:21], v[130:133], v[210:213], v[18:21]
	v_mfma_f32_16x16x32_bf16 v[10:13], v[138:141], v[210:213], v[10:13]
	v_mfma_f32_16x16x32_bf16 v[62:65], v[134:137], v[166:169], v[62:65]
	v_mfma_f32_16x16x32_bf16 v[58:61], v[142:145], v[166:169], v[58:61]
	v_mfma_f32_16x16x32_bf16 v[50:53], v[134:137], v[174:177], v[50:53]
	v_mfma_f32_16x16x32_bf16 v[42:45], v[142:145], v[174:177], v[42:45]
	v_mfma_f32_16x16x32_bf16 v[34:37], v[134:137], v[206:209], v[34:37]
	v_mfma_f32_16x16x32_bf16 v[26:29], v[142:145], v[206:209], v[26:29]
	v_mfma_f32_16x16x32_bf16 v[18:21], v[134:137], v[214:217], v[18:21]
	v_mfma_f32_16x16x32_bf16 v[10:13], v[142:145], v[214:217], v[10:13]
	s_setprio 0
	s_setprio 1
	v_mfma_f32_16x16x32_bf16 v[54:57], v[146:149], v[162:165], v[54:57]
	v_mfma_f32_16x16x32_bf16 v[46:49], v[154:157], v[162:165], v[46:49]
	v_mfma_f32_16x16x32_bf16 v[38:41], v[146:149], v[170:173], v[38:41]
	v_mfma_f32_16x16x32_bf16 v[30:33], v[154:157], v[170:173], v[30:33]
	v_mfma_f32_16x16x32_bf16 v[22:25], v[146:149], v[178:181], v[22:25]
	v_mfma_f32_16x16x32_bf16 v[14:17], v[154:157], v[178:181], v[14:17]
	v_mfma_f32_16x16x32_bf16 v[6:9], v[146:149], v[210:213], v[6:9]
	v_mfma_f32_16x16x32_bf16 v[2:5], v[154:157], v[210:213], v[2:5]
	v_mfma_f32_16x16x32_bf16 v[54:57], v[150:153], v[166:169], v[54:57]
	v_mfma_f32_16x16x32_bf16 v[46:49], v[158:161], v[166:169], v[46:49]
	v_mfma_f32_16x16x32_bf16 v[38:41], v[150:153], v[174:177], v[38:41]
	v_mfma_f32_16x16x32_bf16 v[30:33], v[158:161], v[174:177], v[30:33]
	v_mfma_f32_16x16x32_bf16 v[22:25], v[150:153], v[206:209], v[22:25]
	v_mfma_f32_16x16x32_bf16 v[14:17], v[158:161], v[206:209], v[14:17]
	v_mfma_f32_16x16x32_bf16 v[6:9], v[150:153], v[214:217], v[6:9]
	v_mfma_f32_16x16x32_bf16 v[2:5], v[158:161], v[214:217], v[2:5]
	s_barrier
	s_setprio 0
	s_add_i32 s55, 0, 0x18000
	s_add_i32 s56, 0, 0x1c000
	v_add_u32_e32 v142, s55, v201
	v_add_u32_e32 v158, s56, v201
	ds_read_b128 v[130:133], v142
	ds_read_b128 v[134:137], v142 offset:1024
	ds_read_b128 v[138:141], v142 offset:2048
	ds_read_b128 v[142:145], v142 offset:3072
	ds_read_b128 v[146:149], v158
	ds_read_b128 v[150:153], v158 offset:1024
	ds_read_b128 v[154:157], v158 offset:2048
	ds_read_b128 v[158:161], v158 offset:3072
	s_add_u32 s24, s24, 0x80000
	s_addc_u32 s25, s25, 0
	s_mov_b32 m0, s31
	v_lshl_add_u64 v[224:225], s[24:25], 0, v[182:183]
	ds_read_b128 v[162:165], v205 offset:32768
	ds_read_b128 v[166:169], v205 offset:33792
	ds_read_b128 v[170:173], v205 offset:34816
	ds_read_b128 v[174:177], v205 offset:35840
	ds_read_b128 v[178:181], v205 offset:36864
	ds_read_b128 v[206:209], v205 offset:37888
	ds_read_b128 v[210:213], v205 offset:38912
	ds_read_b128 v[214:217], v205 offset:39936
	global_load_lds_dwordx4 v[224:225], off
	s_mov_b32 m0, s33
	v_lshl_add_u64 v[224:225], s[24:25], 0, v[186:187]
	global_load_lds_dwordx4 v[224:225], off
	s_waitcnt vmcnt(8)
	s_waitcnt lgkmcnt(0)
	s_setprio 1
	s_barrier
	v_mfma_f32_16x16x32_bf16 v[126:129], v[130:133], v[162:165], v[126:129]
	v_mfma_f32_16x16x32_bf16 v[122:125], v[138:141], v[162:165], v[122:125]
	v_mfma_f32_16x16x32_bf16 v[114:117], v[130:133], v[170:173], v[114:117]
	v_mfma_f32_16x16x32_bf16 v[106:109], v[138:141], v[170:173], v[106:109]
	v_mfma_f32_16x16x32_bf16 v[98:101], v[130:133], v[178:181], v[98:101]
	v_mfma_f32_16x16x32_bf16 v[90:93], v[138:141], v[178:181], v[90:93]
	v_mfma_f32_16x16x32_bf16 v[82:85], v[130:133], v[210:213], v[82:85]
	v_mfma_f32_16x16x32_bf16 v[74:77], v[138:141], v[210:213], v[74:77]
	v_mfma_f32_16x16x32_bf16 v[126:129], v[134:137], v[166:169], v[126:129]
	v_mfma_f32_16x16x32_bf16 v[122:125], v[142:145], v[166:169], v[122:125]
	v_mfma_f32_16x16x32_bf16 v[114:117], v[134:137], v[174:177], v[114:117]
	v_mfma_f32_16x16x32_bf16 v[106:109], v[142:145], v[174:177], v[106:109]
	v_mfma_f32_16x16x32_bf16 v[98:101], v[134:137], v[206:209], v[98:101]
	v_mfma_f32_16x16x32_bf16 v[90:93], v[142:145], v[206:209], v[90:93]
	v_mfma_f32_16x16x32_bf16 v[82:85], v[134:137], v[214:217], v[82:85]
	v_mfma_f32_16x16x32_bf16 v[74:77], v[142:145], v[214:217], v[74:77]
	s_setprio 0
	s_setprio 1
	v_mfma_f32_16x16x32_bf16 v[118:121], v[146:149], v[162:165], v[118:121]
	v_mfma_f32_16x16x32_bf16 v[110:113], v[154:157], v[162:165], v[110:113]
	v_mfma_f32_16x16x32_bf16 v[102:105], v[146:149], v[170:173], v[102:105]
	v_mfma_f32_16x16x32_bf16 v[94:97], v[154:157], v[170:173], v[94:97]
	v_mfma_f32_16x16x32_bf16 v[86:89], v[146:149], v[178:181], v[86:89]
	v_mfma_f32_16x16x32_bf16 v[78:81], v[154:157], v[178:181], v[78:81]
	v_mfma_f32_16x16x32_bf16 v[70:73], v[146:149], v[210:213], v[70:73]
	v_mfma_f32_16x16x32_bf16 v[66:69], v[154:157], v[210:213], v[66:69]
	v_mfma_f32_16x16x32_bf16 v[118:121], v[150:153], v[166:169], v[118:121]
	v_mfma_f32_16x16x32_bf16 v[110:113], v[158:161], v[166:169], v[110:113]
	v_mfma_f32_16x16x32_bf16 v[102:105], v[150:153], v[174:177], v[102:105]
	v_mfma_f32_16x16x32_bf16 v[94:97], v[158:161], v[174:177], v[94:97]
	v_mfma_f32_16x16x32_bf16 v[86:89], v[150:153], v[206:209], v[86:89]
	v_mfma_f32_16x16x32_bf16 v[78:81], v[158:161], v[206:209], v[78:81]
	v_mfma_f32_16x16x32_bf16 v[70:73], v[150:153], v[214:217], v[70:73]
	v_mfma_f32_16x16x32_bf16 v[66:69], v[158:161], v[214:217], v[66:69]
	s_barrier
; #define PG8_STAGE(bufoff, gbase, voff) do { _Pragma("unroll") for (int _i = 0; _i < 2; ++_i) \
;         __builtin_amdgcn_global_load_lds((const unsigned*)((const char*)(gbase) + (voff)[_i]), (PG8_LAS unsigned*)(lds + (bufoff) + ldsw + _i * 8192), 16, 0, 0); } while (0)
; #define PG8_WAIT_V(n) asm volatile("s_waitcnt vmcnt(" #n ")" ::: "memory")
; #define PG8_WAIT_L(n) asm volatile("s_waitcnt lgkmcnt(" #n ")" ::: "memory")
; #define PG8_BAR __builtin_amdgcn_s_barrier()
; #define PG8_SCHED __builtin_amdgcn_sched_barrier(0)
; template <class Epi, class Sched, bool ALIGN_EPI = true, bool SP2 = true>
; __device__ __forceinline__ void gemm_phase(PG8_LAS unsigned char* lds, const int K  , const Sched& S, const Epi& E) {
;     ...
;             PG8_LDA(At, 1, 1); PG8_STAGE(PG8_SB(1, 0), b3, voffB); PG8_STAGE(PG8_SB(1, 1), b3 + hstep, voffB); PG8_STAGE(PG8_SA(1, 0), a3, voffA);
;             PG8_WAIT_V(8); PG8_WAIT_L(0); PG8_BAR; PG8_MMA(1, 0, At, B0); PG8_MMA(1, 1, At, B1); PG8_BAR; PG8_SCHED;
;     ...
;         if constexpr (ALIGN_EPI) { if (wr == 0) PG8_BAR; }
	s_setprio 0
	s_add_i32 s24, s55, s29
	v_lshl_add_u64 v[198:199], v[198:199], 0, s[6:7]
	s_mov_b32 m0, s24
	ds_read_b128 v[162:165], v205 offset:49152
	ds_read_b128 v[166:169], v205 offset:50176
	ds_read_b128 v[170:173], v205 offset:51200
	ds_read_b128 v[174:177], v205 offset:52224
	ds_read_b128 v[178:181], v205 offset:53248
	ds_read_b128 v[206:209], v205 offset:54272
	ds_read_b128 v[210:213], v205 offset:55296
	ds_read_b128 v[214:217], v205 offset:56320
	global_load_lds_dwordx4 v[198:199], off
	s_add_i32 m0, s24, 0x2000
	s_add_u32 s22, s22, 0x80080
	v_lshl_add_u64 v[198:199], v[218:219], 0, s[6:7]
	s_addc_u32 s23, s23, 0
	s_add_i32 s24, s56, s29
	global_load_lds_dwordx4 v[198:199], off
	s_mov_b32 m0, s24
	v_lshl_add_u64 v[198:199], s[22:23], 0, v[184:185]
	global_load_lds_dwordx4 v[198:199], off
	s_add_i32 m0, s24, 0x2000
	v_lshl_add_u64 v[198:199], s[22:23], 0, v[188:189]
	global_load_lds_dwordx4 v[198:199], off
	s_mov_b32 m0, s38
	v_lshl_add_u64 v[198:199], v[220:221], 0, s[6:7]
	global_load_lds_dwordx4 v[198:199], off
	s_mov_b32 m0, s39
	v_lshl_add_u64 v[198:199], v[222:223], 0, s[6:7]
	global_load_lds_dwordx4 v[198:199], off
	s_waitcnt vmcnt(8)
	s_waitcnt lgkmcnt(0)
	s_setprio 1
	s_barrier
	v_mfma_f32_16x16x32_bf16 v[62:65], v[130:133], v[162:165], v[62:65]
	v_mfma_f32_16x16x32_bf16 v[58:61], v[138:141], v[162:165], v[58:61]
	v_mfma_f32_16x16x32_bf16 v[50:53], v[130:133], v[170:173], v[50:53]
	v_mfma_f32_16x16x32_bf16 v[42:45], v[138:141], v[170:173], v[42:45]
	v_mfma_f32_16x16x32_bf16 v[34:37], v[130:133], v[178:181], v[34:37]
	v_mfma_f32_16x16x32_bf16 v[26:29], v[138:141], v[178:181], v[26:29]
	v_mfma_f32_16x16x32_bf16 v[18:21], v[130:133], v[210:213], v[18:21]
	v_mfma_f32_16x16x32_bf16 v[10:13], v[138:141], v[210:213], v[10:13]
	v_mfma_f32_16x16x32_bf16 v[62:65], v[134:137], v[166:169], v[62:65]
	v_mfma_f32_16x16x32_bf16 v[58:61], v[142:145], v[166:169], v[58:61]
	v_mfma_f32_16x16x32_bf16 v[50:53], v[134:137], v[174:177], v[50:53]
	v_mfma_f32_16x16x32_bf16 v[42:45], v[142:145], v[174:177], v[42:45]
	v_mfma_f32_16x16x32_bf16 v[34:37], v[134:137], v[206:209], v[34:37]
	v_mfma_f32_16x16x32_bf16 v[26:29], v[142:145], v[206:209], v[26:29]
	v_mfma_f32_16x16x32_bf16 v[18:21], v[134:137], v[214:217], v[18:21]
	v_mfma_f32_16x16x32_bf16 v[10:13], v[142:145], v[214:217], v[10:13]
	s_setprio 0
	s_setprio 1
	v_mfma_f32_16x16x32_bf16 v[54:57], v[146:149], v[162:165], v[54:57]
	v_mfma_f32_16x16x32_bf16 v[46:49], v[154:157], v[162:165], v[46:49]
	v_mfma_f32_16x16x32_bf16 v[38:41], v[146:149], v[170:173], v[38:41]
	v_mfma_f32_16x16x32_bf16 v[30:33], v[154:157], v[170:173], v[30:33]
	v_mfma_f32_16x16x32_bf16 v[22:25], v[146:149], v[178:181], v[22:25]
	v_mfma_f32_16x16x32_bf16 v[14:17], v[154:157], v[178:181], v[14:17]
	v_mfma_f32_16x16x32_bf16 v[6:9], v[146:149], v[210:213], v[6:9]
	v_mfma_f32_16x16x32_bf16 v[2:5], v[154:157], v[210:213], v[2:5]
	v_mfma_f32_16x16x32_bf16 v[54:57], v[150:153], v[166:169], v[54:57]
	v_mfma_f32_16x16x32_bf16 v[46:49], v[158:161], v[166:169], v[46:49]
	v_mfma_f32_16x16x32_bf16 v[38:41], v[150:153], v[174:177], v[38:41]
	v_mfma_f32_16x16x32_bf16 v[30:33], v[158:161], v[174:177], v[30:33]
	v_mfma_f32_16x16x32_bf16 v[22:25], v[150:153], v[206:209], v[22:25]
	v_mfma_f32_16x16x32_bf16 v[14:17], v[158:161], v[206:209], v[14:17]
	v_mfma_f32_16x16x32_bf16 v[6:9], v[150:153], v[214:217], v[6:9]
	v_mfma_f32_16x16x32_bf16 v[2:5], v[158:161], v[214:217], v[2:5]
	s_barrier
	s_setprio 0
	s_add_i32 s54, s54, 2
	s_add_u32 s20, s20, 0x100
	s_addc_u32 s21, s21, 0
	s_add_u32 s52, s52, 0x100
	s_addc_u32 s53, s53, 0
	s_cmp_gt_u32 s54, 29
	s_cbranch_scc0 .LBB0_2296
	s_and_b64 vcc, exec, s[8:9]
	s_cbranch_vccz .LBB0_2299
	s_barrier

; #define PG8_STAGE(bufoff, gbase, voff) do { _Pragma("unroll") for (int _i = 0; _i < 2; ++_i) \
;         __builtin_amdgcn_global_load_lds((const unsigned*)((const char*)(gbase) + (voff)[_i]), (PG8_LAS unsigned*)(lds + (bufoff) + ldsw + _i * 8192), 16, 0, 0); } while (0)
; #define PG8_WAIT_V(n) asm volatile("s_waitcnt vmcnt(" #n ")" ::: "memory")
; #define PG8_WAIT_L(n) asm volatile("s_waitcnt lgkmcnt(" #n ")" ::: "memory")
; #define PG8_BAR __builtin_amdgcn_s_barrier()
; #define PG8_SCHED __builtin_amdgcn_sched_barrier(0)
;     __device__ __forceinline__ int nt(const pg8::Unit& u) const { return u.kind == 0 ? ntiles : q_nt(u.kind - 1); }
; template <class Epi, class Sched, bool ALIGN_EPI = true, bool SP2 = true>
; __device__ __forceinline__ void gemm_phase(PG8_LAS unsigned char* lds, const int K  , const Sched& S, const Epi& E) {
;     ...
;         for (int t = 0; t < nt; t += 2) {
;             const bool last = (t == nt - 2);
;             const char* a1 = cA + (size_t)(t + 1) * kstep;
;             const char* a2 = last ? nA : cA + (size_t)(t + 2) * kstep; const char* b2 = last ? nB : cB + (size_t)(t + 2) * kstep;
;             const char* a3 = a2 + kstep; const char* b3 = b2 + kstep;
;             if constexpr (SP2) {
;             PG8_LDB(B0, 0, 0); PG8_LDB(B1, 0, 1); PG8_SCHED; PG8_LDA(At, 0, 0); PG8_STAGE(PG8_SA(1, 1), a1 + hstep, voffA);
;             PG8_WAIT_V(8); PG8_WAIT_L(0); PG8_BAR; PG8_MMA(0, 0, At, B0); PG8_MMA(0, 1, At, B1); PG8_BAR; PG8_SCHED;
;             PG8_LDA(At, 0, 1); PG8_STAGE(PG8_SB(0, 0), b2, voffB); PG8_STAGE(PG8_SB(0, 1), b2 + hstep, voffB); PG8_STAGE(PG8_SA(0, 0), a2, voffA);
.LBB0_2433:
	ds_read_b128 v[146:149], v152
	ds_read_b128 v[158:161], v152 offset:1024
	ds_read_b128 v[162:165], v152 offset:2048
	ds_read_b128 v[166:169], v152 offset:3072
	ds_read_b128 v[170:173], v153
	ds_read_b128 v[174:177], v153 offset:1024
	ds_read_b128 v[178:181], v153 offset:2048
	ds_read_b128 v[182:185], v153 offset:3072
	s_add_u32 s22, s20, 0xfff80080
	s_addc_u32 s23, s21, -1
	s_cmp_eq_u32 s48, 28
	s_cselect_b32 s25, s13, s23
	s_cselect_b32 s24, s44, s22
	s_cselect_b32 s23, s11, s47
	s_cselect_b32 s22, s45, s46
	v_lshl_add_u64 v[218:219], s[20:21], 0, v[138:139]
	s_add_i32 m0, s19, 0xc000
	ds_read_b128 v[186:189], v154
	ds_read_b128 v[190:193], v154 offset:1024
	ds_read_b128 v[194:197], v154 offset:2048
	ds_read_b128 v[198:201], v154 offset:3072
	ds_read_b128 v[202:205], v154 offset:4096
	ds_read_b128 v[206:209], v154 offset:5120
	ds_read_b128 v[210:213], v154 offset:6144
	ds_read_b128 v[214:217], v154 offset:7168
	global_load_lds_dwordx4 v[218:219], off
	s_add_i32 m0, s19, 0xe000
	v_lshl_add_u64 v[218:219], s[20:21], 0, v[140:141]
	global_load_lds_dwordx4 v[218:219], off
	s_waitcnt vmcnt(8)
	s_waitcnt lgkmcnt(0)
	s_setprio 1
	s_barrier
	v_mfma_f32_16x16x32_bf16 v[126:129], v[146:149], v[186:189], v[126:129]
	v_mfma_f32_16x16x32_bf16 v[118:121], v[162:165], v[186:189], v[118:121]
	v_mfma_f32_16x16x32_bf16 v[110:113], v[146:149], v[194:197], v[110:113]
	v_mfma_f32_16x16x32_bf16 v[102:105], v[162:165], v[194:197], v[102:105]
	v_mfma_f32_16x16x32_bf16 v[94:97], v[146:149], v[202:205], v[94:97]
	v_mfma_f32_16x16x32_bf16 v[86:89], v[162:165], v[202:205], v[86:89]
	v_mfma_f32_16x16x32_bf16 v[78:81], v[146:149], v[210:213], v[78:81]
	v_mfma_f32_16x16x32_bf16 v[70:73], v[162:165], v[210:213], v[70:73]
	v_mfma_f32_16x16x32_bf16 v[126:129], v[158:161], v[190:193], v[126:129]
	v_mfma_f32_16x16x32_bf16 v[118:121], v[166:169], v[190:193], v[118:121]
	v_mfma_f32_16x16x32_bf16 v[110:113], v[158:161], v[198:201], v[110:113]
	v_mfma_f32_16x16x32_bf16 v[102:105], v[166:169], v[198:201], v[102:105]
	v_mfma_f32_16x16x32_bf16 v[94:97], v[158:161], v[206:209], v[94:97]
	v_mfma_f32_16x16x32_bf16 v[86:89], v[166:169], v[206:209], v[86:89]
	v_mfma_f32_16x16x32_bf16 v[78:81], v[158:161], v[214:217], v[78:81]
	v_mfma_f32_16x16x32_bf16 v[70:73], v[166:169], v[214:217], v[70:73]
	s_setprio 0
	s_setprio 1
	v_mfma_f32_16x16x32_bf16 v[122:125], v[170:173], v[186:189], v[122:125]
	v_mfma_f32_16x16x32_bf16 v[114:117], v[178:181], v[186:189], v[114:117]
	v_mfma_f32_16x16x32_bf16 v[106:109], v[170:173], v[194:197], v[106:109]
	v_mfma_f32_16x16x32_bf16 v[98:101], v[178:181], v[194:197], v[98:101]
	v_mfma_f32_16x16x32_bf16 v[90:93], v[170:173], v[202:205], v[90:93]
	v_mfma_f32_16x16x32_bf16 v[82:85], v[178:181], v[202:205], v[82:85]
	v_mfma_f32_16x16x32_bf16 v[74:77], v[170:173], v[210:213], v[74:77]
	v_mfma_f32_16x16x32_bf16 v[66:69], v[178:181], v[210:213], v[66:69]
	v_mfma_f32_16x16x32_bf16 v[122:125], v[174:177], v[190:193], v[122:125]
	v_mfma_f32_16x16x32_bf16 v[114:117], v[182:185], v[190:193], v[114:117]
	v_mfma_f32_16x16x32_bf16 v[106:109], v[174:177], v[198:201], v[106:109]
	v_mfma_f32_16x16x32_bf16 v[98:101], v[182:185], v[198:201], v[98:101]
	v_mfma_f32_16x16x32_bf16 v[90:93], v[174:177], v[206:209], v[90:93]
	v_mfma_f32_16x16x32_bf16 v[82:85], v[182:185], v[206:209], v[82:85]
	v_mfma_f32_16x16x32_bf16 v[74:77], v[174:177], v[214:217], v[74:77]
	v_mfma_f32_16x16x32_bf16 v[66:69], v[182:185], v[214:217], v[66:69]
	s_barrier
	s_setprio 0
	s_add_i32 s49, s39, s28
	v_lshl_add_u64 v[218:219], s[22:23], 0, v[134:135]
	s_mov_b32 m0, s49
	ds_read_b128 v[186:189], v154 offset:16384
	ds_read_b128 v[190:193], v154 offset:17408
	ds_read_b128 v[194:197], v154 offset:18432
	ds_read_b128 v[198:201], v154 offset:19456
	ds_read_b128 v[202:205], v154 offset:20480
	ds_read_b128 v[206:209], v154 offset:21504
	ds_read_b128 v[210:213], v154 offset:22528
	ds_read_b128 v[214:217], v154 offset:23552
	global_load_lds_dwordx4 v[218:219], off
	s_add_i32 m0, s49, 0x2000
	s_add_u32 s50, s22, 0x80000
	v_lshl_add_u64 v[220:221], s[22:23], 0, v[130:131]
	s_addc_u32 s51, s23, 0
	s_add_i32 s49, s40, s28
	global_load_lds_dwordx4 v[220:221], off
	v_lshl_add_u64 v[222:223], s[50:51], 0, v[134:135]
	s_mov_b32 m0, s49
	v_lshl_add_u64 v[224:225], s[24:25], 0, v[132:133]
	global_load_lds_dwordx4 v[222:223], off
	s_add_i32 m0, s49, 0x2000
	v_lshl_add_u64 v[222:223], s[50:51], 0, v[130:131]
	global_load_lds_dwordx4 v[222:223], off
	s_mov_b32 m0, s19
	v_lshl_add_u64 v[222:223], s[24:25], 0, v[136:137]
	global_load_lds_dwordx4 v[222:223], off
	s_mov_b32 m0, s31
	s_nop 0
	global_load_lds_dwordx4 v[224:225], off
	s_waitcnt vmcnt(8)
	s_waitcnt lgkmcnt(0)
	s_setprio 1
	s_barrier
; #define PG8_STAGE(bufoff, gbase, voff) do { _Pragma("unroll") for (int _i = 0; _i < 2; ++_i) \
;         __builtin_amdgcn_global_load_lds((const unsigned*)((const char*)(gbase) + (voff)[_i]), (PG8_LAS unsigned*)(lds + (bufoff) + ldsw + _i * 8192), 16, 0, 0); } while (0)
; #define PG8_WAIT_V(n) asm volatile("s_waitcnt vmcnt(" #n ")" ::: "memory")
; #define PG8_WAIT_L(n) asm volatile("s_waitcnt lgkmcnt(" #n ")" ::: "memory")
; #define PG8_BAR __builtin_amdgcn_s_barrier()
; #define PG8_SCHED __builtin_amdgcn_sched_barrier(0)
; template <class Epi, class Sched, bool ALIGN_EPI = true, bool SP2 = true>
; __device__ __forceinline__ void gemm_phase(PG8_LAS unsigned char* lds, const int K  , const Sched& S, const Epi& E) {
;     ...
;             PG8_WAIT_V(8); PG8_WAIT_L(0); PG8_BAR; PG8_MMA(1, 0, At, B0); PG8_MMA(1, 1, At, B1); PG8_BAR; PG8_SCHED;
;             PG8_LDB(B0, 1, 0); PG8_LDB(B1, 1, 1); PG8_SCHED; PG8_LDA(At, 1, 0); PG8_STAGE(PG8_SA(0, 1), a2 + hstep, voffA);
;             PG8_WAIT_V(8); PG8_WAIT_L(0); PG8_BAR; PG8_MMA(0, 0, At, B0); PG8_MMA(0, 1, At, B1); PG8_BAR; PG8_SCHED;
	v_mfma_f32_16x16x32_bf16 v[62:65], v[146:149], v[186:189], v[62:65]
	v_mfma_f32_16x16x32_bf16 v[54:57], v[162:165], v[186:189], v[54:57]
	v_mfma_f32_16x16x32_bf16 v[46:49], v[146:149], v[194:197], v[46:49]
	v_mfma_f32_16x16x32_bf16 v[38:41], v[162:165], v[194:197], v[38:41]
	v_mfma_f32_16x16x32_bf16 v[30:33], v[146:149], v[202:205], v[30:33]
	v_mfma_f32_16x16x32_bf16 v[22:25], v[162:165], v[202:205], v[22:25]
	v_mfma_f32_16x16x32_bf16 v[14:17], v[146:149], v[210:213], v[14:17]
	v_mfma_f32_16x16x32_bf16 v[6:9], v[162:165], v[210:213], v[6:9]
	v_mfma_f32_16x16x32_bf16 v[62:65], v[158:161], v[190:193], v[62:65]
	v_mfma_f32_16x16x32_bf16 v[54:57], v[166:169], v[190:193], v[54:57]
	v_mfma_f32_16x16x32_bf16 v[46:49], v[158:161], v[198:201], v[46:49]
	v_mfma_f32_16x16x32_bf16 v[38:41], v[166:169], v[198:201], v[38:41]
	v_mfma_f32_16x16x32_bf16 v[30:33], v[158:161], v[206:209], v[30:33]
	v_mfma_f32_16x16x32_bf16 v[22:25], v[166:169], v[206:209], v[22:25]
	v_mfma_f32_16x16x32_bf16 v[14:17], v[158:161], v[214:217], v[14:17]
	v_mfma_f32_16x16x32_bf16 v[6:9], v[166:169], v[214:217], v[6:9]
	s_setprio 0
	s_setprio 1
	v_mfma_f32_16x16x32_bf16 v[58:61], v[170:173], v[186:189], v[58:61]
	v_mfma_f32_16x16x32_bf16 v[50:53], v[178:181], v[186:189], v[50:53]
	v_mfma_f32_16x16x32_bf16 v[42:45], v[170:173], v[194:197], v[42:45]
	v_mfma_f32_16x16x32_bf16 v[34:37], v[178:181], v[194:197], v[34:37]
	v_mfma_f32_16x16x32_bf16 v[26:29], v[170:173], v[202:205], v[26:29]
	v_mfma_f32_16x16x32_bf16 v[18:21], v[178:181], v[202:205], v[18:21]
	v_mfma_f32_16x16x32_bf16 v[10:13], v[170:173], v[210:213], v[10:13]
	v_mfma_f32_16x16x32_bf16 v[2:5], v[178:181], v[210:213], v[2:5]
	v_mfma_f32_16x16x32_bf16 v[58:61], v[174:177], v[190:193], v[58:61]
	v_mfma_f32_16x16x32_bf16 v[50:53], v[182:185], v[190:193], v[50:53]
	v_mfma_f32_16x16x32_bf16 v[42:45], v[174:177], v[198:201], v[42:45]
	v_mfma_f32_16x16x32_bf16 v[34:37], v[182:185], v[198:201], v[34:37]
	v_mfma_f32_16x16x32_bf16 v[26:29], v[174:177], v[206:209], v[26:29]
	v_mfma_f32_16x16x32_bf16 v[18:21], v[182:185], v[206:209], v[18:21]
	v_mfma_f32_16x16x32_bf16 v[10:13], v[174:177], v[214:217], v[10:13]
	v_mfma_f32_16x16x32_bf16 v[2:5], v[182:185], v[214:217], v[2:5]
	s_barrier
	s_setprio 0
	s_add_i32 s49, 0, 0x18000
	v_add_u32_e32 v157, s49, v150
	s_add_i32 s50, 0, 0x1c000
	ds_read_b128 v[146:149], v157
	ds_read_b128 v[158:161], v157 offset:1024
	ds_read_b128 v[162:165], v157 offset:2048
	ds_read_b128 v[166:169], v157 offset:3072
	v_add_u32_e32 v157, s50, v150
	ds_read_b128 v[170:173], v157
	ds_read_b128 v[174:177], v157 offset:1024
	ds_read_b128 v[178:181], v157 offset:2048
	ds_read_b128 v[182:185], v157 offset:3072
	s_add_u32 s24, s24, 0x80000
	s_addc_u32 s25, s25, 0
	s_mov_b32 m0, s33
	v_lshl_add_u64 v[226:227], s[24:25], 0, v[136:137]
	ds_read_b128 v[186:189], v154 offset:32768
	ds_read_b128 v[190:193], v154 offset:33792
	ds_read_b128 v[194:197], v154 offset:34816
	ds_read_b128 v[198:201], v154 offset:35840
	ds_read_b128 v[202:205], v154 offset:36864
	ds_read_b128 v[206:209], v154 offset:37888
	ds_read_b128 v[210:213], v154 offset:38912
	ds_read_b128 v[214:217], v154 offset:39936
	global_load_lds_dwordx4 v[226:227], off
	s_mov_b32 m0, s34
	v_lshl_add_u64 v[226:227], s[24:25], 0, v[132:133]
	global_load_lds_dwordx4 v[226:227], off
	s_waitcnt vmcnt(8)
	s_waitcnt lgkmcnt(0)
	s_setprio 1
	s_barrier
	v_mfma_f32_16x16x32_bf16 v[126:129], v[146:149], v[186:189], v[126:129]
	v_mfma_f32_16x16x32_bf16 v[118:121], v[162:165], v[186:189], v[118:121]
	v_mfma_f32_16x16x32_bf16 v[110:113], v[146:149], v[194:197], v[110:113]
	v_mfma_f32_16x16x32_bf16 v[102:105], v[162:165], v[194:197], v[102:105]
	v_mfma_f32_16x16x32_bf16 v[94:97], v[146:149], v[202:205], v[94:97]
	v_mfma_f32_16x16x32_bf16 v[86:89], v[162:165], v[202:205], v[86:89]
	v_mfma_f32_16x16x32_bf16 v[78:81], v[146:149], v[210:213], v[78:81]
	v_mfma_f32_16x16x32_bf16 v[70:73], v[162:165], v[210:213], v[70:73]
	v_mfma_f32_16x16x32_bf16 v[126:129], v[158:161], v[190:193], v[126:129]
	v_mfma_f32_16x16x32_bf16 v[118:121], v[166:169], v[190:193], v[118:121]
	v_mfma_f32_16x16x32_bf16 v[110:113], v[158:161], v[198:201], v[110:113]
	v_mfma_f32_16x16x32_bf16 v[102:105], v[166:169], v[198:201], v[102:105]
	v_mfma_f32_16x16x32_bf16 v[94:97], v[158:161], v[206:209], v[94:97]
	v_mfma_f32_16x16x32_bf16 v[86:89], v[166:169], v[206:209], v[86:89]
	v_mfma_f32_16x16x32_bf16 v[78:81], v[158:161], v[214:217], v[78:81]
	v_mfma_f32_16x16x32_bf16 v[70:73], v[166:169], v[214:217], v[70:73]
	s_setprio 0
	s_setprio 1
	v_mfma_f32_16x16x32_bf16 v[122:125], v[170:173], v[186:189], v[122:125]
	v_mfma_f32_16x16x32_bf16 v[114:117], v[178:181], v[186:189], v[114:117]
	v_mfma_f32_16x16x32_bf16 v[106:109], v[170:173], v[194:197], v[106:109]
	v_mfma_f32_16x16x32_bf16 v[98:101], v[178:181], v[194:197], v[98:101]
	v_mfma_f32_16x16x32_bf16 v[90:93], v[170:173], v[202:205], v[90:93]
	v_mfma_f32_16x16x32_bf16 v[82:85], v[178:181], v[202:205], v[82:85]
	v_mfma_f32_16x16x32_bf16 v[74:77], v[170:173], v[210:213], v[74:77]
	v_mfma_f32_16x16x32_bf16 v[66:69], v[178:181], v[210:213], v[66:69]
	v_mfma_f32_16x16x32_bf16 v[122:125], v[174:177], v[190:193], v[122:125]
	v_mfma_f32_16x16x32_bf16 v[114:117], v[182:185], v[190:193], v[114:117]
	v_mfma_f32_16x16x32_bf16 v[106:109], v[174:177], v[198:201], v[106:109]
	v_mfma_f32_16x16x32_bf16 v[98:101], v[182:185], v[198:201], v[98:101]
	v_mfma_f32_16x16x32_bf16 v[90:93], v[174:177], v[206:209], v[90:93]
	v_mfma_f32_16x16x32_bf16 v[82:85], v[182:185], v[206:209], v[82:85]
	v_mfma_f32_16x16x32_bf16 v[74:77], v[174:177], v[214:217], v[74:77]
	v_mfma_f32_16x16x32_bf16 v[66:69], v[182:185], v[214:217], v[66:69]
	s_barrier
; #define PG8_STAGE(bufoff, gbase, voff) do { _Pragma("unroll") for (int _i = 0; _i < 2; ++_i) \
;         __builtin_amdgcn_global_load_lds((const unsigned*)((const char*)(gbase) + (voff)[_i]), (PG8_LAS unsigned*)(lds + (bufoff) + ldsw + _i * 8192), 16, 0, 0); } while (0)
; #define PG8_WAIT_V(n) asm volatile("s_waitcnt vmcnt(" #n ")" ::: "memory")
; #define PG8_WAIT_L(n) asm volatile("s_waitcnt lgkmcnt(" #n ")" ::: "memory")
; #define PG8_BAR __builtin_amdgcn_s_barrier()
; #define PG8_SCHED __builtin_amdgcn_sched_barrier(0)
; template <class Epi, class Sched, bool ALIGN_EPI = true, bool SP2 = true>
; __device__ __forceinline__ void gemm_phase(PG8_LAS unsigned char* lds, const int K  , const Sched& S, const Epi& E) {
;     ...
;             PG8_LDA(At, 1, 1); PG8_STAGE(PG8_SB(1, 0), b3, voffB); PG8_STAGE(PG8_SB(1, 1), b3 + hstep, voffB); PG8_STAGE(PG8_SA(1, 0), a3, voffA);
;             PG8_WAIT_V(8); PG8_WAIT_L(0); PG8_BAR; PG8_MMA(1, 0, At, B0); PG8_MMA(1, 1, At, B1); PG8_BAR; PG8_SCHED;
;     ...
;         if constexpr (ALIGN_EPI) { if (wr == 0) PG8_BAR; }
	s_setprio 0
	s_add_i32 s24, s49, s28
	v_lshl_add_u64 v[218:219], v[218:219], 0, s[6:7]
	s_mov_b32 m0, s24
	ds_read_b128 v[186:189], v154 offset:49152
	ds_read_b128 v[190:193], v154 offset:50176
	ds_read_b128 v[194:197], v154 offset:51200
	ds_read_b128 v[198:201], v154 offset:52224
	ds_read_b128 v[202:205], v154 offset:53248
	ds_read_b128 v[206:209], v154 offset:54272
	ds_read_b128 v[210:213], v154 offset:55296
	ds_read_b128 v[214:217], v154 offset:56320
	global_load_lds_dwordx4 v[218:219], off
	s_add_i32 m0, s24, 0x2000
	s_add_u32 s22, s22, 0x80080
	v_lshl_add_u64 v[218:219], v[220:221], 0, s[6:7]
	s_addc_u32 s23, s23, 0
	s_add_i32 s24, s50, s28
	global_load_lds_dwordx4 v[218:219], off
	s_mov_b32 m0, s24
	v_lshl_add_u64 v[218:219], s[22:23], 0, v[134:135]
	global_load_lds_dwordx4 v[218:219], off
	s_add_i32 m0, s24, 0x2000
	v_lshl_add_u64 v[218:219], s[22:23], 0, v[130:131]
	global_load_lds_dwordx4 v[218:219], off
	s_mov_b32 m0, s36
	v_lshl_add_u64 v[218:219], v[222:223], 0, s[6:7]
	global_load_lds_dwordx4 v[218:219], off
	s_mov_b32 m0, s37
	v_lshl_add_u64 v[218:219], v[224:225], 0, s[6:7]
	global_load_lds_dwordx4 v[218:219], off
	s_waitcnt vmcnt(8)
	s_waitcnt lgkmcnt(0)
	s_setprio 1
	s_barrier
	v_mfma_f32_16x16x32_bf16 v[62:65], v[146:149], v[186:189], v[62:65]
	v_mfma_f32_16x16x32_bf16 v[54:57], v[162:165], v[186:189], v[54:57]
	v_mfma_f32_16x16x32_bf16 v[46:49], v[146:149], v[194:197], v[46:49]
	v_mfma_f32_16x16x32_bf16 v[38:41], v[162:165], v[194:197], v[38:41]
	v_mfma_f32_16x16x32_bf16 v[30:33], v[146:149], v[202:205], v[30:33]
	v_mfma_f32_16x16x32_bf16 v[22:25], v[162:165], v[202:205], v[22:25]
	v_mfma_f32_16x16x32_bf16 v[14:17], v[146:149], v[210:213], v[14:17]
	v_mfma_f32_16x16x32_bf16 v[6:9], v[162:165], v[210:213], v[6:9]
	v_mfma_f32_16x16x32_bf16 v[62:65], v[158:161], v[190:193], v[62:65]
	v_mfma_f32_16x16x32_bf16 v[54:57], v[166:169], v[190:193], v[54:57]
	v_mfma_f32_16x16x32_bf16 v[46:49], v[158:161], v[198:201], v[46:49]
	v_mfma_f32_16x16x32_bf16 v[38:41], v[166:169], v[198:201], v[38:41]
	v_mfma_f32_16x16x32_bf16 v[30:33], v[158:161], v[206:209], v[30:33]
	v_mfma_f32_16x16x32_bf16 v[22:25], v[166:169], v[206:209], v[22:25]
	v_mfma_f32_16x16x32_bf16 v[14:17], v[158:161], v[214:217], v[14:17]
	v_mfma_f32_16x16x32_bf16 v[6:9], v[166:169], v[214:217], v[6:9]
	s_setprio 0
	s_setprio 1
	v_mfma_f32_16x16x32_bf16 v[58:61], v[170:173], v[186:189], v[58:61]
	v_mfma_f32_16x16x32_bf16 v[50:53], v[178:181], v[186:189], v[50:53]
	v_mfma_f32_16x16x32_bf16 v[42:45], v[170:173], v[194:197], v[42:45]
	v_mfma_f32_16x16x32_bf16 v[34:37], v[178:181], v[194:197], v[34:37]
	v_mfma_f32_16x16x32_bf16 v[26:29], v[170:173], v[202:205], v[26:29]
	v_mfma_f32_16x16x32_bf16 v[18:21], v[178:181], v[202:205], v[18:21]
	v_mfma_f32_16x16x32_bf16 v[10:13], v[170:173], v[210:213], v[10:13]
	v_mfma_f32_16x16x32_bf16 v[2:5], v[178:181], v[210:213], v[2:5]
	v_mfma_f32_16x16x32_bf16 v[58:61], v[174:177], v[190:193], v[58:61]
	v_mfma_f32_16x16x32_bf16 v[50:53], v[182:185], v[190:193], v[50:53]
	v_mfma_f32_16x16x32_bf16 v[42:45], v[174:177], v[198:201], v[42:45]
	v_mfma_f32_16x16x32_bf16 v[34:37], v[182:185], v[198:201], v[34:37]
	v_mfma_f32_16x16x32_bf16 v[26:29], v[174:177], v[206:209], v[26:29]
	v_mfma_f32_16x16x32_bf16 v[18:21], v[182:185], v[206:209], v[18:21]
	v_mfma_f32_16x16x32_bf16 v[10:13], v[174:177], v[214:217], v[10:13]
	v_mfma_f32_16x16x32_bf16 v[2:5], v[182:185], v[214:217], v[2:5]
	s_barrier
	s_setprio 0
	s_add_i32 s48, s48, 2
	s_add_u32 s20, s20, 0x100
	s_addc_u32 s21, s21, 0
	s_add_u32 s46, s46, 0x100
	s_addc_u32 s47, s47, 0
	s_cmp_gt_u32 s48, 29
	s_cbranch_scc0 .LBB0_2433
	s_and_b64 vcc, exec, s[8:9]
	s_cbranch_vccz .LBB0_2436
	s_barrier

; #define PG8_STAGE(bufoff, gbase, voff) do { _Pragma("unroll") for (int _i = 0; _i < 2; ++_i) \
;         __builtin_amdgcn_global_load_lds((const unsigned*)((const char*)(gbase) + (voff)[_i]), (PG8_LAS unsigned*)(lds + (bufoff) + ldsw + _i * 8192), 16, 0, 0); } while (0)
; #define PG8_WAIT_V(n) asm volatile("s_waitcnt vmcnt(" #n ")" ::: "memory")
; #define PG8_WAIT_L(n) asm volatile("s_waitcnt lgkmcnt(" #n ")" ::: "memory")
; #define PG8_BAR __builtin_amdgcn_s_barrier()
; #define PG8_SCHED __builtin_amdgcn_sched_barrier(0)
;     __device__ __forceinline__ int nt(const pg8::Unit& u) const { return u.kind == 0 ? ntiles : q_nt(u.kind - 1); }
; template <class Epi, class Sched, bool ALIGN_EPI = true, bool SP2 = true>
; __device__ __forceinline__ void gemm_phase(PG8_LAS unsigned char* lds, const int K  , const Sched& S, const Epi& E) {
;     ...
;         for (int t = 0; t < nt; t += 2) {
;             const bool last = (t == nt - 2);
;             const char* a1 = cA + (size_t)(t + 1) * kstep;
;             const char* a2 = last ? nA : cA + (size_t)(t + 2) * kstep; const char* b2 = last ? nB : cB + (size_t)(t + 2) * kstep;
;             const char* a3 = a2 + kstep; const char* b3 = b2 + kstep;
;             if constexpr (SP2) {
;             PG8_LDB(B0, 0, 0); PG8_LDB(B1, 0, 1); PG8_SCHED; PG8_LDA(At, 0, 0); PG8_STAGE(PG8_SA(1, 1), a1 + hstep, voffA);
;             PG8_WAIT_V(8); PG8_WAIT_L(0); PG8_BAR; PG8_MMA(0, 0, At, B0); PG8_MMA(0, 1, At, B1); PG8_BAR; PG8_SCHED;
;             PG8_LDA(At, 0, 1); PG8_STAGE(PG8_SB(0, 0), b2, voffB); PG8_STAGE(PG8_SB(0, 1), b2 + hstep, voffB); PG8_STAGE(PG8_SA(0, 0), a2, voffA);
;             PG8_WAIT_V(8); PG8_WAIT_L(0); PG8_BAR; PG8_MMA(1, 0, At, B0); PG8_MMA(1, 1, At, B1); PG8_BAR; PG8_SCHED;
.LBB0_2516:
	ds_read_b128 v[16:19], v206
	ds_read_b128 v[20:23], v206 offset:1024
	ds_read_b128 v[24:27], v206 offset:2048
	ds_read_b128 v[28:31], v206 offset:3072
	ds_read_b128 v[0:3], v207
	ds_read_b128 v[4:7], v207 offset:1024
	ds_read_b128 v[8:11], v207 offset:2048
	ds_read_b128 v[12:15], v207 offset:3072
	s_add_u32 s18, s16, 0xfff50080
	s_addc_u32 s19, s17, -1
	s_cmp_eq_u32 s57, 40
	s_cselect_b32 s21, s7, s19
	s_cselect_b32 s20, s6, s18
	s_cselect_b32 s19, s15, s56
	s_cselect_b32 s18, s14, s55
	v_lshl_add_u64 v[200:201], s[16:17], 0, v[176:177]
	s_add_i32 m0, s25, 0xc000
	ds_read_b128 v[160:163], v208
	ds_read_b128 v[164:167], v208 offset:1024
	ds_read_b128 v[184:187], v208 offset:2048
	ds_read_b128 v[188:191], v208 offset:3072
	ds_read_b128 v[192:195], v208 offset:4096
	ds_read_b128 v[196:199], v208 offset:5120
	ds_read_b128 v[210:213], v208 offset:6144
	ds_read_b128 v[214:217], v208 offset:7168
	global_load_lds_dwordx4 v[200:201], off
	s_add_i32 m0, s25, 0xe000
	v_lshl_add_u64 v[200:201], s[16:17], 0, v[178:179]
	global_load_lds_dwordx4 v[200:201], off
	s_waitcnt vmcnt(8)
	s_waitcnt lgkmcnt(0)
	s_setprio 1
	s_barrier
	v_mfma_scale_f32_16x16x128_f8f6f4 v[156:159], v[16:23], v[160:167], v[156:159], v202, v202 op_sel_hi:[0,0,0]
	v_mfma_scale_f32_16x16x128_f8f6f4 v[152:155], v[24:31], v[160:167], v[152:155], v202, v202 op_sel_hi:[0,0,0]
	v_mfma_scale_f32_16x16x128_f8f6f4 v[140:143], v[16:23], v[184:191], v[140:143], v202, v202 op_sel_hi:[0,0,0]
	v_mfma_scale_f32_16x16x128_f8f6f4 v[136:139], v[24:31], v[184:191], v[136:139], v202, v202 op_sel_hi:[0,0,0]
	v_mfma_scale_f32_16x16x128_f8f6f4 v[124:127], v[16:23], v[192:199], v[124:127], v202, v202 op_sel_hi:[0,0,0]
	v_mfma_scale_f32_16x16x128_f8f6f4 v[120:123], v[24:31], v[192:199], v[120:123], v202, v202 op_sel_hi:[0,0,0]
	v_mfma_scale_f32_16x16x128_f8f6f4 v[108:111], v[16:23], v[210:217], v[108:111], v202, v202 op_sel_hi:[0,0,0]
	v_mfma_scale_f32_16x16x128_f8f6f4 v[104:107], v[24:31], v[210:217], v[104:107], v202, v202 op_sel_hi:[0,0,0]
	s_setprio 0
	s_setprio 1
	v_mfma_scale_f32_16x16x128_f8f6f4 v[148:151], v[0:7], v[160:167], v[148:151], v202, v202 op_sel_hi:[0,0,0]
	v_mfma_scale_f32_16x16x128_f8f6f4 v[144:147], v[8:15], v[160:167], v[144:147], v202, v202 op_sel_hi:[0,0,0]
	v_mfma_scale_f32_16x16x128_f8f6f4 v[132:135], v[0:7], v[184:191], v[132:135], v202, v202 op_sel_hi:[0,0,0]
	v_mfma_scale_f32_16x16x128_f8f6f4 v[128:131], v[8:15], v[184:191], v[128:131], v202, v202 op_sel_hi:[0,0,0]
	v_mfma_scale_f32_16x16x128_f8f6f4 v[116:119], v[0:7], v[192:199], v[116:119], v202, v202 op_sel_hi:[0,0,0]
	v_mfma_scale_f32_16x16x128_f8f6f4 v[112:115], v[8:15], v[192:199], v[112:115], v202, v202 op_sel_hi:[0,0,0]
	v_mfma_scale_f32_16x16x128_f8f6f4 v[100:103], v[0:7], v[210:217], v[100:103], v202, v202 op_sel_hi:[0,0,0]
	v_mfma_scale_f32_16x16x128_f8f6f4 v[96:99], v[8:15], v[210:217], v[96:99], v202, v202 op_sel_hi:[0,0,0]
	s_barrier
	s_setprio 0
	s_add_i32 s58, s38, s24
	v_lshl_add_u64 v[160:161], s[18:19], 0, v[170:171]
	s_mov_b32 m0, s58
	ds_read_b128 v[184:187], v208 offset:16384
	ds_read_b128 v[188:191], v208 offset:17408
	ds_read_b128 v[192:195], v208 offset:18432
	ds_read_b128 v[196:199], v208 offset:19456
	ds_read_b128 v[210:213], v208 offset:20480
	ds_read_b128 v[214:217], v208 offset:21504
	ds_read_b128 v[218:221], v208 offset:22528
	ds_read_b128 v[222:225], v208 offset:23552
	global_load_lds_dwordx4 v[160:161], off
	s_add_i32 m0, s58, 0x2000
	s_add_u32 s58, s18, 0xb0000
	v_lshl_add_u64 v[162:163], s[18:19], 0, v[174:175]
	s_addc_u32 s59, s19, 0
	s_add_i32 s60, s39, s24
	global_load_lds_dwordx4 v[162:163], off
	v_lshl_add_u64 v[164:165], s[58:59], 0, v[170:171]
	s_mov_b32 m0, s60
	v_lshl_add_u64 v[166:167], s[20:21], 0, v[172:173]
	global_load_lds_dwordx4 v[164:165], off
	s_add_i32 m0, s60, 0x2000
	v_lshl_add_u64 v[164:165], s[58:59], 0, v[174:175]
	global_load_lds_dwordx4 v[164:165], off
	s_mov_b32 m0, s25
	v_lshl_add_u64 v[164:165], s[20:21], 0, v[168:169]
	global_load_lds_dwordx4 v[164:165], off
	s_mov_b32 m0, s26
	s_nop 0
	global_load_lds_dwordx4 v[166:167], off
	s_waitcnt vmcnt(8)
	s_waitcnt lgkmcnt(0)
	s_setprio 1
	s_barrier
	v_mfma_scale_f32_16x16x128_f8f6f4 v[92:95], v[16:23], v[184:191], v[92:95], v202, v202 op_sel_hi:[0,0,0]
	v_mfma_scale_f32_16x16x128_f8f6f4 v[88:91], v[24:31], v[184:191], v[88:91], v202, v202 op_sel_hi:[0,0,0]
	v_mfma_scale_f32_16x16x128_f8f6f4 v[76:79], v[16:23], v[192:199], v[76:79], v202, v202 op_sel_hi:[0,0,0]
	v_mfma_scale_f32_16x16x128_f8f6f4 v[72:75], v[24:31], v[192:199], v[72:75], v202, v202 op_sel_hi:[0,0,0]
	v_mfma_scale_f32_16x16x128_f8f6f4 v[60:63], v[16:23], v[210:217], v[60:63], v202, v202 op_sel_hi:[0,0,0]
	v_mfma_scale_f32_16x16x128_f8f6f4 v[56:59], v[24:31], v[210:217], v[56:59], v202, v202 op_sel_hi:[0,0,0]
	v_mfma_scale_f32_16x16x128_f8f6f4 v[44:47], v[16:23], v[218:225], v[44:47], v202, v202 op_sel_hi:[0,0,0]
	v_mfma_scale_f32_16x16x128_f8f6f4 v[40:43], v[24:31], v[218:225], v[40:43], v202, v202 op_sel_hi:[0,0,0]
	s_setprio 0
	s_setprio 1
	v_mfma_scale_f32_16x16x128_f8f6f4 v[84:87], v[0:7], v[184:191], v[84:87], v202, v202 op_sel_hi:[0,0,0]
	v_mfma_scale_f32_16x16x128_f8f6f4 v[80:83], v[8:15], v[184:191], v[80:83], v202, v202 op_sel_hi:[0,0,0]
	v_mfma_scale_f32_16x16x128_f8f6f4 v[68:71], v[0:7], v[192:199], v[68:71], v202, v202 op_sel_hi:[0,0,0]
	v_mfma_scale_f32_16x16x128_f8f6f4 v[64:67], v[8:15], v[192:199], v[64:67], v202, v202 op_sel_hi:[0,0,0]
	v_mfma_scale_f32_16x16x128_f8f6f4 v[52:55], v[0:7], v[210:217], v[52:55], v202, v202 op_sel_hi:[0,0,0]
	v_mfma_scale_f32_16x16x128_f8f6f4 v[48:51], v[8:15], v[210:217], v[48:51], v202, v202 op_sel_hi:[0,0,0]
	v_mfma_scale_f32_16x16x128_f8f6f4 v[36:39], v[0:7], v[218:225], v[36:39], v202, v202 op_sel_hi:[0,0,0]
	v_mfma_scale_f32_16x16x128_f8f6f4 v[32:35], v[8:15], v[218:225], v[32:35], v202, v202 op_sel_hi:[0,0,0]
	s_barrier
; #define PG8_STAGE(bufoff, gbase, voff) do { _Pragma("unroll") for (int _i = 0; _i < 2; ++_i) \
;         __builtin_amdgcn_global_load_lds((const unsigned*)((const char*)(gbase) + (voff)[_i]), (PG8_LAS unsigned*)(lds + (bufoff) + ldsw + _i * 8192), 16, 0, 0); } while (0)
; #define PG8_WAIT_V(n) asm volatile("s_waitcnt vmcnt(" #n ")" ::: "memory")
; #define PG8_WAIT_L(n) asm volatile("s_waitcnt lgkmcnt(" #n ")" ::: "memory")
; #define PG8_BAR __builtin_amdgcn_s_barrier()
; #define PG8_SCHED __builtin_amdgcn_sched_barrier(0)
; template <class Epi, class Sched, bool ALIGN_EPI = true, bool SP2 = true>
; __device__ __forceinline__ void gemm_phase(PG8_LAS unsigned char* lds, const int K  , const Sched& S, const Epi& E) {
;     ...
;             PG8_LDB(B0, 1, 0); PG8_LDB(B1, 1, 1); PG8_SCHED; PG8_LDA(At, 1, 0); PG8_STAGE(PG8_SA(0, 1), a2 + hstep, voffA);
;             PG8_WAIT_V(8); PG8_WAIT_L(0); PG8_BAR; PG8_MMA(0, 0, At, B0); PG8_MMA(0, 1, At, B1); PG8_BAR; PG8_SCHED;
;             PG8_LDA(At, 1, 1); PG8_STAGE(PG8_SB(1, 0), b3, voffB); PG8_STAGE(PG8_SB(1, 1), b3 + hstep, voffB); PG8_STAGE(PG8_SA(1, 0), a3, voffA);
;             PG8_WAIT_V(8); PG8_WAIT_L(0); PG8_BAR; PG8_MMA(1, 0, At, B0); PG8_MMA(1, 1, At, B1); PG8_BAR; PG8_SCHED;
;     ...
;         if constexpr (Epi::FP8) asm volatile("s_nop 15\n\ts_nop 15\n\ts_nop 15\n\ts_nop 15\n\ts_nop 15" ::: "memory");
;         if constexpr (ALIGN_EPI) { if (wr == 0) PG8_BAR; }
	s_setprio 0
	s_add_i32 s58, 0, 0x18000
	s_add_i32 s59, 0, 0x1c000
	v_add_u32_e32 v12, s58, v204
	v_add_u32_e32 v28, s59, v204
	ds_read_b128 v[0:3], v12
	ds_read_b128 v[4:7], v12 offset:1024
	ds_read_b128 v[8:11], v12 offset:2048
	ds_read_b128 v[12:15], v12 offset:3072
	ds_read_b128 v[16:19], v28
	ds_read_b128 v[20:23], v28 offset:1024
	ds_read_b128 v[24:27], v28 offset:2048
	ds_read_b128 v[28:31], v28 offset:3072
	s_add_u32 s20, s20, 0xb0000
	s_addc_u32 s21, s21, 0
	s_mov_b32 m0, s27
	v_lshl_add_u64 v[200:201], s[20:21], 0, v[168:169]
	ds_read_b128 v[184:187], v208 offset:32768
	ds_read_b128 v[188:191], v208 offset:33792
	ds_read_b128 v[192:195], v208 offset:34816
	ds_read_b128 v[196:199], v208 offset:35840
	ds_read_b128 v[210:213], v208 offset:36864
	ds_read_b128 v[214:217], v208 offset:37888
	ds_read_b128 v[218:221], v208 offset:38912
	ds_read_b128 v[222:225], v208 offset:39936
	global_load_lds_dwordx4 v[200:201], off
	s_mov_b32 m0, s28
	v_lshl_add_u64 v[200:201], s[20:21], 0, v[172:173]
	global_load_lds_dwordx4 v[200:201], off
	s_waitcnt vmcnt(8)
	s_waitcnt lgkmcnt(0)
	s_setprio 1
	s_barrier
	v_mfma_scale_f32_16x16x128_f8f6f4 v[156:159], v[0:7], v[184:191], v[156:159], v202, v202 op_sel_hi:[0,0,0]
	v_mfma_scale_f32_16x16x128_f8f6f4 v[152:155], v[8:15], v[184:191], v[152:155], v202, v202 op_sel_hi:[0,0,0]
	v_mfma_scale_f32_16x16x128_f8f6f4 v[140:143], v[0:7], v[192:199], v[140:143], v202, v202 op_sel_hi:[0,0,0]
	v_mfma_scale_f32_16x16x128_f8f6f4 v[136:139], v[8:15], v[192:199], v[136:139], v202, v202 op_sel_hi:[0,0,0]
	v_mfma_scale_f32_16x16x128_f8f6f4 v[124:127], v[0:7], v[210:217], v[124:127], v202, v202 op_sel_hi:[0,0,0]
	v_mfma_scale_f32_16x16x128_f8f6f4 v[120:123], v[8:15], v[210:217], v[120:123], v202, v202 op_sel_hi:[0,0,0]
	v_mfma_scale_f32_16x16x128_f8f6f4 v[108:111], v[0:7], v[218:225], v[108:111], v202, v202 op_sel_hi:[0,0,0]
	v_mfma_scale_f32_16x16x128_f8f6f4 v[104:107], v[8:15], v[218:225], v[104:107], v202, v202 op_sel_hi:[0,0,0]
	s_setprio 0
	s_setprio 1
	v_mfma_scale_f32_16x16x128_f8f6f4 v[148:151], v[16:23], v[184:191], v[148:151], v202, v202 op_sel_hi:[0,0,0]
	v_mfma_scale_f32_16x16x128_f8f6f4 v[144:147], v[24:31], v[184:191], v[144:147], v202, v202 op_sel_hi:[0,0,0]
	v_mfma_scale_f32_16x16x128_f8f6f4 v[132:135], v[16:23], v[192:199], v[132:135], v202, v202 op_sel_hi:[0,0,0]
	v_mfma_scale_f32_16x16x128_f8f6f4 v[128:131], v[24:31], v[192:199], v[128:131], v202, v202 op_sel_hi:[0,0,0]
	v_mfma_scale_f32_16x16x128_f8f6f4 v[116:119], v[16:23], v[210:217], v[116:119], v202, v202 op_sel_hi:[0,0,0]
	v_mfma_scale_f32_16x16x128_f8f6f4 v[112:115], v[24:31], v[210:217], v[112:115], v202, v202 op_sel_hi:[0,0,0]
	v_mfma_scale_f32_16x16x128_f8f6f4 v[100:103], v[16:23], v[218:225], v[100:103], v202, v202 op_sel_hi:[0,0,0]
	v_mfma_scale_f32_16x16x128_f8f6f4 v[96:99], v[24:31], v[218:225], v[96:99], v202, v202 op_sel_hi:[0,0,0]
	s_barrier
	s_setprio 0
	s_add_i32 s20, s58, s24
	v_lshl_add_u64 v[160:161], v[160:161], 0, s[8:9]
	s_mov_b32 m0, s20
	ds_read_b128 v[184:187], v208 offset:49152
	ds_read_b128 v[188:191], v208 offset:50176
	ds_read_b128 v[192:195], v208 offset:51200
	ds_read_b128 v[196:199], v208 offset:52224
	ds_read_b128 v[210:213], v208 offset:53248
	ds_read_b128 v[214:217], v208 offset:54272
	ds_read_b128 v[218:221], v208 offset:55296
	ds_read_b128 v[222:225], v208 offset:56320
	global_load_lds_dwordx4 v[160:161], off
	s_add_i32 m0, s20, 0x2000
	s_add_u32 s18, s18, 0xb0080
	v_lshl_add_u64 v[160:161], v[162:163], 0, s[8:9]
	s_addc_u32 s19, s19, 0
	s_add_i32 s20, s59, s24
	global_load_lds_dwordx4 v[160:161], off
	s_mov_b32 m0, s20
	v_lshl_add_u64 v[160:161], s[18:19], 0, v[170:171]
	global_load_lds_dwordx4 v[160:161], off
	s_add_i32 m0, s20, 0x2000
	v_lshl_add_u64 v[160:161], s[18:19], 0, v[174:175]
	global_load_lds_dwordx4 v[160:161], off
	s_mov_b32 m0, s35
	v_lshl_add_u64 v[160:161], v[164:165], 0, s[8:9]
	global_load_lds_dwordx4 v[160:161], off
	s_mov_b32 m0, s36
	v_lshl_add_u64 v[160:161], v[166:167], 0, s[8:9]
	global_load_lds_dwordx4 v[160:161], off
	s_waitcnt vmcnt(8)
	s_waitcnt lgkmcnt(0)
	s_setprio 1
	s_barrier
	v_mfma_scale_f32_16x16x128_f8f6f4 v[92:95], v[0:7], v[184:191], v[92:95], v202, v202 op_sel_hi:[0,0,0]
	v_mfma_scale_f32_16x16x128_f8f6f4 v[88:91], v[8:15], v[184:191], v[88:91], v202, v202 op_sel_hi:[0,0,0]
	v_mfma_scale_f32_16x16x128_f8f6f4 v[76:79], v[0:7], v[192:199], v[76:79], v202, v202 op_sel_hi:[0,0,0]
	v_mfma_scale_f32_16x16x128_f8f6f4 v[72:75], v[8:15], v[192:199], v[72:75], v202, v202 op_sel_hi:[0,0,0]
	v_mfma_scale_f32_16x16x128_f8f6f4 v[60:63], v[0:7], v[210:217], v[60:63], v202, v202 op_sel_hi:[0,0,0]
	v_mfma_scale_f32_16x16x128_f8f6f4 v[56:59], v[8:15], v[210:217], v[56:59], v202, v202 op_sel_hi:[0,0,0]
	v_mfma_scale_f32_16x16x128_f8f6f4 v[44:47], v[0:7], v[218:225], v[44:47], v202, v202 op_sel_hi:[0,0,0]
	v_mfma_scale_f32_16x16x128_f8f6f4 v[40:43], v[8:15], v[218:225], v[40:43], v202, v202 op_sel_hi:[0,0,0]
	s_setprio 0
	s_setprio 1
	v_mfma_scale_f32_16x16x128_f8f6f4 v[84:87], v[16:23], v[184:191], v[84:87], v202, v202 op_sel_hi:[0,0,0]
	v_mfma_scale_f32_16x16x128_f8f6f4 v[80:83], v[24:31], v[184:191], v[80:83], v202, v202 op_sel_hi:[0,0,0]
	v_mfma_scale_f32_16x16x128_f8f6f4 v[68:71], v[16:23], v[192:199], v[68:71], v202, v202 op_sel_hi:[0,0,0]
	v_mfma_scale_f32_16x16x128_f8f6f4 v[64:67], v[24:31], v[192:199], v[64:67], v202, v202 op_sel_hi:[0,0,0]
	v_mfma_scale_f32_16x16x128_f8f6f4 v[52:55], v[16:23], v[210:217], v[52:55], v202, v202 op_sel_hi:[0,0,0]
	v_mfma_scale_f32_16x16x128_f8f6f4 v[48:51], v[24:31], v[210:217], v[48:51], v202, v202 op_sel_hi:[0,0,0]
	v_mfma_scale_f32_16x16x128_f8f6f4 v[36:39], v[16:23], v[218:225], v[36:39], v202, v202 op_sel_hi:[0,0,0]
	v_mfma_scale_f32_16x16x128_f8f6f4 v[32:35], v[24:31], v[218:225], v[32:35], v202, v202 op_sel_hi:[0,0,0]
	s_barrier
	s_setprio 0
	s_add_i32 s57, s57, 2
	s_add_u32 s16, s16, 0x100
	s_addc_u32 s17, s17, 0
	s_add_u32 s55, s55, 0x100
	s_addc_u32 s56, s56, 0
	s_cmp_gt_u32 s57, 41
	s_cbranch_scc0 .LBB0_2516
	s_nop 15
	s_nop 15
	s_nop 15
	s_nop 15
	s_nop 15
	s_and_b64 vcc, exec, s[10:11]
	s_cbranch_vccz .LBB0_2519
	s_barrier
